# MFMA issue order within each 16-MFMA block: bstat (one operand held for 4 consecutive MFMAs)
# baseline (speedup 1.0000x reference)
.LBB0_197:
	s_ashr_i32 s47, s46, 31
	ds_read_b128 v[18:21], v190
	ds_read_b128 v[22:25], v190 offset:1024
	ds_read_b128 v[26:29], v190 offset:2048
	ds_read_b128 v[30:33], v190 offset:3072
	ds_read_b128 v[2:5], v190 offset:16384
	ds_read_b128 v[6:9], v190 offset:17408
	ds_read_b128 v[10:13], v190 offset:18432
	ds_read_b128 v[14:17], v190 offset:19456
	s_lshl_b64 s[8:9], s[46:47], 20
	s_add_u32 s48, s22, s8
	s_addc_u32 s49, s23, s9
	s_and_b64 s[8:9], s[2:3], exec
	s_cselect_b32 s47, s49, s73
	s_cselect_b32 s70, s48, s72
	s_ashr_i32 s45, s44, 31
	s_lshl_b64 s[8:9], s[44:45], 20
	s_add_u32 s50, s27, s8
	s_addc_u32 s51, s68, s9
	s_and_b64 s[8:9], s[2:3], exec
	s_cselect_b32 s45, s51, s55
	s_cselect_b32 s71, s50, s54
	s_add_u32 s8, s72, 0x80080
	s_addc_u32 s9, s73, 0
	s_mov_b32 m0, s92
	v_lshl_add_u64 v[216:217], s[8:9], 0, v[164:165]
	ds_read_b128 v[180:183], v191
	ds_read_b128 v[184:187], v191 offset:1024
	ds_read_b128 v[192:195], v191 offset:2048
	ds_read_b128 v[196:199], v191 offset:3072
	ds_read_b128 v[200:203], v191 offset:4096
	ds_read_b128 v[204:207], v191 offset:5120
	ds_read_b128 v[208:211], v191 offset:6144
	ds_read_b128 v[212:215], v191 offset:7168
	global_load_lds_dwordx4 v[216:217], off
	v_lshl_add_u64 v[216:217], s[8:9], 0, v[168:169]
	s_mov_b32 m0, s93
	s_nop 0
	global_load_lds_dwordx4 v[216:217], off
	s_waitcnt vmcnt(8)
	s_waitcnt lgkmcnt(0)
	s_barrier
	s_setprio 1
	s_waitcnt lgkmcnt(0)
	v_mfma_scale_f32_16x16x128_f8f6f4 v[158:161], v[18:25], v[180:187], 0, v189, v189 op_sel_hi:[0,0,0]
	v_mfma_scale_f32_16x16x128_f8f6f4 v[150:153], v[18:25], v[192:199], 0, v189, v189 op_sel_hi:[0,0,0]
	v_mfma_scale_f32_16x16x128_f8f6f4 v[142:145], v[18:25], v[200:207], 0, v189, v189 op_sel_hi:[0,0,0]
	v_mfma_scale_f32_16x16x128_f8f6f4 v[134:137], v[18:25], v[208:215], 0, v189, v189 op_sel_hi:[0,0,0]
	v_mfma_scale_f32_16x16x128_f8f6f4 v[130:133], v[26:33], v[208:215], 0, v189, v189 op_sel_hi:[0,0,0]
	v_mfma_scale_f32_16x16x128_f8f6f4 v[138:141], v[26:33], v[200:207], 0, v189, v189 op_sel_hi:[0,0,0]
	v_mfma_scale_f32_16x16x128_f8f6f4 v[146:149], v[26:33], v[192:199], 0, v189, v189 op_sel_hi:[0,0,0]
	v_mfma_scale_f32_16x16x128_f8f6f4 v[154:157], v[26:33], v[180:187], 0, v189, v189 op_sel_hi:[0,0,0]
	s_setprio 0
	s_setprio 1
	v_mfma_scale_f32_16x16x128_f8f6f4 v[122:125], v[10:17], v[180:187], 0, v189, v189 op_sel_hi:[0,0,0]
	v_mfma_scale_f32_16x16x128_f8f6f4 v[114:117], v[10:17], v[192:199], 0, v189, v189 op_sel_hi:[0,0,0]
	v_mfma_scale_f32_16x16x128_f8f6f4 v[106:109], v[10:17], v[200:207], 0, v189, v189 op_sel_hi:[0,0,0]
	v_mfma_scale_f32_16x16x128_f8f6f4 v[98:101], v[10:17], v[208:215], 0, v189, v189 op_sel_hi:[0,0,0]
	v_mfma_scale_f32_16x16x128_f8f6f4 v[102:105], v[2:9], v[208:215], 0, v189, v189 op_sel_hi:[0,0,0]
	v_mfma_scale_f32_16x16x128_f8f6f4 v[110:113], v[2:9], v[200:207], 0, v189, v189 op_sel_hi:[0,0,0]
	v_mfma_scale_f32_16x16x128_f8f6f4 v[118:121], v[2:9], v[192:199], 0, v189, v189 op_sel_hi:[0,0,0]
	v_mfma_scale_f32_16x16x128_f8f6f4 v[126:129], v[2:9], v[180:187], 0, v189, v189 op_sel_hi:[0,0,0]
	s_setprio 0
	s_barrier
	v_lshl_add_u64 v[180:181], s[54:55], 0, v[166:167]
	s_mov_b32 m0, s77
	v_lshl_add_u64 v[182:183], v[180:181], 0, s[16:17]
	ds_read_b128 v[192:195], v191 offset:16384
	ds_read_b128 v[196:199], v191 offset:17408
	ds_read_b128 v[200:203], v191 offset:18432
	ds_read_b128 v[204:207], v191 offset:19456
	ds_read_b128 v[208:211], v191 offset:20480
	ds_read_b128 v[212:215], v191 offset:21504
	ds_read_b128 v[216:219], v191 offset:22528
	ds_read_b128 v[220:223], v191 offset:23552
	global_load_lds_dwordx4 v[182:183], off
	v_lshl_add_u64 v[182:183], s[54:55], 0, v[170:171]
	s_add_u32 s8, s54, 0x80100
	v_lshl_add_u64 v[184:185], v[182:183], 0, s[16:17]
	s_mov_b32 m0, s78
	s_addc_u32 s9, s55, 0
	global_load_lds_dwordx4 v[184:185], off
	v_lshl_add_u64 v[184:185], s[8:9], 0, v[166:167]
	s_mov_b32 m0, s79
	s_nop 0
	global_load_lds_dwordx4 v[184:185], off
	v_lshl_add_u64 v[184:185], s[8:9], 0, v[170:171]
	s_mov_b32 m0, s80
	s_nop 0
	global_load_lds_dwordx4 v[184:185], off
	v_lshl_add_u64 v[184:185], s[72:73], 0, v[164:165]
	v_lshl_add_u64 v[186:187], v[184:185], 0, s[16:17]
	s_mov_b32 m0, s53
	s_nop 0
	global_load_lds_dwordx4 v[186:187], off
	v_lshl_add_u64 v[186:187], s[72:73], 0, v[168:169]
	v_lshl_add_u64 v[224:225], v[186:187], 0, s[16:17]
	s_mov_b32 m0, s81
	s_nop 0
	global_load_lds_dwordx4 v[224:225], off
	s_waitcnt vmcnt(8)
	s_waitcnt lgkmcnt(0)
	s_barrier
	s_setprio 1
	s_waitcnt lgkmcnt(0)
	v_mfma_scale_f32_16x16x128_f8f6f4 v[94:97], v[18:25], v[192:199], 0, v189, v189 op_sel_hi:[0,0,0]
	v_mfma_scale_f32_16x16x128_f8f6f4 v[86:89], v[18:25], v[200:207], 0, v189, v189 op_sel_hi:[0,0,0]
	v_mfma_scale_f32_16x16x128_f8f6f4 v[78:81], v[18:25], v[208:215], 0, v189, v189 op_sel_hi:[0,0,0]
	v_mfma_scale_f32_16x16x128_f8f6f4 v[70:73], v[18:25], v[216:223], 0, v189, v189 op_sel_hi:[0,0,0]
	v_mfma_scale_f32_16x16x128_f8f6f4 v[66:69], v[26:33], v[216:223], 0, v189, v189 op_sel_hi:[0,0,0]
	v_mfma_scale_f32_16x16x128_f8f6f4 v[74:77], v[26:33], v[208:215], 0, v189, v189 op_sel_hi:[0,0,0]
	v_mfma_scale_f32_16x16x128_f8f6f4 v[82:85], v[26:33], v[200:207], 0, v189, v189 op_sel_hi:[0,0,0]
	v_mfma_scale_f32_16x16x128_f8f6f4 v[90:93], v[26:33], v[192:199], 0, v189, v189 op_sel_hi:[0,0,0]
	s_setprio 0
	s_setprio 1
	v_mfma_scale_f32_16x16x128_f8f6f4 v[58:61], v[10:17], v[192:199], 0, v189, v189 op_sel_hi:[0,0,0]
	v_mfma_scale_f32_16x16x128_f8f6f4 v[50:53], v[10:17], v[200:207], 0, v189, v189 op_sel_hi:[0,0,0]
	v_mfma_scale_f32_16x16x128_f8f6f4 v[42:45], v[10:17], v[208:215], 0, v189, v189 op_sel_hi:[0,0,0]
	v_mfma_scale_f32_16x16x128_f8f6f4 v[34:37], v[10:17], v[216:223], 0, v189, v189 op_sel_hi:[0,0,0]
	v_mfma_scale_f32_16x16x128_f8f6f4 v[38:41], v[2:9], v[216:223], 0, v189, v189 op_sel_hi:[0,0,0]
	v_mfma_scale_f32_16x16x128_f8f6f4 v[46:49], v[2:9], v[208:215], 0, v189, v189 op_sel_hi:[0,0,0]
	v_mfma_scale_f32_16x16x128_f8f6f4 v[54:57], v[2:9], v[200:207], 0, v189, v189 op_sel_hi:[0,0,0]
	v_mfma_scale_f32_16x16x128_f8f6f4 v[62:65], v[2:9], v[192:199], 0, v189, v189 op_sel_hi:[0,0,0]
	s_setprio 0
	s_barrier
	ds_read_b128 v[18:21], v190 offset:32768
	ds_read_b128 v[22:25], v190 offset:33792
	ds_read_b128 v[26:29], v190 offset:34816
	ds_read_b128 v[30:33], v190 offset:35840
	ds_read_b128 v[2:5], v190 offset:49152
	ds_read_b128 v[6:9], v190 offset:50176
	ds_read_b128 v[10:13], v190 offset:51200
	ds_read_b128 v[14:17], v190 offset:52224
	s_add_u32 s8, s72, 0x80100
	s_addc_u32 s9, s73, 0
	s_mov_b32 m0, s82
	v_lshl_add_u64 v[224:225], s[8:9], 0, v[164:165]
	ds_read_b128 v[192:195], v191 offset:32768
	ds_read_b128 v[196:199], v191 offset:33792
	ds_read_b128 v[200:203], v191 offset:34816
	ds_read_b128 v[204:207], v191 offset:35840
	ds_read_b128 v[208:211], v191 offset:36864
	ds_read_b128 v[212:215], v191 offset:37888
	ds_read_b128 v[216:219], v191 offset:38912
	ds_read_b128 v[220:223], v191 offset:39936
	global_load_lds_dwordx4 v[224:225], off
	v_lshl_add_u64 v[224:225], s[8:9], 0, v[168:169]
	s_mov_b32 m0, s83
	s_nop 0
	global_load_lds_dwordx4 v[224:225], off
	s_waitcnt vmcnt(8)
	s_waitcnt lgkmcnt(0)
	s_barrier
	s_setprio 1
	s_waitcnt lgkmcnt(0)
	v_mfma_scale_f32_16x16x128_f8f6f4 v[158:161], v[18:25], v[192:199], v[158:161], v189, v189 op_sel_hi:[0,0,0]
	v_mfma_scale_f32_16x16x128_f8f6f4 v[150:153], v[18:25], v[200:207], v[150:153], v189, v189 op_sel_hi:[0,0,0]
	v_mfma_scale_f32_16x16x128_f8f6f4 v[142:145], v[18:25], v[208:215], v[142:145], v189, v189 op_sel_hi:[0,0,0]
	v_mfma_scale_f32_16x16x128_f8f6f4 v[134:137], v[18:25], v[216:223], v[134:137], v189, v189 op_sel_hi:[0,0,0]
	v_mfma_scale_f32_16x16x128_f8f6f4 v[130:133], v[26:33], v[216:223], v[130:133], v189, v189 op_sel_hi:[0,0,0]
	v_mfma_scale_f32_16x16x128_f8f6f4 v[138:141], v[26:33], v[208:215], v[138:141], v189, v189 op_sel_hi:[0,0,0]
	v_mfma_scale_f32_16x16x128_f8f6f4 v[146:149], v[26:33], v[200:207], v[146:149], v189, v189 op_sel_hi:[0,0,0]
	v_mfma_scale_f32_16x16x128_f8f6f4 v[154:157], v[26:33], v[192:199], v[154:157], v189, v189 op_sel_hi:[0,0,0]
	s_setprio 0
	s_setprio 1
	v_mfma_scale_f32_16x16x128_f8f6f4 v[122:125], v[10:17], v[192:199], v[122:125], v189, v189 op_sel_hi:[0,0,0]
	v_mfma_scale_f32_16x16x128_f8f6f4 v[114:117], v[10:17], v[200:207], v[114:117], v189, v189 op_sel_hi:[0,0,0]
	v_mfma_scale_f32_16x16x128_f8f6f4 v[106:109], v[10:17], v[208:215], v[106:109], v189, v189 op_sel_hi:[0,0,0]
	v_mfma_scale_f32_16x16x128_f8f6f4 v[98:101], v[10:17], v[216:223], v[98:101], v189, v189 op_sel_hi:[0,0,0]
	v_mfma_scale_f32_16x16x128_f8f6f4 v[102:105], v[2:9], v[216:223], v[102:105], v189, v189 op_sel_hi:[0,0,0]
	v_mfma_scale_f32_16x16x128_f8f6f4 v[110:113], v[2:9], v[208:215], v[110:113], v189, v189 op_sel_hi:[0,0,0]
	v_mfma_scale_f32_16x16x128_f8f6f4 v[118:121], v[2:9], v[200:207], v[118:121], v189, v189 op_sel_hi:[0,0,0]
	v_mfma_scale_f32_16x16x128_f8f6f4 v[126:129], v[2:9], v[192:199], v[126:129], v189, v189 op_sel_hi:[0,0,0]
	s_setprio 0
	s_barrier
	s_mov_b32 m0, s86
	v_lshl_add_u64 v[180:181], v[180:181], 0, s[20:21]
	s_add_u32 s8, s54, 0x80180
	ds_read_b128 v[192:195], v191 offset:49152
	ds_read_b128 v[196:199], v191 offset:50176
	ds_read_b128 v[200:203], v191 offset:51200
	ds_read_b128 v[204:207], v191 offset:52224
	ds_read_b128 v[208:211], v191 offset:53248
	ds_read_b128 v[212:215], v191 offset:54272
	ds_read_b128 v[216:219], v191 offset:55296
	ds_read_b128 v[220:223], v191 offset:56320
	global_load_lds_dwordx4 v[180:181], off
	v_lshl_add_u64 v[180:181], v[182:183], 0, s[20:21]
	s_mov_b32 m0, s87
	s_addc_u32 s9, s55, 0
	global_load_lds_dwordx4 v[180:181], off
	v_lshl_add_u64 v[180:181], s[8:9], 0, v[166:167]
	s_mov_b32 m0, s90
	s_nop 0
	global_load_lds_dwordx4 v[180:181], off
	v_lshl_add_u64 v[180:181], s[8:9], 0, v[170:171]
	s_mov_b32 m0, s91
	s_nop 0
	global_load_lds_dwordx4 v[180:181], off
	v_lshl_add_u64 v[180:181], v[184:185], 0, s[20:21]
	s_mov_b32 m0, s88
	s_nop 0
	global_load_lds_dwordx4 v[180:181], off
	v_lshl_add_u64 v[180:181], v[186:187], 0, s[20:21]
	s_mov_b32 m0, s89
	s_nop 0
	global_load_lds_dwordx4 v[180:181], off
	s_waitcnt vmcnt(8)
	s_waitcnt lgkmcnt(0)
	s_barrier
	s_setprio 1
	s_waitcnt lgkmcnt(0)
	v_mfma_scale_f32_16x16x128_f8f6f4 v[94:97], v[18:25], v[192:199], v[94:97], v189, v189 op_sel_hi:[0,0,0]
	v_mfma_scale_f32_16x16x128_f8f6f4 v[86:89], v[18:25], v[200:207], v[86:89], v189, v189 op_sel_hi:[0,0,0]
	v_mfma_scale_f32_16x16x128_f8f6f4 v[78:81], v[18:25], v[208:215], v[78:81], v189, v189 op_sel_hi:[0,0,0]
	v_mfma_scale_f32_16x16x128_f8f6f4 v[70:73], v[18:25], v[216:223], v[70:73], v189, v189 op_sel_hi:[0,0,0]
	v_mfma_scale_f32_16x16x128_f8f6f4 v[66:69], v[26:33], v[216:223], v[66:69], v189, v189 op_sel_hi:[0,0,0]
	v_mfma_scale_f32_16x16x128_f8f6f4 v[74:77], v[26:33], v[208:215], v[74:77], v189, v189 op_sel_hi:[0,0,0]
	v_mfma_scale_f32_16x16x128_f8f6f4 v[82:85], v[26:33], v[200:207], v[82:85], v189, v189 op_sel_hi:[0,0,0]
	v_mfma_scale_f32_16x16x128_f8f6f4 v[90:93], v[26:33], v[192:199], v[90:93], v189, v189 op_sel_hi:[0,0,0]
	s_setprio 0
	s_setprio 1
	v_mfma_scale_f32_16x16x128_f8f6f4 v[58:61], v[10:17], v[192:199], v[58:61], v189, v189 op_sel_hi:[0,0,0]
	v_mfma_scale_f32_16x16x128_f8f6f4 v[50:53], v[10:17], v[200:207], v[50:53], v189, v189 op_sel_hi:[0,0,0]
	v_mfma_scale_f32_16x16x128_f8f6f4 v[42:45], v[10:17], v[208:215], v[42:45], v189, v189 op_sel_hi:[0,0,0]
	v_mfma_scale_f32_16x16x128_f8f6f4 v[34:37], v[10:17], v[216:223], v[34:37], v189, v189 op_sel_hi:[0,0,0]
	v_mfma_scale_f32_16x16x128_f8f6f4 v[38:41], v[2:9], v[216:223], v[38:41], v189, v189 op_sel_hi:[0,0,0]
	v_mfma_scale_f32_16x16x128_f8f6f4 v[46:49], v[2:9], v[208:215], v[46:49], v189, v189 op_sel_hi:[0,0,0]
	v_mfma_scale_f32_16x16x128_f8f6f4 v[54:57], v[2:9], v[200:207], v[54:57], v189, v189 op_sel_hi:[0,0,0]
	v_mfma_scale_f32_16x16x128_f8f6f4 v[62:65], v[2:9], v[192:199], v[62:65], v189, v189 op_sel_hi:[0,0,0]
	s_setprio 0
	s_barrier
	s_add_u32 s72, s72, 0x80180
	s_addc_u32 s73, s73, 0
	s_add_u32 s8, s54, 0x200
	s_addc_u32 s9, s55, 0
	s_mov_b32 s62, 0
.LBB0_198:
	ds_read_b128 v[2:5], v190
	ds_read_b128 v[6:9], v190 offset:1024
	ds_read_b128 v[18:21], v190 offset:2048
	ds_read_b128 v[22:25], v190 offset:3072
	ds_read_b128 v[26:29], v190 offset:16384
	ds_read_b128 v[30:33], v190 offset:17408
	ds_read_b128 v[180:183], v190 offset:18432
	ds_read_b128 v[184:187], v190 offset:19456
	s_add_u32 s54, s72, 0xfff80080
	s_addc_u32 s55, s73, -1
	s_cmp_eq_u32 s62, 28
	s_cselect_b32 s75, s47, s55
	s_cselect_b32 s74, s70, s54
	s_cselect_b32 s55, s45, s9
	s_cselect_b32 s54, s71, s8
	s_mov_b32 m0, s92
	v_lshl_add_u64 v[216:217], s[72:73], 0, v[172:173]
	ds_read_b128 v[10:13], v191
	ds_read_b128 v[14:17], v191 offset:1024
	ds_read_b128 v[192:195], v191 offset:2048
	ds_read_b128 v[196:199], v191 offset:3072
	ds_read_b128 v[200:203], v191 offset:4096
	ds_read_b128 v[204:207], v191 offset:5120
	ds_read_b128 v[208:211], v191 offset:6144
	ds_read_b128 v[212:215], v191 offset:7168
	global_load_lds_dwordx4 v[216:217], off
	v_lshl_add_u64 v[216:217], s[72:73], 0, v[174:175]
	s_mov_b32 m0, s93
	s_nop 0
	global_load_lds_dwordx4 v[216:217], off
	s_waitcnt vmcnt(8)
	s_waitcnt lgkmcnt(0)
	s_barrier
	s_setprio 1
	s_waitcnt lgkmcnt(0)
	v_mfma_scale_f32_16x16x128_f8f6f4 v[158:161], v[2:9], v[10:17], v[158:161], v189, v189 op_sel_hi:[0,0,0]
	v_mfma_scale_f32_16x16x128_f8f6f4 v[150:153], v[2:9], v[192:199], v[150:153], v189, v189 op_sel_hi:[0,0,0]
	v_mfma_scale_f32_16x16x128_f8f6f4 v[142:145], v[2:9], v[200:207], v[142:145], v189, v189 op_sel_hi:[0,0,0]
	v_mfma_scale_f32_16x16x128_f8f6f4 v[134:137], v[2:9], v[208:215], v[134:137], v189, v189 op_sel_hi:[0,0,0]
	v_mfma_scale_f32_16x16x128_f8f6f4 v[130:133], v[18:25], v[208:215], v[130:133], v189, v189 op_sel_hi:[0,0,0]
	v_mfma_scale_f32_16x16x128_f8f6f4 v[138:141], v[18:25], v[200:207], v[138:141], v189, v189 op_sel_hi:[0,0,0]
	v_mfma_scale_f32_16x16x128_f8f6f4 v[146:149], v[18:25], v[192:199], v[146:149], v189, v189 op_sel_hi:[0,0,0]
	v_mfma_scale_f32_16x16x128_f8f6f4 v[154:157], v[18:25], v[10:17], v[154:157], v189, v189 op_sel_hi:[0,0,0]
	s_setprio 0
	s_setprio 1
	v_mfma_scale_f32_16x16x128_f8f6f4 v[122:125], v[180:187], v[10:17], v[122:125], v189, v189 op_sel_hi:[0,0,0]
	v_mfma_scale_f32_16x16x128_f8f6f4 v[114:117], v[180:187], v[192:199], v[114:117], v189, v189 op_sel_hi:[0,0,0]
	v_mfma_scale_f32_16x16x128_f8f6f4 v[106:109], v[180:187], v[200:207], v[106:109], v189, v189 op_sel_hi:[0,0,0]
	v_mfma_scale_f32_16x16x128_f8f6f4 v[98:101], v[180:187], v[208:215], v[98:101], v189, v189 op_sel_hi:[0,0,0]
	v_mfma_scale_f32_16x16x128_f8f6f4 v[102:105], v[26:33], v[208:215], v[102:105], v189, v189 op_sel_hi:[0,0,0]
	v_mfma_scale_f32_16x16x128_f8f6f4 v[110:113], v[26:33], v[200:207], v[110:113], v189, v189 op_sel_hi:[0,0,0]
	v_mfma_scale_f32_16x16x128_f8f6f4 v[118:121], v[26:33], v[192:199], v[118:121], v189, v189 op_sel_hi:[0,0,0]
	v_mfma_scale_f32_16x16x128_f8f6f4 v[126:129], v[26:33], v[10:17], v[126:129], v189, v189 op_sel_hi:[0,0,0]
	s_setprio 0
	s_barrier
	s_mov_b32 m0, s77
	v_lshl_add_u64 v[10:11], s[54:55], 0, v[166:167]
	s_add_u32 vcc_lo, s54, 0x80000
	ds_read_b128 v[192:195], v191 offset:16384
	ds_read_b128 v[196:199], v191 offset:17408
	ds_read_b128 v[200:203], v191 offset:18432
	ds_read_b128 v[204:207], v191 offset:19456
	ds_read_b128 v[208:211], v191 offset:20480
	ds_read_b128 v[212:215], v191 offset:21504
	ds_read_b128 v[216:219], v191 offset:22528
	ds_read_b128 v[220:223], v191 offset:23552
	global_load_lds_dwordx4 v[10:11], off
	v_lshl_add_u64 v[12:13], s[54:55], 0, v[170:171]
	s_mov_b32 m0, s78
	s_addc_u32 vcc_hi, s55, 0
	global_load_lds_dwordx4 v[12:13], off
	v_lshl_add_u64 v[14:15], vcc, 0, v[166:167]
	s_mov_b32 m0, s79
	v_lshl_add_u64 v[16:17], s[74:75], 0, v[168:169]
	global_load_lds_dwordx4 v[14:15], off
	v_lshl_add_u64 v[14:15], vcc, 0, v[170:171]
	s_mov_b32 m0, s80
	s_nop 0
	global_load_lds_dwordx4 v[14:15], off
	v_lshl_add_u64 v[14:15], s[74:75], 0, v[164:165]
	s_mov_b32 m0, s53
	s_nop 0
	global_load_lds_dwordx4 v[14:15], off
	s_mov_b32 m0, s81
	s_nop 0
	global_load_lds_dwordx4 v[16:17], off
	s_waitcnt vmcnt(8)
	s_waitcnt lgkmcnt(0)
	s_barrier
	s_setprio 1
	s_waitcnt lgkmcnt(0)
	v_mfma_scale_f32_16x16x128_f8f6f4 v[94:97], v[2:9], v[192:199], v[94:97], v189, v189 op_sel_hi:[0,0,0]
	v_mfma_scale_f32_16x16x128_f8f6f4 v[86:89], v[2:9], v[200:207], v[86:89], v189, v189 op_sel_hi:[0,0,0]
	v_mfma_scale_f32_16x16x128_f8f6f4 v[78:81], v[2:9], v[208:215], v[78:81], v189, v189 op_sel_hi:[0,0,0]
	v_mfma_scale_f32_16x16x128_f8f6f4 v[70:73], v[2:9], v[216:223], v[70:73], v189, v189 op_sel_hi:[0,0,0]
	v_mfma_scale_f32_16x16x128_f8f6f4 v[66:69], v[18:25], v[216:223], v[66:69], v189, v189 op_sel_hi:[0,0,0]
	v_mfma_scale_f32_16x16x128_f8f6f4 v[74:77], v[18:25], v[208:215], v[74:77], v189, v189 op_sel_hi:[0,0,0]
	v_mfma_scale_f32_16x16x128_f8f6f4 v[82:85], v[18:25], v[200:207], v[82:85], v189, v189 op_sel_hi:[0,0,0]
	v_mfma_scale_f32_16x16x128_f8f6f4 v[90:93], v[18:25], v[192:199], v[90:93], v189, v189 op_sel_hi:[0,0,0]
	s_setprio 0
	s_setprio 1
	v_mfma_scale_f32_16x16x128_f8f6f4 v[58:61], v[180:187], v[192:199], v[58:61], v189, v189 op_sel_hi:[0,0,0]
	v_mfma_scale_f32_16x16x128_f8f6f4 v[50:53], v[180:187], v[200:207], v[50:53], v189, v189 op_sel_hi:[0,0,0]
	v_mfma_scale_f32_16x16x128_f8f6f4 v[42:45], v[180:187], v[208:215], v[42:45], v189, v189 op_sel_hi:[0,0,0]
	v_mfma_scale_f32_16x16x128_f8f6f4 v[34:37], v[180:187], v[216:223], v[34:37], v189, v189 op_sel_hi:[0,0,0]
	v_mfma_scale_f32_16x16x128_f8f6f4 v[38:41], v[26:33], v[216:223], v[38:41], v189, v189 op_sel_hi:[0,0,0]
	v_mfma_scale_f32_16x16x128_f8f6f4 v[46:49], v[26:33], v[208:215], v[46:49], v189, v189 op_sel_hi:[0,0,0]
	v_mfma_scale_f32_16x16x128_f8f6f4 v[54:57], v[26:33], v[200:207], v[54:57], v189, v189 op_sel_hi:[0,0,0]
	v_mfma_scale_f32_16x16x128_f8f6f4 v[62:65], v[26:33], v[192:199], v[62:65], v189, v189 op_sel_hi:[0,0,0]
	s_setprio 0
	s_barrier
	ds_read_b128 v[18:21], v190 offset:32768
	ds_read_b128 v[22:25], v190 offset:33792
	ds_read_b128 v[26:29], v190 offset:34816
	ds_read_b128 v[30:33], v190 offset:35840
	ds_read_b128 v[2:5], v190 offset:49152
	ds_read_b128 v[6:9], v190 offset:50176
	ds_read_b128 v[180:183], v190 offset:51200
	ds_read_b128 v[184:187], v190 offset:52224
	s_add_u32 s74, s74, 0x80000
	s_addc_u32 s75, s75, 0
	s_mov_b32 m0, s82
	v_lshl_add_u64 v[224:225], s[74:75], 0, v[164:165]
	ds_read_b128 v[192:195], v191 offset:32768
	ds_read_b128 v[196:199], v191 offset:33792
	ds_read_b128 v[200:203], v191 offset:34816
	ds_read_b128 v[204:207], v191 offset:35840
	ds_read_b128 v[208:211], v191 offset:36864
	ds_read_b128 v[212:215], v191 offset:37888
	ds_read_b128 v[216:219], v191 offset:38912
	ds_read_b128 v[220:223], v191 offset:39936
	global_load_lds_dwordx4 v[224:225], off
	v_lshl_add_u64 v[224:225], s[74:75], 0, v[168:169]
	s_mov_b32 m0, s83
	s_nop 0
	global_load_lds_dwordx4 v[224:225], off
	s_waitcnt vmcnt(8)
	s_waitcnt lgkmcnt(0)
	s_barrier
	s_setprio 1
	s_waitcnt lgkmcnt(0)
	v_mfma_scale_f32_16x16x128_f8f6f4 v[158:161], v[18:25], v[192:199], v[158:161], v189, v189 op_sel_hi:[0,0,0]
	v_mfma_scale_f32_16x16x128_f8f6f4 v[150:153], v[18:25], v[200:207], v[150:153], v189, v189 op_sel_hi:[0,0,0]
	v_mfma_scale_f32_16x16x128_f8f6f4 v[142:145], v[18:25], v[208:215], v[142:145], v189, v189 op_sel_hi:[0,0,0]
	v_mfma_scale_f32_16x16x128_f8f6f4 v[134:137], v[18:25], v[216:223], v[134:137], v189, v189 op_sel_hi:[0,0,0]
	v_mfma_scale_f32_16x16x128_f8f6f4 v[130:133], v[26:33], v[216:223], v[130:133], v189, v189 op_sel_hi:[0,0,0]
	v_mfma_scale_f32_16x16x128_f8f6f4 v[138:141], v[26:33], v[208:215], v[138:141], v189, v189 op_sel_hi:[0,0,0]
	v_mfma_scale_f32_16x16x128_f8f6f4 v[146:149], v[26:33], v[200:207], v[146:149], v189, v189 op_sel_hi:[0,0,0]
	v_mfma_scale_f32_16x16x128_f8f6f4 v[154:157], v[26:33], v[192:199], v[154:157], v189, v189 op_sel_hi:[0,0,0]
	s_setprio 0
	s_setprio 1
	v_mfma_scale_f32_16x16x128_f8f6f4 v[122:125], v[180:187], v[192:199], v[122:125], v189, v189 op_sel_hi:[0,0,0]
	v_mfma_scale_f32_16x16x128_f8f6f4 v[114:117], v[180:187], v[200:207], v[114:117], v189, v189 op_sel_hi:[0,0,0]
	v_mfma_scale_f32_16x16x128_f8f6f4 v[106:109], v[180:187], v[208:215], v[106:109], v189, v189 op_sel_hi:[0,0,0]
	v_mfma_scale_f32_16x16x128_f8f6f4 v[98:101], v[180:187], v[216:223], v[98:101], v189, v189 op_sel_hi:[0,0,0]
	v_mfma_scale_f32_16x16x128_f8f6f4 v[102:105], v[2:9], v[216:223], v[102:105], v189, v189 op_sel_hi:[0,0,0]
	v_mfma_scale_f32_16x16x128_f8f6f4 v[110:113], v[2:9], v[208:215], v[110:113], v189, v189 op_sel_hi:[0,0,0]
	v_mfma_scale_f32_16x16x128_f8f6f4 v[118:121], v[2:9], v[200:207], v[118:121], v189, v189 op_sel_hi:[0,0,0]
	v_mfma_scale_f32_16x16x128_f8f6f4 v[126:129], v[2:9], v[192:199], v[126:129], v189, v189 op_sel_hi:[0,0,0]
	s_setprio 0
	s_barrier
	s_mov_b32 m0, s86
	v_lshl_add_u64 v[10:11], v[10:11], 0, s[4:5]
	s_add_u32 s54, s54, 0x80080
	ds_read_b128 v[192:195], v191 offset:49152
	ds_read_b128 v[196:199], v191 offset:50176
	ds_read_b128 v[200:203], v191 offset:51200
	ds_read_b128 v[204:207], v191 offset:52224
	ds_read_b128 v[208:211], v191 offset:53248
	ds_read_b128 v[212:215], v191 offset:54272
	ds_read_b128 v[216:219], v191 offset:55296
	ds_read_b128 v[220:223], v191 offset:56320
	global_load_lds_dwordx4 v[10:11], off
	v_lshl_add_u64 v[10:11], v[12:13], 0, s[4:5]
	s_mov_b32 m0, s87
	s_addc_u32 s55, s55, 0
	global_load_lds_dwordx4 v[10:11], off
	v_lshl_add_u64 v[10:11], s[54:55], 0, v[166:167]
	s_mov_b32 m0, s90
	s_nop 0
	global_load_lds_dwordx4 v[10:11], off
	v_lshl_add_u64 v[10:11], s[54:55], 0, v[170:171]
	s_mov_b32 m0, s91
	s_nop 0
	global_load_lds_dwordx4 v[10:11], off
	v_lshl_add_u64 v[10:11], v[14:15], 0, s[4:5]
	s_mov_b32 m0, s88
	s_nop 0
	global_load_lds_dwordx4 v[10:11], off
	v_lshl_add_u64 v[10:11], v[16:17], 0, s[4:5]
	s_mov_b32 m0, s89
	s_nop 0
	global_load_lds_dwordx4 v[10:11], off
	s_waitcnt vmcnt(8)
	s_waitcnt lgkmcnt(0)
	s_barrier
	s_setprio 1
	s_waitcnt lgkmcnt(0)
	v_mfma_scale_f32_16x16x128_f8f6f4 v[94:97], v[18:25], v[192:199], v[94:97], v189, v189 op_sel_hi:[0,0,0]
	v_mfma_scale_f32_16x16x128_f8f6f4 v[86:89], v[18:25], v[200:207], v[86:89], v189, v189 op_sel_hi:[0,0,0]
	v_mfma_scale_f32_16x16x128_f8f6f4 v[78:81], v[18:25], v[208:215], v[78:81], v189, v189 op_sel_hi:[0,0,0]
	v_mfma_scale_f32_16x16x128_f8f6f4 v[70:73], v[18:25], v[216:223], v[70:73], v189, v189 op_sel_hi:[0,0,0]
	v_mfma_scale_f32_16x16x128_f8f6f4 v[66:69], v[26:33], v[216:223], v[66:69], v189, v189 op_sel_hi:[0,0,0]
	v_mfma_scale_f32_16x16x128_f8f6f4 v[74:77], v[26:33], v[208:215], v[74:77], v189, v189 op_sel_hi:[0,0,0]
	v_mfma_scale_f32_16x16x128_f8f6f4 v[82:85], v[26:33], v[200:207], v[82:85], v189, v189 op_sel_hi:[0,0,0]
	v_mfma_scale_f32_16x16x128_f8f6f4 v[90:93], v[26:33], v[192:199], v[90:93], v189, v189 op_sel_hi:[0,0,0]
	s_setprio 0
	s_setprio 1
	v_mfma_scale_f32_16x16x128_f8f6f4 v[58:61], v[180:187], v[192:199], v[58:61], v189, v189 op_sel_hi:[0,0,0]
	v_mfma_scale_f32_16x16x128_f8f6f4 v[50:53], v[180:187], v[200:207], v[50:53], v189, v189 op_sel_hi:[0,0,0]
	v_mfma_scale_f32_16x16x128_f8f6f4 v[42:45], v[180:187], v[208:215], v[42:45], v189, v189 op_sel_hi:[0,0,0]
	v_mfma_scale_f32_16x16x128_f8f6f4 v[34:37], v[180:187], v[216:223], v[34:37], v189, v189 op_sel_hi:[0,0,0]
	v_mfma_scale_f32_16x16x128_f8f6f4 v[38:41], v[2:9], v[216:223], v[38:41], v189, v189 op_sel_hi:[0,0,0]
	v_mfma_scale_f32_16x16x128_f8f6f4 v[46:49], v[2:9], v[208:215], v[46:49], v189, v189 op_sel_hi:[0,0,0]
	v_mfma_scale_f32_16x16x128_f8f6f4 v[54:57], v[2:9], v[200:207], v[54:57], v189, v189 op_sel_hi:[0,0,0]
	v_mfma_scale_f32_16x16x128_f8f6f4 v[62:65], v[2:9], v[192:199], v[62:65], v189, v189 op_sel_hi:[0,0,0]
	s_setprio 0
	s_barrier
	s_add_i32 s62, s62, 2
	s_add_u32 s72, s72, 0x100
	s_addc_u32 s73, s73, 0
	s_add_u32 s8, s8, 0x100
	s_addc_u32 s9, s9, 0
	s_cmp_gt_u32 s62, 29
	s_cbranch_scc0 .LBB0_198
	s_and_b64 vcc, exec, s[6:7]
	s_cbranch_vccz .LBB0_201
	s_barrier

.LBB0_282:
	ds_read_b128 v[2:5], v187
	ds_read_b128 v[6:9], v187 offset:1024
	ds_read_b128 v[174:177], v187 offset:2048
	ds_read_b128 v[178:181], v187 offset:3072
	ds_read_b128 v[190:193], v187 offset:16384
	ds_read_b128 v[194:197], v187 offset:17408
	ds_read_b128 v[198:201], v187 offset:18432
	ds_read_b128 v[202:205], v187 offset:19456
	s_add_u32 s49, s52, 0x100
	s_addc_u32 s71, s53, 0
	s_and_b64 s[62:63], s[54:55], exec
	s_cselect_b32 s73, s1, s71
	s_cselect_b32 s72, s0, s49
	s_add_u32 s49, s50, 0x100
	s_addc_u32 s62, s51, 0
	s_and_b64 s[54:55], s[54:55], exec
	s_cselect_b32 s55, s5, s62
	s_cselect_b32 s54, s4, s49
	s_add_u32 s62, s52, 0x158080
	s_addc_u32 s63, s53, 0
	s_add_i32 s49, s33, 0xc000
	v_lshl_add_u64 v[182:183], s[62:63], 0, v[154:155]
	s_mov_b32 m0, s49
	s_add_i32 s71, s33, 0xe000
	ds_read_b128 v[206:209], v188
	ds_read_b128 v[210:213], v188 offset:1024
	ds_read_b128 v[214:217], v188 offset:2048
	ds_read_b128 v[218:221], v188 offset:3072
	ds_read_b128 v[222:225], v188 offset:4096
	ds_read_b128 v[226:229], v188 offset:5120
	ds_read_b128 v[230:233], v188 offset:6144
	ds_read_b128 v[234:237], v188 offset:7168
	global_load_lds_dwordx4 v[182:183], off
	v_lshl_add_u64 v[182:183], s[62:63], 0, v[158:159]
	s_mov_b32 m0, s71
	s_nop 0
	global_load_lds_dwordx4 v[182:183], off
	s_waitcnt vmcnt(8)
	s_waitcnt lgkmcnt(0)
	s_barrier
	s_setprio 1
	s_waitcnt lgkmcnt(0)
	v_mfma_scale_f32_16x16x128_f8f6f4 v[134:137], v[2:9], v[206:213], 0, v186, v186 op_sel_hi:[0,0,0]
	v_mfma_scale_f32_16x16x128_f8f6f4 v[126:129], v[2:9], v[214:221], 0, v186, v186 op_sel_hi:[0,0,0]
	v_mfma_scale_f32_16x16x128_f8f6f4 v[118:121], v[2:9], v[222:229], 0, v186, v186 op_sel_hi:[0,0,0]
	v_mfma_scale_f32_16x16x128_f8f6f4 v[110:113], v[2:9], v[230:237], 0, v186, v186 op_sel_hi:[0,0,0]
	v_mfma_scale_f32_16x16x128_f8f6f4 v[106:109], v[174:181], v[230:237], 0, v186, v186 op_sel_hi:[0,0,0]
	v_mfma_scale_f32_16x16x128_f8f6f4 v[114:117], v[174:181], v[222:229], 0, v186, v186 op_sel_hi:[0,0,0]
	v_mfma_scale_f32_16x16x128_f8f6f4 v[122:125], v[174:181], v[214:221], 0, v186, v186 op_sel_hi:[0,0,0]
	v_mfma_scale_f32_16x16x128_f8f6f4 v[130:133], v[174:181], v[206:213], 0, v186, v186 op_sel_hi:[0,0,0]
	s_setprio 0
	s_setprio 1
	v_mfma_scale_f32_16x16x128_f8f6f4 v[98:101], v[198:205], v[206:213], 0, v186, v186 op_sel_hi:[0,0,0]
	v_mfma_scale_f32_16x16x128_f8f6f4 v[90:93], v[198:205], v[214:221], 0, v186, v186 op_sel_hi:[0,0,0]
	v_mfma_scale_f32_16x16x128_f8f6f4 v[82:85], v[198:205], v[222:229], 0, v186, v186 op_sel_hi:[0,0,0]
	v_mfma_scale_f32_16x16x128_f8f6f4 v[74:77], v[198:205], v[230:237], 0, v186, v186 op_sel_hi:[0,0,0]
	v_mfma_scale_f32_16x16x128_f8f6f4 v[78:81], v[190:197], v[230:237], 0, v186, v186 op_sel_hi:[0,0,0]
	v_mfma_scale_f32_16x16x128_f8f6f4 v[86:89], v[190:197], v[222:229], 0, v186, v186 op_sel_hi:[0,0,0]
	v_mfma_scale_f32_16x16x128_f8f6f4 v[94:97], v[190:197], v[214:221], 0, v186, v186 op_sel_hi:[0,0,0]
	v_mfma_scale_f32_16x16x128_f8f6f4 v[102:105], v[190:197], v[206:213], 0, v186, v186 op_sel_hi:[0,0,0]
	s_setprio 0
	s_barrier
	s_mov_b32 m0, s47
	v_lshl_add_u64 v[182:183], s[54:55], 0, v[156:157]
	s_add_u32 s62, s54, 0x158000
	ds_read_b128 v[206:209], v188 offset:16384
	ds_read_b128 v[210:213], v188 offset:17408
	ds_read_b128 v[214:217], v188 offset:18432
	ds_read_b128 v[218:221], v188 offset:19456
	ds_read_b128 v[222:225], v188 offset:20480
	ds_read_b128 v[226:229], v188 offset:21504
	ds_read_b128 v[230:233], v188 offset:22528
	ds_read_b128 v[234:237], v188 offset:23552
	global_load_lds_dwordx4 v[182:183], off
	v_lshl_add_u64 v[238:239], s[54:55], 0, v[160:161]
	s_mov_b32 m0, s68
	s_addc_u32 s63, s55, 0
	global_load_lds_dwordx4 v[238:239], off
	v_lshl_add_u64 v[242:243], s[62:63], 0, v[156:157]
	s_mov_b32 m0, s69
	v_lshl_add_u64 v[244:245], s[72:73], 0, v[158:159]
	global_load_lds_dwordx4 v[242:243], off
	v_lshl_add_u64 v[242:243], s[62:63], 0, v[160:161]
	s_mov_b32 m0, s74
	s_nop 0
	global_load_lds_dwordx4 v[242:243], off
	v_lshl_add_u64 v[242:243], s[72:73], 0, v[154:155]
	s_mov_b32 m0, s33
	s_nop 0
	global_load_lds_dwordx4 v[242:243], off
	s_mov_b32 m0, s75
	s_nop 0
	global_load_lds_dwordx4 v[244:245], off
	s_waitcnt vmcnt(8)
	s_waitcnt lgkmcnt(0)
	s_barrier
	s_setprio 1
	s_waitcnt lgkmcnt(0)
	v_mfma_scale_f32_16x16x128_f8f6f4 v[70:73], v[2:9], v[206:213], 0, v186, v186 op_sel_hi:[0,0,0]
	v_mfma_scale_f32_16x16x128_f8f6f4 v[62:65], v[2:9], v[214:221], 0, v186, v186 op_sel_hi:[0,0,0]
	v_mfma_scale_f32_16x16x128_f8f6f4 v[54:57], v[2:9], v[222:229], 0, v186, v186 op_sel_hi:[0,0,0]
	v_mfma_scale_f32_16x16x128_f8f6f4 v[46:49], v[2:9], v[230:237], 0, v186, v186 op_sel_hi:[0,0,0]
	v_mfma_scale_f32_16x16x128_f8f6f4 v[42:45], v[174:181], v[230:237], 0, v186, v186 op_sel_hi:[0,0,0]
	v_mfma_scale_f32_16x16x128_f8f6f4 v[50:53], v[174:181], v[222:229], 0, v186, v186 op_sel_hi:[0,0,0]
	v_mfma_scale_f32_16x16x128_f8f6f4 v[58:61], v[174:181], v[214:221], 0, v186, v186 op_sel_hi:[0,0,0]
	v_mfma_scale_f32_16x16x128_f8f6f4 v[66:69], v[174:181], v[206:213], 0, v186, v186 op_sel_hi:[0,0,0]
	s_setprio 0
	s_setprio 1
	v_mfma_scale_f32_16x16x128_f8f6f4 v[34:37], v[198:205], v[206:213], 0, v186, v186 op_sel_hi:[0,0,0]
	v_mfma_scale_f32_16x16x128_f8f6f4 v[26:29], v[198:205], v[214:221], 0, v186, v186 op_sel_hi:[0,0,0]
	v_mfma_scale_f32_16x16x128_f8f6f4 v[18:21], v[198:205], v[222:229], 0, v186, v186 op_sel_hi:[0,0,0]
	v_mfma_scale_f32_16x16x128_f8f6f4 v[10:13], v[198:205], v[230:237], 0, v186, v186 op_sel_hi:[0,0,0]
	v_mfma_scale_f32_16x16x128_f8f6f4 v[14:17], v[190:197], v[230:237], 0, v186, v186 op_sel_hi:[0,0,0]
	v_mfma_scale_f32_16x16x128_f8f6f4 v[22:25], v[190:197], v[222:229], 0, v186, v186 op_sel_hi:[0,0,0]
	v_mfma_scale_f32_16x16x128_f8f6f4 v[30:33], v[190:197], v[214:221], 0, v186, v186 op_sel_hi:[0,0,0]
	v_mfma_scale_f32_16x16x128_f8f6f4 v[38:41], v[190:197], v[206:213], 0, v186, v186 op_sel_hi:[0,0,0]
	s_setprio 0
	s_barrier
	ds_read_b128 v[2:5], v187 offset:32768
	ds_read_b128 v[6:9], v187 offset:33792
	ds_read_b128 v[174:177], v187 offset:34816
	ds_read_b128 v[178:181], v187 offset:35840
	ds_read_b128 v[190:193], v187 offset:49152
	ds_read_b128 v[194:197], v187 offset:50176
	ds_read_b128 v[198:201], v187 offset:51200
	ds_read_b128 v[202:205], v187 offset:52224
	s_add_u32 s62, s72, 0x158000
	s_addc_u32 s63, s73, 0
	s_mov_b32 m0, s76
	v_lshl_add_u64 v[246:247], s[62:63], 0, v[154:155]
	ds_read_b128 v[206:209], v188 offset:32768
	ds_read_b128 v[210:213], v188 offset:33792
	ds_read_b128 v[214:217], v188 offset:34816
	ds_read_b128 v[218:221], v188 offset:35840
	ds_read_b128 v[222:225], v188 offset:36864
	ds_read_b128 v[226:229], v188 offset:37888
	ds_read_b128 v[230:233], v188 offset:38912
	ds_read_b128 v[234:237], v188 offset:39936
	global_load_lds_dwordx4 v[246:247], off
	v_lshl_add_u64 v[246:247], s[62:63], 0, v[158:159]
	s_mov_b32 m0, s77
	s_nop 0
	global_load_lds_dwordx4 v[246:247], off
	s_waitcnt vmcnt(8)
	s_waitcnt lgkmcnt(0)
	s_barrier
	s_setprio 1
	s_waitcnt lgkmcnt(0)
	v_mfma_scale_f32_16x16x128_f8f6f4 v[134:137], v[2:9], v[206:213], v[134:137], v186, v186 op_sel_hi:[0,0,0]
	v_mfma_scale_f32_16x16x128_f8f6f4 v[126:129], v[2:9], v[214:221], v[126:129], v186, v186 op_sel_hi:[0,0,0]
	v_mfma_scale_f32_16x16x128_f8f6f4 v[118:121], v[2:9], v[222:229], v[118:121], v186, v186 op_sel_hi:[0,0,0]
	v_mfma_scale_f32_16x16x128_f8f6f4 v[110:113], v[2:9], v[230:237], v[110:113], v186, v186 op_sel_hi:[0,0,0]
	v_mfma_scale_f32_16x16x128_f8f6f4 v[106:109], v[174:181], v[230:237], v[106:109], v186, v186 op_sel_hi:[0,0,0]
	v_mfma_scale_f32_16x16x128_f8f6f4 v[114:117], v[174:181], v[222:229], v[114:117], v186, v186 op_sel_hi:[0,0,0]
	v_mfma_scale_f32_16x16x128_f8f6f4 v[122:125], v[174:181], v[214:221], v[122:125], v186, v186 op_sel_hi:[0,0,0]
	v_mfma_scale_f32_16x16x128_f8f6f4 v[130:133], v[174:181], v[206:213], v[130:133], v186, v186 op_sel_hi:[0,0,0]
	s_setprio 0
	s_setprio 1
	v_mfma_scale_f32_16x16x128_f8f6f4 v[98:101], v[198:205], v[206:213], v[98:101], v186, v186 op_sel_hi:[0,0,0]
	v_mfma_scale_f32_16x16x128_f8f6f4 v[90:93], v[198:205], v[214:221], v[90:93], v186, v186 op_sel_hi:[0,0,0]
	v_mfma_scale_f32_16x16x128_f8f6f4 v[82:85], v[198:205], v[222:229], v[82:85], v186, v186 op_sel_hi:[0,0,0]
	v_mfma_scale_f32_16x16x128_f8f6f4 v[74:77], v[198:205], v[230:237], v[74:77], v186, v186 op_sel_hi:[0,0,0]
	v_mfma_scale_f32_16x16x128_f8f6f4 v[78:81], v[190:197], v[230:237], v[78:81], v186, v186 op_sel_hi:[0,0,0]
	v_mfma_scale_f32_16x16x128_f8f6f4 v[86:89], v[190:197], v[222:229], v[86:89], v186, v186 op_sel_hi:[0,0,0]
	v_mfma_scale_f32_16x16x128_f8f6f4 v[94:97], v[190:197], v[214:221], v[94:97], v186, v186 op_sel_hi:[0,0,0]
	v_mfma_scale_f32_16x16x128_f8f6f4 v[102:105], v[190:197], v[206:213], v[102:105], v186, v186 op_sel_hi:[0,0,0]
	s_setprio 0
	s_barrier
	s_mov_b32 m0, s83
	v_lshl_add_u64 v[182:183], v[182:183], 0, s[26:27]
	s_add_u32 s54, s54, 0x158080
	ds_read_b128 v[206:209], v188 offset:49152
	ds_read_b128 v[210:213], v188 offset:50176
	ds_read_b128 v[214:217], v188 offset:51200
	ds_read_b128 v[218:221], v188 offset:52224
	ds_read_b128 v[222:225], v188 offset:53248
	ds_read_b128 v[226:229], v188 offset:54272
	ds_read_b128 v[230:233], v188 offset:55296
	ds_read_b128 v[234:237], v188 offset:56320
	global_load_lds_dwordx4 v[182:183], off
	v_lshl_add_u64 v[182:183], v[238:239], 0, s[26:27]
	s_mov_b32 m0, s84
	s_addc_u32 s55, s55, 0
	global_load_lds_dwordx4 v[182:183], off
	v_lshl_add_u64 v[182:183], s[54:55], 0, v[156:157]
	s_mov_b32 m0, s87
	s_nop 0
	global_load_lds_dwordx4 v[182:183], off
	v_lshl_add_u64 v[182:183], s[54:55], 0, v[160:161]
	s_mov_b32 m0, s88
	s_nop 0
	global_load_lds_dwordx4 v[182:183], off
	v_lshl_add_u64 v[182:183], v[242:243], 0, s[26:27]
	s_mov_b32 m0, s85
	s_nop 0
	global_load_lds_dwordx4 v[182:183], off
	v_lshl_add_u64 v[182:183], v[244:245], 0, s[26:27]
	s_mov_b32 m0, s86
	s_nop 0
	global_load_lds_dwordx4 v[182:183], off
	s_waitcnt vmcnt(8)
	s_waitcnt lgkmcnt(0)
	s_barrier
	s_setprio 1
	s_waitcnt lgkmcnt(0)
	v_mfma_scale_f32_16x16x128_f8f6f4 v[70:73], v[2:9], v[206:213], v[70:73], v186, v186 op_sel_hi:[0,0,0]
	v_mfma_scale_f32_16x16x128_f8f6f4 v[62:65], v[2:9], v[214:221], v[62:65], v186, v186 op_sel_hi:[0,0,0]
	v_mfma_scale_f32_16x16x128_f8f6f4 v[54:57], v[2:9], v[222:229], v[54:57], v186, v186 op_sel_hi:[0,0,0]
	v_mfma_scale_f32_16x16x128_f8f6f4 v[46:49], v[2:9], v[230:237], v[46:49], v186, v186 op_sel_hi:[0,0,0]
	v_mfma_scale_f32_16x16x128_f8f6f4 v[42:45], v[174:181], v[230:237], v[42:45], v186, v186 op_sel_hi:[0,0,0]
	v_mfma_scale_f32_16x16x128_f8f6f4 v[50:53], v[174:181], v[222:229], v[50:53], v186, v186 op_sel_hi:[0,0,0]
	v_mfma_scale_f32_16x16x128_f8f6f4 v[58:61], v[174:181], v[214:221], v[58:61], v186, v186 op_sel_hi:[0,0,0]
	v_mfma_scale_f32_16x16x128_f8f6f4 v[66:69], v[174:181], v[206:213], v[66:69], v186, v186 op_sel_hi:[0,0,0]
	s_setprio 0
	s_setprio 1
	v_mfma_scale_f32_16x16x128_f8f6f4 v[34:37], v[198:205], v[206:213], v[34:37], v186, v186 op_sel_hi:[0,0,0]
	v_mfma_scale_f32_16x16x128_f8f6f4 v[26:29], v[198:205], v[214:221], v[26:29], v186, v186 op_sel_hi:[0,0,0]
	v_mfma_scale_f32_16x16x128_f8f6f4 v[18:21], v[198:205], v[222:229], v[18:21], v186, v186 op_sel_hi:[0,0,0]
	v_mfma_scale_f32_16x16x128_f8f6f4 v[10:13], v[198:205], v[230:237], v[10:13], v186, v186 op_sel_hi:[0,0,0]
	v_mfma_scale_f32_16x16x128_f8f6f4 v[14:17], v[190:197], v[230:237], v[14:17], v186, v186 op_sel_hi:[0,0,0]
	v_mfma_scale_f32_16x16x128_f8f6f4 v[22:25], v[190:197], v[222:229], v[22:25], v186, v186 op_sel_hi:[0,0,0]
	v_mfma_scale_f32_16x16x128_f8f6f4 v[30:33], v[190:197], v[214:221], v[30:33], v186, v186 op_sel_hi:[0,0,0]
	v_mfma_scale_f32_16x16x128_f8f6f4 v[38:41], v[190:197], v[206:213], v[38:41], v186, v186 op_sel_hi:[0,0,0]
	s_setprio 0
	s_barrier
	s_cmp_lt_u32 s95, 3
	s_cbranch_scc1 .LBB0_287
	s_add_u32 s54, s79, s9
	s_addc_u32 s55, s80, s8
	s_add_u32 s52, s52, 0x158180
	s_addc_u32 s53, s53, 0
	s_add_u32 s8, s50, 0x200
	v_lshl_add_u64 v[174:175], v[172:173], 2, s[54:55]
	s_addc_u32 s9, s51, 0
	s_mov_b32 s72, 4
	s_cmp_eq_u32 s95, s72
	s_cselect_b64 s[50:51], -1, 0
	s_cmp_lg_u32 s95, s72
	s_cbranch_scc1 .LBB0_285

.LBB0_285:
	ds_read_b128 v[2:5], v187
	ds_read_b128 v[6:9], v187 offset:1024
	ds_read_b128 v[190:193], v187 offset:2048
	ds_read_b128 v[194:197], v187 offset:3072
	ds_read_b128 v[198:201], v187 offset:16384
	ds_read_b128 v[202:205], v187 offset:17408
	ds_read_b128 v[206:209], v187 offset:18432
	ds_read_b128 v[210:213], v187 offset:19456
	s_add_u32 s54, s52, 0xffea8080
	s_addc_u32 s55, s53, -1
	s_and_b64 s[50:51], s[50:51], exec
	s_cselect_b32 s50, s4, s8
	s_cselect_b32 s55, s1, s55
	s_cselect_b32 s54, s0, s54
	s_cselect_b32 s51, s5, s9
	s_mov_b32 m0, s49
	v_lshl_add_u64 v[238:239], s[52:53], 0, v[162:163]
	ds_read_b128 v[176:179], v188
	ds_read_b128 v[180:183], v188 offset:1024
	ds_read_b128 v[214:217], v188 offset:2048
	ds_read_b128 v[218:221], v188 offset:3072
	ds_read_b128 v[222:225], v188 offset:4096
	ds_read_b128 v[226:229], v188 offset:5120
	ds_read_b128 v[230:233], v188 offset:6144
	ds_read_b128 v[234:237], v188 offset:7168
	global_load_lds_dwordx4 v[238:239], off
	v_lshl_add_u64 v[238:239], s[52:53], 0, v[164:165]
	s_mov_b32 m0, s71
	s_nop 0
	global_load_lds_dwordx4 v[238:239], off
	s_waitcnt vmcnt(8)
	s_waitcnt lgkmcnt(0)
	s_barrier
	s_setprio 1
	s_waitcnt lgkmcnt(0)
	v_mfma_scale_f32_16x16x128_f8f6f4 v[134:137], v[2:9], v[176:183], v[134:137], v186, v186 op_sel_hi:[0,0,0]
	v_mfma_scale_f32_16x16x128_f8f6f4 v[126:129], v[2:9], v[214:221], v[126:129], v186, v186 op_sel_hi:[0,0,0]
	v_mfma_scale_f32_16x16x128_f8f6f4 v[118:121], v[2:9], v[222:229], v[118:121], v186, v186 op_sel_hi:[0,0,0]
	v_mfma_scale_f32_16x16x128_f8f6f4 v[110:113], v[2:9], v[230:237], v[110:113], v186, v186 op_sel_hi:[0,0,0]
	v_mfma_scale_f32_16x16x128_f8f6f4 v[106:109], v[190:197], v[230:237], v[106:109], v186, v186 op_sel_hi:[0,0,0]
	v_mfma_scale_f32_16x16x128_f8f6f4 v[114:117], v[190:197], v[222:229], v[114:117], v186, v186 op_sel_hi:[0,0,0]
	v_mfma_scale_f32_16x16x128_f8f6f4 v[122:125], v[190:197], v[214:221], v[122:125], v186, v186 op_sel_hi:[0,0,0]
	v_mfma_scale_f32_16x16x128_f8f6f4 v[130:133], v[190:197], v[176:183], v[130:133], v186, v186 op_sel_hi:[0,0,0]
	s_setprio 0
	s_setprio 1
	v_mfma_scale_f32_16x16x128_f8f6f4 v[98:101], v[206:213], v[176:183], v[98:101], v186, v186 op_sel_hi:[0,0,0]
	v_mfma_scale_f32_16x16x128_f8f6f4 v[90:93], v[206:213], v[214:221], v[90:93], v186, v186 op_sel_hi:[0,0,0]
	v_mfma_scale_f32_16x16x128_f8f6f4 v[82:85], v[206:213], v[222:229], v[82:85], v186, v186 op_sel_hi:[0,0,0]
	v_mfma_scale_f32_16x16x128_f8f6f4 v[74:77], v[206:213], v[230:237], v[74:77], v186, v186 op_sel_hi:[0,0,0]
	v_mfma_scale_f32_16x16x128_f8f6f4 v[78:81], v[198:205], v[230:237], v[78:81], v186, v186 op_sel_hi:[0,0,0]
	v_mfma_scale_f32_16x16x128_f8f6f4 v[86:89], v[198:205], v[222:229], v[86:89], v186, v186 op_sel_hi:[0,0,0]
	v_mfma_scale_f32_16x16x128_f8f6f4 v[94:97], v[198:205], v[214:221], v[94:97], v186, v186 op_sel_hi:[0,0,0]
	v_mfma_scale_f32_16x16x128_f8f6f4 v[102:105], v[198:205], v[176:183], v[102:105], v186, v186 op_sel_hi:[0,0,0]
	s_setprio 0
	s_barrier
	s_mov_b32 m0, s47
	v_lshl_add_u64 v[176:177], s[50:51], 0, v[156:157]
	s_add_u32 s62, s50, 0x158000
	ds_read_b128 v[214:217], v188 offset:16384
	ds_read_b128 v[218:221], v188 offset:17408
	ds_read_b128 v[222:225], v188 offset:18432
	ds_read_b128 v[226:229], v188 offset:19456
	ds_read_b128 v[230:233], v188 offset:20480
	ds_read_b128 v[234:237], v188 offset:21504
	ds_read_b128 v[242:245], v188 offset:22528
	ds_read_b128 v[246:249], v188 offset:23552
	global_load_lds_dwordx4 v[176:177], off
	v_lshl_add_u64 v[178:179], s[50:51], 0, v[160:161]
	s_mov_b32 m0, s68
	s_addc_u32 s63, s51, 0
	global_load_lds_dwordx4 v[178:179], off
	v_lshl_add_u64 v[180:181], s[62:63], 0, v[156:157]
	s_mov_b32 m0, s69
	v_lshl_add_u64 v[182:183], s[54:55], 0, v[158:159]
	global_load_lds_dwordx4 v[180:181], off
	v_lshl_add_u64 v[180:181], s[62:63], 0, v[160:161]
	s_mov_b32 m0, s74
	s_nop 0
	global_load_lds_dwordx4 v[180:181], off
	v_lshl_add_u64 v[180:181], s[54:55], 0, v[154:155]
	s_mov_b32 m0, s33
	s_nop 0
	global_load_lds_dwordx4 v[180:181], off
	s_mov_b32 m0, s75
	s_nop 0
	global_load_lds_dwordx4 v[182:183], off
	s_waitcnt vmcnt(8)
	s_waitcnt lgkmcnt(0)
	s_barrier
	s_setprio 1
	s_waitcnt lgkmcnt(0)
	v_mfma_scale_f32_16x16x128_f8f6f4 v[70:73], v[2:9], v[214:221], v[70:73], v186, v186 op_sel_hi:[0,0,0]
	v_mfma_scale_f32_16x16x128_f8f6f4 v[62:65], v[2:9], v[222:229], v[62:65], v186, v186 op_sel_hi:[0,0,0]
	v_mfma_scale_f32_16x16x128_f8f6f4 v[54:57], v[2:9], v[230:237], v[54:57], v186, v186 op_sel_hi:[0,0,0]
	v_mfma_scale_f32_16x16x128_f8f6f4 v[46:49], v[2:9], v[242:249], v[46:49], v186, v186 op_sel_hi:[0,0,0]
	v_mfma_scale_f32_16x16x128_f8f6f4 v[42:45], v[190:197], v[242:249], v[42:45], v186, v186 op_sel_hi:[0,0,0]
	v_mfma_scale_f32_16x16x128_f8f6f4 v[50:53], v[190:197], v[230:237], v[50:53], v186, v186 op_sel_hi:[0,0,0]
	v_mfma_scale_f32_16x16x128_f8f6f4 v[58:61], v[190:197], v[222:229], v[58:61], v186, v186 op_sel_hi:[0,0,0]
	v_mfma_scale_f32_16x16x128_f8f6f4 v[66:69], v[190:197], v[214:221], v[66:69], v186, v186 op_sel_hi:[0,0,0]
	s_setprio 0
	s_setprio 1
	v_mfma_scale_f32_16x16x128_f8f6f4 v[34:37], v[206:213], v[214:221], v[34:37], v186, v186 op_sel_hi:[0,0,0]
	v_mfma_scale_f32_16x16x128_f8f6f4 v[26:29], v[206:213], v[222:229], v[26:29], v186, v186 op_sel_hi:[0,0,0]
	v_mfma_scale_f32_16x16x128_f8f6f4 v[18:21], v[206:213], v[230:237], v[18:21], v186, v186 op_sel_hi:[0,0,0]
	v_mfma_scale_f32_16x16x128_f8f6f4 v[10:13], v[206:213], v[242:249], v[10:13], v186, v186 op_sel_hi:[0,0,0]
	v_mfma_scale_f32_16x16x128_f8f6f4 v[14:17], v[198:205], v[242:249], v[14:17], v186, v186 op_sel_hi:[0,0,0]
	v_mfma_scale_f32_16x16x128_f8f6f4 v[22:25], v[198:205], v[230:237], v[22:25], v186, v186 op_sel_hi:[0,0,0]
	v_mfma_scale_f32_16x16x128_f8f6f4 v[30:33], v[198:205], v[222:229], v[30:33], v186, v186 op_sel_hi:[0,0,0]
	v_mfma_scale_f32_16x16x128_f8f6f4 v[38:41], v[198:205], v[214:221], v[38:41], v186, v186 op_sel_hi:[0,0,0]
	s_setprio 0
	s_barrier
	ds_read_b128 v[190:193], v187 offset:32768
	ds_read_b128 v[194:197], v187 offset:33792
	ds_read_b128 v[198:201], v187 offset:34816
	ds_read_b128 v[202:205], v187 offset:35840
	ds_read_b128 v[2:5], v187 offset:49152
	ds_read_b128 v[6:9], v187 offset:50176
	ds_read_b128 v[206:209], v187 offset:51200
	ds_read_b128 v[210:213], v187 offset:52224
	s_add_u32 s54, s54, 0x158000
	s_addc_u32 s55, s55, 0
	s_mov_b32 m0, s76
	v_lshl_add_u64 v[238:239], s[54:55], 0, v[154:155]
	ds_read_b128 v[214:217], v188 offset:32768
	ds_read_b128 v[218:221], v188 offset:33792
	ds_read_b128 v[222:225], v188 offset:34816
	ds_read_b128 v[226:229], v188 offset:35840
	ds_read_b128 v[230:233], v188 offset:36864
	ds_read_b128 v[234:237], v188 offset:37888
	ds_read_b128 v[242:245], v188 offset:38912
	ds_read_b128 v[246:249], v188 offset:39936
	global_load_lds_dwordx4 v[238:239], off
	v_lshl_add_u64 v[238:239], s[54:55], 0, v[158:159]
	s_mov_b32 m0, s77
	s_nop 0
	global_load_lds_dwordx4 v[238:239], off
	s_waitcnt vmcnt(8)
	s_waitcnt lgkmcnt(0)
	s_barrier
	s_setprio 1
	s_waitcnt lgkmcnt(0)
	v_mfma_scale_f32_16x16x128_f8f6f4 v[134:137], v[190:197], v[214:221], v[134:137], v186, v186 op_sel_hi:[0,0,0]
	v_mfma_scale_f32_16x16x128_f8f6f4 v[126:129], v[190:197], v[222:229], v[126:129], v186, v186 op_sel_hi:[0,0,0]
	v_mfma_scale_f32_16x16x128_f8f6f4 v[118:121], v[190:197], v[230:237], v[118:121], v186, v186 op_sel_hi:[0,0,0]
	v_mfma_scale_f32_16x16x128_f8f6f4 v[110:113], v[190:197], v[242:249], v[110:113], v186, v186 op_sel_hi:[0,0,0]
	v_mfma_scale_f32_16x16x128_f8f6f4 v[106:109], v[198:205], v[242:249], v[106:109], v186, v186 op_sel_hi:[0,0,0]
	v_mfma_scale_f32_16x16x128_f8f6f4 v[114:117], v[198:205], v[230:237], v[114:117], v186, v186 op_sel_hi:[0,0,0]
	v_mfma_scale_f32_16x16x128_f8f6f4 v[122:125], v[198:205], v[222:229], v[122:125], v186, v186 op_sel_hi:[0,0,0]
	v_mfma_scale_f32_16x16x128_f8f6f4 v[130:133], v[198:205], v[214:221], v[130:133], v186, v186 op_sel_hi:[0,0,0]
	s_setprio 0
	s_setprio 1
	v_mfma_scale_f32_16x16x128_f8f6f4 v[98:101], v[206:213], v[214:221], v[98:101], v186, v186 op_sel_hi:[0,0,0]
	v_mfma_scale_f32_16x16x128_f8f6f4 v[90:93], v[206:213], v[222:229], v[90:93], v186, v186 op_sel_hi:[0,0,0]
	v_mfma_scale_f32_16x16x128_f8f6f4 v[82:85], v[206:213], v[230:237], v[82:85], v186, v186 op_sel_hi:[0,0,0]
	v_mfma_scale_f32_16x16x128_f8f6f4 v[74:77], v[206:213], v[242:249], v[74:77], v186, v186 op_sel_hi:[0,0,0]
	v_mfma_scale_f32_16x16x128_f8f6f4 v[78:81], v[2:9], v[242:249], v[78:81], v186, v186 op_sel_hi:[0,0,0]
	v_mfma_scale_f32_16x16x128_f8f6f4 v[86:89], v[2:9], v[230:237], v[86:89], v186, v186 op_sel_hi:[0,0,0]
	v_mfma_scale_f32_16x16x128_f8f6f4 v[94:97], v[2:9], v[222:229], v[94:97], v186, v186 op_sel_hi:[0,0,0]
	v_mfma_scale_f32_16x16x128_f8f6f4 v[102:105], v[2:9], v[214:221], v[102:105], v186, v186 op_sel_hi:[0,0,0]
	s_setprio 0
	s_barrier
	s_mov_b32 m0, s83
	v_lshl_add_u64 v[176:177], v[176:177], 0, s[26:27]
	s_add_u32 s50, s50, 0x158080
	ds_read_b128 v[214:217], v188 offset:49152
	ds_read_b128 v[218:221], v188 offset:50176
	ds_read_b128 v[222:225], v188 offset:51200
	ds_read_b128 v[226:229], v188 offset:52224
	ds_read_b128 v[230:233], v188 offset:53248
	ds_read_b128 v[234:237], v188 offset:54272
	ds_read_b128 v[242:245], v188 offset:55296
	ds_read_b128 v[246:249], v188 offset:56320
	global_load_lds_dwordx4 v[176:177], off
	v_lshl_add_u64 v[176:177], v[178:179], 0, s[26:27]
	s_mov_b32 m0, s84
	s_addc_u32 s51, s51, 0
	global_load_lds_dwordx4 v[176:177], off
	v_lshl_add_u64 v[176:177], s[50:51], 0, v[156:157]
	s_mov_b32 m0, s87
	s_nop 0
	global_load_lds_dwordx4 v[176:177], off
	v_lshl_add_u64 v[176:177], s[50:51], 0, v[160:161]
	s_mov_b32 m0, s88
	s_nop 0
	global_load_lds_dwordx4 v[176:177], off
	v_lshl_add_u64 v[176:177], v[180:181], 0, s[26:27]
	s_mov_b32 m0, s85
	s_nop 0
	global_load_lds_dwordx4 v[176:177], off
	v_lshl_add_u64 v[176:177], v[182:183], 0, s[26:27]
	s_mov_b32 m0, s86
	s_nop 0
	global_load_lds_dwordx4 v[176:177], off
	s_waitcnt vmcnt(8)
	s_waitcnt lgkmcnt(0)
	s_barrier
	s_setprio 1
	s_waitcnt lgkmcnt(0)
	v_mfma_scale_f32_16x16x128_f8f6f4 v[70:73], v[190:197], v[214:221], v[70:73], v186, v186 op_sel_hi:[0,0,0]
	v_mfma_scale_f32_16x16x128_f8f6f4 v[62:65], v[190:197], v[222:229], v[62:65], v186, v186 op_sel_hi:[0,0,0]
	v_mfma_scale_f32_16x16x128_f8f6f4 v[54:57], v[190:197], v[230:237], v[54:57], v186, v186 op_sel_hi:[0,0,0]
	v_mfma_scale_f32_16x16x128_f8f6f4 v[46:49], v[190:197], v[242:249], v[46:49], v186, v186 op_sel_hi:[0,0,0]
	v_mfma_scale_f32_16x16x128_f8f6f4 v[42:45], v[198:205], v[242:249], v[42:45], v186, v186 op_sel_hi:[0,0,0]
	v_mfma_scale_f32_16x16x128_f8f6f4 v[50:53], v[198:205], v[230:237], v[50:53], v186, v186 op_sel_hi:[0,0,0]
	v_mfma_scale_f32_16x16x128_f8f6f4 v[58:61], v[198:205], v[222:229], v[58:61], v186, v186 op_sel_hi:[0,0,0]
	v_mfma_scale_f32_16x16x128_f8f6f4 v[66:69], v[198:205], v[214:221], v[66:69], v186, v186 op_sel_hi:[0,0,0]
	s_setprio 0
	s_setprio 1
	v_mfma_scale_f32_16x16x128_f8f6f4 v[34:37], v[206:213], v[214:221], v[34:37], v186, v186 op_sel_hi:[0,0,0]
	v_mfma_scale_f32_16x16x128_f8f6f4 v[26:29], v[206:213], v[222:229], v[26:29], v186, v186 op_sel_hi:[0,0,0]
	v_mfma_scale_f32_16x16x128_f8f6f4 v[18:21], v[206:213], v[230:237], v[18:21], v186, v186 op_sel_hi:[0,0,0]
	v_mfma_scale_f32_16x16x128_f8f6f4 v[10:13], v[206:213], v[242:249], v[10:13], v186, v186 op_sel_hi:[0,0,0]
	v_mfma_scale_f32_16x16x128_f8f6f4 v[14:17], v[2:9], v[242:249], v[14:17], v186, v186 op_sel_hi:[0,0,0]
	v_mfma_scale_f32_16x16x128_f8f6f4 v[22:25], v[2:9], v[230:237], v[22:25], v186, v186 op_sel_hi:[0,0,0]
	v_mfma_scale_f32_16x16x128_f8f6f4 v[30:33], v[2:9], v[222:229], v[30:33], v186, v186 op_sel_hi:[0,0,0]
	v_mfma_scale_f32_16x16x128_f8f6f4 v[38:41], v[2:9], v[214:221], v[38:41], v186, v186 op_sel_hi:[0,0,0]
	s_setprio 0
	s_barrier
	s_add_i32 s50, s72, 2
	s_add_u32 s52, s52, 0x100
	s_addc_u32 s53, s53, 0
	s_add_u32 s8, s8, 0x100
	s_addc_u32 s9, s9, 0
	s_cmp_ge_i32 s72, s95
	s_cbranch_scc1 .LBB0_287
	s_mov_b32 s72, s50
	s_cmp_eq_u32 s95, s72
	s_cselect_b64 s[50:51], -1, 0
	s_cmp_lg_u32 s95, s72
	s_cbranch_scc0 .LBB0_284
	s_branch .LBB0_285

.LBB0_437:
	s_ashr_i32 s47, s46, 31
	ds_read_b128 v[18:21], v200
	ds_read_b128 v[22:25], v200 offset:1024
	ds_read_b128 v[26:29], v200 offset:2048
	ds_read_b128 v[30:33], v200 offset:3072
	ds_read_b128 v[2:5], v200 offset:16384
	ds_read_b128 v[6:9], v200 offset:17408
	ds_read_b128 v[10:13], v200 offset:18432
	ds_read_b128 v[14:17], v200 offset:19456
	s_lshl_b64 s[8:9], s[46:47], 20
	s_add_u32 s48, s12, s8
	s_addc_u32 s49, s13, s9
	s_and_b64 s[8:9], s[2:3], exec
	s_cselect_b32 s47, s49, s73
	s_cselect_b32 s71, s48, s72
	s_ashr_i32 s45, s44, 31
	s_lshl_b64 s[8:9], s[44:45], 20
	s_add_u32 s50, s39, s8
	s_addc_u32 s51, s76, s9
	s_and_b64 s[8:9], s[2:3], exec
	s_cselect_b32 s45, s51, s55
	s_cselect_b32 s94, s50, s54
	s_add_u32 s8, s72, 0x80080
	s_addc_u32 s9, s73, 0
	s_mov_b32 m0, s33
	v_lshl_add_u64 v[226:227], s[8:9], 0, v[162:163]
	ds_read_b128 v[180:183], v201
	ds_read_b128 v[184:187], v201 offset:1024
	ds_read_b128 v[202:205], v201 offset:2048
	ds_read_b128 v[206:209], v201 offset:3072
	ds_read_b128 v[210:213], v201 offset:4096
	ds_read_b128 v[214:217], v201 offset:5120
	ds_read_b128 v[218:221], v201 offset:6144
	ds_read_b128 v[222:225], v201 offset:7168
	global_load_lds_dwordx4 v[226:227], off
	v_lshl_add_u64 v[226:227], s[8:9], 0, v[166:167]
	s_mov_b32 m0, s93
	s_nop 0
	global_load_lds_dwordx4 v[226:227], off
	s_waitcnt vmcnt(8)
	s_waitcnt lgkmcnt(0)
	s_barrier
	s_setprio 1
	s_waitcnt lgkmcnt(0)
	v_mfma_scale_f32_16x16x128_f8f6f4 v[158:161], v[18:25], v[180:187], 0, v199, v199 op_sel_hi:[0,0,0]
	v_mfma_scale_f32_16x16x128_f8f6f4 v[150:153], v[18:25], v[202:209], 0, v199, v199 op_sel_hi:[0,0,0]
	v_mfma_scale_f32_16x16x128_f8f6f4 v[142:145], v[18:25], v[210:217], 0, v199, v199 op_sel_hi:[0,0,0]
	v_mfma_scale_f32_16x16x128_f8f6f4 v[134:137], v[18:25], v[218:225], 0, v199, v199 op_sel_hi:[0,0,0]
	v_mfma_scale_f32_16x16x128_f8f6f4 v[130:133], v[26:33], v[218:225], 0, v199, v199 op_sel_hi:[0,0,0]
	v_mfma_scale_f32_16x16x128_f8f6f4 v[138:141], v[26:33], v[210:217], 0, v199, v199 op_sel_hi:[0,0,0]
	v_mfma_scale_f32_16x16x128_f8f6f4 v[146:149], v[26:33], v[202:209], 0, v199, v199 op_sel_hi:[0,0,0]
	v_mfma_scale_f32_16x16x128_f8f6f4 v[154:157], v[26:33], v[180:187], 0, v199, v199 op_sel_hi:[0,0,0]
	s_setprio 0
	s_setprio 1
	v_mfma_scale_f32_16x16x128_f8f6f4 v[122:125], v[10:17], v[180:187], 0, v199, v199 op_sel_hi:[0,0,0]
	v_mfma_scale_f32_16x16x128_f8f6f4 v[114:117], v[10:17], v[202:209], 0, v199, v199 op_sel_hi:[0,0,0]
	v_mfma_scale_f32_16x16x128_f8f6f4 v[106:109], v[10:17], v[210:217], 0, v199, v199 op_sel_hi:[0,0,0]
	v_mfma_scale_f32_16x16x128_f8f6f4 v[98:101], v[10:17], v[218:225], 0, v199, v199 op_sel_hi:[0,0,0]
	v_mfma_scale_f32_16x16x128_f8f6f4 v[102:105], v[2:9], v[218:225], 0, v199, v199 op_sel_hi:[0,0,0]
	v_mfma_scale_f32_16x16x128_f8f6f4 v[110:113], v[2:9], v[210:217], 0, v199, v199 op_sel_hi:[0,0,0]
	v_mfma_scale_f32_16x16x128_f8f6f4 v[118:121], v[2:9], v[202:209], 0, v199, v199 op_sel_hi:[0,0,0]
	v_mfma_scale_f32_16x16x128_f8f6f4 v[126:129], v[2:9], v[180:187], 0, v199, v199 op_sel_hi:[0,0,0]
	s_setprio 0
	s_barrier
	v_lshl_add_u64 v[180:181], s[54:55], 0, v[164:165]
	s_mov_b32 m0, s78
	v_lshl_add_u64 v[182:183], v[180:181], 0, s[26:27]
	ds_read_b128 v[202:205], v201 offset:16384
	ds_read_b128 v[206:209], v201 offset:17408
	ds_read_b128 v[210:213], v201 offset:18432
	ds_read_b128 v[214:217], v201 offset:19456
	ds_read_b128 v[218:221], v201 offset:20480
	ds_read_b128 v[222:225], v201 offset:21504
	ds_read_b128 v[226:229], v201 offset:22528
	ds_read_b128 v[230:233], v201 offset:23552
	global_load_lds_dwordx4 v[182:183], off
	v_lshl_add_u64 v[182:183], s[54:55], 0, v[168:169]
	s_add_u32 s8, s54, 0x80100
	v_lshl_add_u64 v[184:185], v[182:183], 0, s[26:27]
	s_mov_b32 m0, s79
	s_addc_u32 s9, s55, 0
	global_load_lds_dwordx4 v[184:185], off
	v_lshl_add_u64 v[184:185], s[8:9], 0, v[164:165]
	s_mov_b32 m0, s80
	s_nop 0
	global_load_lds_dwordx4 v[184:185], off
	v_lshl_add_u64 v[184:185], s[8:9], 0, v[168:169]
	s_mov_b32 m0, s81
	s_nop 0
	global_load_lds_dwordx4 v[184:185], off
	v_lshl_add_u64 v[184:185], s[72:73], 0, v[162:163]
	v_lshl_add_u64 v[186:187], v[184:185], 0, s[26:27]
	s_mov_b32 m0, s53
	s_nop 0
	global_load_lds_dwordx4 v[186:187], off
	v_lshl_add_u64 v[186:187], s[72:73], 0, v[166:167]
	v_lshl_add_u64 v[234:235], v[186:187], 0, s[26:27]
	s_mov_b32 m0, s82
	s_nop 0
	global_load_lds_dwordx4 v[234:235], off
	s_waitcnt vmcnt(8)
	s_waitcnt lgkmcnt(0)
	s_barrier
	s_setprio 1
	s_waitcnt lgkmcnt(0)
	v_mfma_scale_f32_16x16x128_f8f6f4 v[94:97], v[18:25], v[202:209], 0, v199, v199 op_sel_hi:[0,0,0]
	v_mfma_scale_f32_16x16x128_f8f6f4 v[86:89], v[18:25], v[210:217], 0, v199, v199 op_sel_hi:[0,0,0]
	v_mfma_scale_f32_16x16x128_f8f6f4 v[78:81], v[18:25], v[218:225], 0, v199, v199 op_sel_hi:[0,0,0]
	v_mfma_scale_f32_16x16x128_f8f6f4 v[70:73], v[18:25], v[226:233], 0, v199, v199 op_sel_hi:[0,0,0]
	v_mfma_scale_f32_16x16x128_f8f6f4 v[66:69], v[26:33], v[226:233], 0, v199, v199 op_sel_hi:[0,0,0]
	v_mfma_scale_f32_16x16x128_f8f6f4 v[74:77], v[26:33], v[218:225], 0, v199, v199 op_sel_hi:[0,0,0]
	v_mfma_scale_f32_16x16x128_f8f6f4 v[82:85], v[26:33], v[210:217], 0, v199, v199 op_sel_hi:[0,0,0]
	v_mfma_scale_f32_16x16x128_f8f6f4 v[90:93], v[26:33], v[202:209], 0, v199, v199 op_sel_hi:[0,0,0]
	s_setprio 0
	s_setprio 1
	v_mfma_scale_f32_16x16x128_f8f6f4 v[58:61], v[10:17], v[202:209], 0, v199, v199 op_sel_hi:[0,0,0]
	v_mfma_scale_f32_16x16x128_f8f6f4 v[50:53], v[10:17], v[210:217], 0, v199, v199 op_sel_hi:[0,0,0]
	v_mfma_scale_f32_16x16x128_f8f6f4 v[42:45], v[10:17], v[218:225], 0, v199, v199 op_sel_hi:[0,0,0]
	v_mfma_scale_f32_16x16x128_f8f6f4 v[34:37], v[10:17], v[226:233], 0, v199, v199 op_sel_hi:[0,0,0]
	v_mfma_scale_f32_16x16x128_f8f6f4 v[38:41], v[2:9], v[226:233], 0, v199, v199 op_sel_hi:[0,0,0]
	v_mfma_scale_f32_16x16x128_f8f6f4 v[46:49], v[2:9], v[218:225], 0, v199, v199 op_sel_hi:[0,0,0]
	v_mfma_scale_f32_16x16x128_f8f6f4 v[54:57], v[2:9], v[210:217], 0, v199, v199 op_sel_hi:[0,0,0]
	v_mfma_scale_f32_16x16x128_f8f6f4 v[62:65], v[2:9], v[202:209], 0, v199, v199 op_sel_hi:[0,0,0]
	s_setprio 0
	s_barrier
	ds_read_b128 v[18:21], v200 offset:32768
	ds_read_b128 v[22:25], v200 offset:33792
	ds_read_b128 v[26:29], v200 offset:34816
	ds_read_b128 v[30:33], v200 offset:35840
	ds_read_b128 v[2:5], v200 offset:49152
	ds_read_b128 v[6:9], v200 offset:50176
	ds_read_b128 v[10:13], v200 offset:51200
	ds_read_b128 v[14:17], v200 offset:52224
	s_add_u32 s8, s72, 0x80100
	s_addc_u32 s9, s73, 0
	s_mov_b32 m0, s83
	v_lshl_add_u64 v[234:235], s[8:9], 0, v[162:163]
	ds_read_b128 v[202:205], v201 offset:32768
	ds_read_b128 v[206:209], v201 offset:33792
	ds_read_b128 v[210:213], v201 offset:34816
	ds_read_b128 v[214:217], v201 offset:35840
	ds_read_b128 v[218:221], v201 offset:36864
	ds_read_b128 v[222:225], v201 offset:37888
	ds_read_b128 v[226:229], v201 offset:38912
	ds_read_b128 v[230:233], v201 offset:39936
	global_load_lds_dwordx4 v[234:235], off
	v_lshl_add_u64 v[234:235], s[8:9], 0, v[166:167]
	s_mov_b32 m0, s84
	s_nop 0
	global_load_lds_dwordx4 v[234:235], off
	s_waitcnt vmcnt(8)
	s_waitcnt lgkmcnt(0)
	s_barrier
	s_setprio 1
	s_waitcnt lgkmcnt(0)
	v_mfma_scale_f32_16x16x128_f8f6f4 v[158:161], v[18:25], v[202:209], v[158:161], v199, v199 op_sel_hi:[0,0,0]
	v_mfma_scale_f32_16x16x128_f8f6f4 v[150:153], v[18:25], v[210:217], v[150:153], v199, v199 op_sel_hi:[0,0,0]
	v_mfma_scale_f32_16x16x128_f8f6f4 v[142:145], v[18:25], v[218:225], v[142:145], v199, v199 op_sel_hi:[0,0,0]
	v_mfma_scale_f32_16x16x128_f8f6f4 v[134:137], v[18:25], v[226:233], v[134:137], v199, v199 op_sel_hi:[0,0,0]
	v_mfma_scale_f32_16x16x128_f8f6f4 v[130:133], v[26:33], v[226:233], v[130:133], v199, v199 op_sel_hi:[0,0,0]
	v_mfma_scale_f32_16x16x128_f8f6f4 v[138:141], v[26:33], v[218:225], v[138:141], v199, v199 op_sel_hi:[0,0,0]
	v_mfma_scale_f32_16x16x128_f8f6f4 v[146:149], v[26:33], v[210:217], v[146:149], v199, v199 op_sel_hi:[0,0,0]
	v_mfma_scale_f32_16x16x128_f8f6f4 v[154:157], v[26:33], v[202:209], v[154:157], v199, v199 op_sel_hi:[0,0,0]
	s_setprio 0
	s_setprio 1
	v_mfma_scale_f32_16x16x128_f8f6f4 v[122:125], v[10:17], v[202:209], v[122:125], v199, v199 op_sel_hi:[0,0,0]
	v_mfma_scale_f32_16x16x128_f8f6f4 v[114:117], v[10:17], v[210:217], v[114:117], v199, v199 op_sel_hi:[0,0,0]
	v_mfma_scale_f32_16x16x128_f8f6f4 v[106:109], v[10:17], v[218:225], v[106:109], v199, v199 op_sel_hi:[0,0,0]
	v_mfma_scale_f32_16x16x128_f8f6f4 v[98:101], v[10:17], v[226:233], v[98:101], v199, v199 op_sel_hi:[0,0,0]
	v_mfma_scale_f32_16x16x128_f8f6f4 v[102:105], v[2:9], v[226:233], v[102:105], v199, v199 op_sel_hi:[0,0,0]
	v_mfma_scale_f32_16x16x128_f8f6f4 v[110:113], v[2:9], v[218:225], v[110:113], v199, v199 op_sel_hi:[0,0,0]
	v_mfma_scale_f32_16x16x128_f8f6f4 v[118:121], v[2:9], v[210:217], v[118:121], v199, v199 op_sel_hi:[0,0,0]
	v_mfma_scale_f32_16x16x128_f8f6f4 v[126:129], v[2:9], v[202:209], v[126:129], v199, v199 op_sel_hi:[0,0,0]
	s_setprio 0
	s_barrier
	s_mov_b32 m0, s87
	v_lshl_add_u64 v[180:181], v[180:181], 0, s[36:37]
	s_add_u32 s8, s54, 0x80180
	ds_read_b128 v[202:205], v201 offset:49152
	ds_read_b128 v[206:209], v201 offset:50176
	ds_read_b128 v[210:213], v201 offset:51200
	ds_read_b128 v[214:217], v201 offset:52224
	ds_read_b128 v[218:221], v201 offset:53248
	ds_read_b128 v[222:225], v201 offset:54272
	ds_read_b128 v[226:229], v201 offset:55296
	ds_read_b128 v[230:233], v201 offset:56320
	global_load_lds_dwordx4 v[180:181], off
	v_lshl_add_u64 v[180:181], v[182:183], 0, s[36:37]
	s_mov_b32 m0, s88
	s_addc_u32 s9, s55, 0
	global_load_lds_dwordx4 v[180:181], off
	v_lshl_add_u64 v[180:181], s[8:9], 0, v[164:165]
	s_mov_b32 m0, s91
	s_nop 0
	global_load_lds_dwordx4 v[180:181], off
	v_lshl_add_u64 v[180:181], s[8:9], 0, v[168:169]
	s_mov_b32 m0, s92
	s_nop 0
	global_load_lds_dwordx4 v[180:181], off
	v_lshl_add_u64 v[180:181], v[184:185], 0, s[36:37]
	s_mov_b32 m0, s89
	s_nop 0
	global_load_lds_dwordx4 v[180:181], off
	v_lshl_add_u64 v[180:181], v[186:187], 0, s[36:37]
	s_mov_b32 m0, s90
	s_nop 0
	global_load_lds_dwordx4 v[180:181], off
	s_waitcnt vmcnt(8)
	s_waitcnt lgkmcnt(0)
	s_barrier
	s_setprio 1
	s_waitcnt lgkmcnt(0)
	v_mfma_scale_f32_16x16x128_f8f6f4 v[94:97], v[18:25], v[202:209], v[94:97], v199, v199 op_sel_hi:[0,0,0]
	v_mfma_scale_f32_16x16x128_f8f6f4 v[86:89], v[18:25], v[210:217], v[86:89], v199, v199 op_sel_hi:[0,0,0]
	v_mfma_scale_f32_16x16x128_f8f6f4 v[78:81], v[18:25], v[218:225], v[78:81], v199, v199 op_sel_hi:[0,0,0]
	v_mfma_scale_f32_16x16x128_f8f6f4 v[70:73], v[18:25], v[226:233], v[70:73], v199, v199 op_sel_hi:[0,0,0]
	v_mfma_scale_f32_16x16x128_f8f6f4 v[66:69], v[26:33], v[226:233], v[66:69], v199, v199 op_sel_hi:[0,0,0]
	v_mfma_scale_f32_16x16x128_f8f6f4 v[74:77], v[26:33], v[218:225], v[74:77], v199, v199 op_sel_hi:[0,0,0]
	v_mfma_scale_f32_16x16x128_f8f6f4 v[82:85], v[26:33], v[210:217], v[82:85], v199, v199 op_sel_hi:[0,0,0]
	v_mfma_scale_f32_16x16x128_f8f6f4 v[90:93], v[26:33], v[202:209], v[90:93], v199, v199 op_sel_hi:[0,0,0]
	s_setprio 0
	s_setprio 1
	v_mfma_scale_f32_16x16x128_f8f6f4 v[58:61], v[10:17], v[202:209], v[58:61], v199, v199 op_sel_hi:[0,0,0]
	v_mfma_scale_f32_16x16x128_f8f6f4 v[50:53], v[10:17], v[210:217], v[50:53], v199, v199 op_sel_hi:[0,0,0]
	v_mfma_scale_f32_16x16x128_f8f6f4 v[42:45], v[10:17], v[218:225], v[42:45], v199, v199 op_sel_hi:[0,0,0]
	v_mfma_scale_f32_16x16x128_f8f6f4 v[34:37], v[10:17], v[226:233], v[34:37], v199, v199 op_sel_hi:[0,0,0]
	v_mfma_scale_f32_16x16x128_f8f6f4 v[38:41], v[2:9], v[226:233], v[38:41], v199, v199 op_sel_hi:[0,0,0]
	v_mfma_scale_f32_16x16x128_f8f6f4 v[46:49], v[2:9], v[218:225], v[46:49], v199, v199 op_sel_hi:[0,0,0]
	v_mfma_scale_f32_16x16x128_f8f6f4 v[54:57], v[2:9], v[210:217], v[54:57], v199, v199 op_sel_hi:[0,0,0]
	v_mfma_scale_f32_16x16x128_f8f6f4 v[62:65], v[2:9], v[202:209], v[62:65], v199, v199 op_sel_hi:[0,0,0]
	s_setprio 0
	s_barrier
	s_add_u32 s72, s72, 0x80180
	s_addc_u32 s73, s73, 0
	s_add_u32 s8, s54, 0x200
	s_addc_u32 s9, s55, 0
	s_mov_b32 s62, 0
.LBB0_438:
	ds_read_b128 v[2:5], v200
	ds_read_b128 v[6:9], v200 offset:1024
	ds_read_b128 v[18:21], v200 offset:2048
	ds_read_b128 v[22:25], v200 offset:3072
	ds_read_b128 v[26:29], v200 offset:16384
	ds_read_b128 v[30:33], v200 offset:17408
	ds_read_b128 v[180:183], v200 offset:18432
	ds_read_b128 v[184:187], v200 offset:19456
	s_add_u32 s54, s72, 0xfff80080
	s_addc_u32 s55, s73, -1
	s_cmp_eq_u32 s62, 28
	s_cselect_b32 s75, s47, s55
	s_cselect_b32 s74, s71, s54
	s_cselect_b32 s55, s45, s9
	s_cselect_b32 s54, s94, s8
	s_mov_b32 m0, s33
	v_lshl_add_u64 v[226:227], s[72:73], 0, v[170:171]
	ds_read_b128 v[10:13], v201
	ds_read_b128 v[14:17], v201 offset:1024
	ds_read_b128 v[202:205], v201 offset:2048
	ds_read_b128 v[206:209], v201 offset:3072
	ds_read_b128 v[210:213], v201 offset:4096
	ds_read_b128 v[214:217], v201 offset:5120
	ds_read_b128 v[218:221], v201 offset:6144
	ds_read_b128 v[222:225], v201 offset:7168
	global_load_lds_dwordx4 v[226:227], off
	v_lshl_add_u64 v[226:227], s[72:73], 0, v[172:173]
	s_mov_b32 m0, s93
	s_nop 0
	global_load_lds_dwordx4 v[226:227], off
	s_waitcnt vmcnt(8)
	s_waitcnt lgkmcnt(0)
	s_barrier
	s_setprio 1
	s_waitcnt lgkmcnt(0)
	v_mfma_scale_f32_16x16x128_f8f6f4 v[158:161], v[2:9], v[10:17], v[158:161], v199, v199 op_sel_hi:[0,0,0]
	v_mfma_scale_f32_16x16x128_f8f6f4 v[150:153], v[2:9], v[202:209], v[150:153], v199, v199 op_sel_hi:[0,0,0]
	v_mfma_scale_f32_16x16x128_f8f6f4 v[142:145], v[2:9], v[210:217], v[142:145], v199, v199 op_sel_hi:[0,0,0]
	v_mfma_scale_f32_16x16x128_f8f6f4 v[134:137], v[2:9], v[218:225], v[134:137], v199, v199 op_sel_hi:[0,0,0]
	v_mfma_scale_f32_16x16x128_f8f6f4 v[130:133], v[18:25], v[218:225], v[130:133], v199, v199 op_sel_hi:[0,0,0]
	v_mfma_scale_f32_16x16x128_f8f6f4 v[138:141], v[18:25], v[210:217], v[138:141], v199, v199 op_sel_hi:[0,0,0]
	v_mfma_scale_f32_16x16x128_f8f6f4 v[146:149], v[18:25], v[202:209], v[146:149], v199, v199 op_sel_hi:[0,0,0]
	v_mfma_scale_f32_16x16x128_f8f6f4 v[154:157], v[18:25], v[10:17], v[154:157], v199, v199 op_sel_hi:[0,0,0]
	s_setprio 0
	s_setprio 1
	v_mfma_scale_f32_16x16x128_f8f6f4 v[122:125], v[180:187], v[10:17], v[122:125], v199, v199 op_sel_hi:[0,0,0]
	v_mfma_scale_f32_16x16x128_f8f6f4 v[114:117], v[180:187], v[202:209], v[114:117], v199, v199 op_sel_hi:[0,0,0]
	v_mfma_scale_f32_16x16x128_f8f6f4 v[106:109], v[180:187], v[210:217], v[106:109], v199, v199 op_sel_hi:[0,0,0]
	v_mfma_scale_f32_16x16x128_f8f6f4 v[98:101], v[180:187], v[218:225], v[98:101], v199, v199 op_sel_hi:[0,0,0]
	v_mfma_scale_f32_16x16x128_f8f6f4 v[102:105], v[26:33], v[218:225], v[102:105], v199, v199 op_sel_hi:[0,0,0]
	v_mfma_scale_f32_16x16x128_f8f6f4 v[110:113], v[26:33], v[210:217], v[110:113], v199, v199 op_sel_hi:[0,0,0]
	v_mfma_scale_f32_16x16x128_f8f6f4 v[118:121], v[26:33], v[202:209], v[118:121], v199, v199 op_sel_hi:[0,0,0]
	v_mfma_scale_f32_16x16x128_f8f6f4 v[126:129], v[26:33], v[10:17], v[126:129], v199, v199 op_sel_hi:[0,0,0]
	s_setprio 0
	s_barrier
	s_mov_b32 m0, s78
	v_lshl_add_u64 v[10:11], s[54:55], 0, v[164:165]
	s_add_u32 s96, s54, 0x80000
	ds_read_b128 v[202:205], v201 offset:16384
	ds_read_b128 v[206:209], v201 offset:17408
	ds_read_b128 v[210:213], v201 offset:18432
	ds_read_b128 v[214:217], v201 offset:19456
	ds_read_b128 v[218:221], v201 offset:20480
	ds_read_b128 v[222:225], v201 offset:21504
	ds_read_b128 v[226:229], v201 offset:22528
	ds_read_b128 v[230:233], v201 offset:23552
	global_load_lds_dwordx4 v[10:11], off
	v_lshl_add_u64 v[12:13], s[54:55], 0, v[168:169]
	s_mov_b32 m0, s79
	s_addc_u32 s97, s55, 0
	global_load_lds_dwordx4 v[12:13], off
	v_lshl_add_u64 v[14:15], s[96:97], 0, v[164:165]
	s_mov_b32 m0, s80
	v_lshl_add_u64 v[16:17], s[74:75], 0, v[166:167]
	global_load_lds_dwordx4 v[14:15], off
	v_lshl_add_u64 v[14:15], s[96:97], 0, v[168:169]
	s_mov_b32 m0, s81
	s_nop 0
	global_load_lds_dwordx4 v[14:15], off
	v_lshl_add_u64 v[14:15], s[74:75], 0, v[162:163]
	s_mov_b32 m0, s53
	s_nop 0
	global_load_lds_dwordx4 v[14:15], off
	s_mov_b32 m0, s82
	s_nop 0
	global_load_lds_dwordx4 v[16:17], off
	s_waitcnt vmcnt(8)
	s_waitcnt lgkmcnt(0)
	s_barrier
	s_setprio 1
	s_waitcnt lgkmcnt(0)
	v_mfma_scale_f32_16x16x128_f8f6f4 v[94:97], v[2:9], v[202:209], v[94:97], v199, v199 op_sel_hi:[0,0,0]
	v_mfma_scale_f32_16x16x128_f8f6f4 v[86:89], v[2:9], v[210:217], v[86:89], v199, v199 op_sel_hi:[0,0,0]
	v_mfma_scale_f32_16x16x128_f8f6f4 v[78:81], v[2:9], v[218:225], v[78:81], v199, v199 op_sel_hi:[0,0,0]
	v_mfma_scale_f32_16x16x128_f8f6f4 v[70:73], v[2:9], v[226:233], v[70:73], v199, v199 op_sel_hi:[0,0,0]
	v_mfma_scale_f32_16x16x128_f8f6f4 v[66:69], v[18:25], v[226:233], v[66:69], v199, v199 op_sel_hi:[0,0,0]
	v_mfma_scale_f32_16x16x128_f8f6f4 v[74:77], v[18:25], v[218:225], v[74:77], v199, v199 op_sel_hi:[0,0,0]
	v_mfma_scale_f32_16x16x128_f8f6f4 v[82:85], v[18:25], v[210:217], v[82:85], v199, v199 op_sel_hi:[0,0,0]
	v_mfma_scale_f32_16x16x128_f8f6f4 v[90:93], v[18:25], v[202:209], v[90:93], v199, v199 op_sel_hi:[0,0,0]
	s_setprio 0
	s_setprio 1
	v_mfma_scale_f32_16x16x128_f8f6f4 v[58:61], v[180:187], v[202:209], v[58:61], v199, v199 op_sel_hi:[0,0,0]
	v_mfma_scale_f32_16x16x128_f8f6f4 v[50:53], v[180:187], v[210:217], v[50:53], v199, v199 op_sel_hi:[0,0,0]
	v_mfma_scale_f32_16x16x128_f8f6f4 v[42:45], v[180:187], v[218:225], v[42:45], v199, v199 op_sel_hi:[0,0,0]
	v_mfma_scale_f32_16x16x128_f8f6f4 v[34:37], v[180:187], v[226:233], v[34:37], v199, v199 op_sel_hi:[0,0,0]
	v_mfma_scale_f32_16x16x128_f8f6f4 v[38:41], v[26:33], v[226:233], v[38:41], v199, v199 op_sel_hi:[0,0,0]
	v_mfma_scale_f32_16x16x128_f8f6f4 v[46:49], v[26:33], v[218:225], v[46:49], v199, v199 op_sel_hi:[0,0,0]
	v_mfma_scale_f32_16x16x128_f8f6f4 v[54:57], v[26:33], v[210:217], v[54:57], v199, v199 op_sel_hi:[0,0,0]
	v_mfma_scale_f32_16x16x128_f8f6f4 v[62:65], v[26:33], v[202:209], v[62:65], v199, v199 op_sel_hi:[0,0,0]
	s_setprio 0
	s_barrier
	ds_read_b128 v[18:21], v200 offset:32768
	ds_read_b128 v[22:25], v200 offset:33792
	ds_read_b128 v[26:29], v200 offset:34816
	ds_read_b128 v[30:33], v200 offset:35840
	ds_read_b128 v[2:5], v200 offset:49152
	ds_read_b128 v[6:9], v200 offset:50176
	ds_read_b128 v[180:183], v200 offset:51200
	ds_read_b128 v[184:187], v200 offset:52224
	s_add_u32 s74, s74, 0x80000
	s_addc_u32 s75, s75, 0
	s_mov_b32 m0, s83
	v_lshl_add_u64 v[234:235], s[74:75], 0, v[162:163]
	ds_read_b128 v[202:205], v201 offset:32768
	ds_read_b128 v[206:209], v201 offset:33792
	ds_read_b128 v[210:213], v201 offset:34816
	ds_read_b128 v[214:217], v201 offset:35840
	ds_read_b128 v[218:221], v201 offset:36864
	ds_read_b128 v[222:225], v201 offset:37888
	ds_read_b128 v[226:229], v201 offset:38912
	ds_read_b128 v[230:233], v201 offset:39936
	global_load_lds_dwordx4 v[234:235], off
	v_lshl_add_u64 v[234:235], s[74:75], 0, v[166:167]
	s_mov_b32 m0, s84
	s_nop 0
	global_load_lds_dwordx4 v[234:235], off
	s_waitcnt vmcnt(8)
	s_waitcnt lgkmcnt(0)
	s_barrier
	s_setprio 1
	s_waitcnt lgkmcnt(0)
	v_mfma_scale_f32_16x16x128_f8f6f4 v[158:161], v[18:25], v[202:209], v[158:161], v199, v199 op_sel_hi:[0,0,0]
	v_mfma_scale_f32_16x16x128_f8f6f4 v[150:153], v[18:25], v[210:217], v[150:153], v199, v199 op_sel_hi:[0,0,0]
	v_mfma_scale_f32_16x16x128_f8f6f4 v[142:145], v[18:25], v[218:225], v[142:145], v199, v199 op_sel_hi:[0,0,0]
	v_mfma_scale_f32_16x16x128_f8f6f4 v[134:137], v[18:25], v[226:233], v[134:137], v199, v199 op_sel_hi:[0,0,0]
	v_mfma_scale_f32_16x16x128_f8f6f4 v[130:133], v[26:33], v[226:233], v[130:133], v199, v199 op_sel_hi:[0,0,0]
	v_mfma_scale_f32_16x16x128_f8f6f4 v[138:141], v[26:33], v[218:225], v[138:141], v199, v199 op_sel_hi:[0,0,0]
	v_mfma_scale_f32_16x16x128_f8f6f4 v[146:149], v[26:33], v[210:217], v[146:149], v199, v199 op_sel_hi:[0,0,0]
	v_mfma_scale_f32_16x16x128_f8f6f4 v[154:157], v[26:33], v[202:209], v[154:157], v199, v199 op_sel_hi:[0,0,0]
	s_setprio 0
	s_setprio 1
	v_mfma_scale_f32_16x16x128_f8f6f4 v[122:125], v[180:187], v[202:209], v[122:125], v199, v199 op_sel_hi:[0,0,0]
	v_mfma_scale_f32_16x16x128_f8f6f4 v[114:117], v[180:187], v[210:217], v[114:117], v199, v199 op_sel_hi:[0,0,0]
	v_mfma_scale_f32_16x16x128_f8f6f4 v[106:109], v[180:187], v[218:225], v[106:109], v199, v199 op_sel_hi:[0,0,0]
	v_mfma_scale_f32_16x16x128_f8f6f4 v[98:101], v[180:187], v[226:233], v[98:101], v199, v199 op_sel_hi:[0,0,0]
	v_mfma_scale_f32_16x16x128_f8f6f4 v[102:105], v[2:9], v[226:233], v[102:105], v199, v199 op_sel_hi:[0,0,0]
	v_mfma_scale_f32_16x16x128_f8f6f4 v[110:113], v[2:9], v[218:225], v[110:113], v199, v199 op_sel_hi:[0,0,0]
	v_mfma_scale_f32_16x16x128_f8f6f4 v[118:121], v[2:9], v[210:217], v[118:121], v199, v199 op_sel_hi:[0,0,0]
	v_mfma_scale_f32_16x16x128_f8f6f4 v[126:129], v[2:9], v[202:209], v[126:129], v199, v199 op_sel_hi:[0,0,0]
	s_setprio 0
	s_barrier
	s_mov_b32 m0, s87
	v_lshl_add_u64 v[10:11], v[10:11], 0, s[4:5]
	s_add_u32 s54, s54, 0x80080
	ds_read_b128 v[202:205], v201 offset:49152
	ds_read_b128 v[206:209], v201 offset:50176
	ds_read_b128 v[210:213], v201 offset:51200
	ds_read_b128 v[214:217], v201 offset:52224
	ds_read_b128 v[218:221], v201 offset:53248
	ds_read_b128 v[222:225], v201 offset:54272
	ds_read_b128 v[226:229], v201 offset:55296
	ds_read_b128 v[230:233], v201 offset:56320
	global_load_lds_dwordx4 v[10:11], off
	v_lshl_add_u64 v[10:11], v[12:13], 0, s[4:5]
	s_mov_b32 m0, s88
	s_addc_u32 s55, s55, 0
	global_load_lds_dwordx4 v[10:11], off
	v_lshl_add_u64 v[10:11], s[54:55], 0, v[164:165]
	s_mov_b32 m0, s91
	s_nop 0
	global_load_lds_dwordx4 v[10:11], off
	v_lshl_add_u64 v[10:11], s[54:55], 0, v[168:169]
	s_mov_b32 m0, s92
	s_nop 0
	global_load_lds_dwordx4 v[10:11], off
	v_lshl_add_u64 v[10:11], v[14:15], 0, s[4:5]
	s_mov_b32 m0, s89
	s_nop 0
	global_load_lds_dwordx4 v[10:11], off
	v_lshl_add_u64 v[10:11], v[16:17], 0, s[4:5]
	s_mov_b32 m0, s90
	s_nop 0
	global_load_lds_dwordx4 v[10:11], off
	s_waitcnt vmcnt(8)
	s_waitcnt lgkmcnt(0)
	s_barrier
	s_setprio 1
	s_waitcnt lgkmcnt(0)
	v_mfma_scale_f32_16x16x128_f8f6f4 v[94:97], v[18:25], v[202:209], v[94:97], v199, v199 op_sel_hi:[0,0,0]
	v_mfma_scale_f32_16x16x128_f8f6f4 v[86:89], v[18:25], v[210:217], v[86:89], v199, v199 op_sel_hi:[0,0,0]
	v_mfma_scale_f32_16x16x128_f8f6f4 v[78:81], v[18:25], v[218:225], v[78:81], v199, v199 op_sel_hi:[0,0,0]
	v_mfma_scale_f32_16x16x128_f8f6f4 v[70:73], v[18:25], v[226:233], v[70:73], v199, v199 op_sel_hi:[0,0,0]
	v_mfma_scale_f32_16x16x128_f8f6f4 v[66:69], v[26:33], v[226:233], v[66:69], v199, v199 op_sel_hi:[0,0,0]
	v_mfma_scale_f32_16x16x128_f8f6f4 v[74:77], v[26:33], v[218:225], v[74:77], v199, v199 op_sel_hi:[0,0,0]
	v_mfma_scale_f32_16x16x128_f8f6f4 v[82:85], v[26:33], v[210:217], v[82:85], v199, v199 op_sel_hi:[0,0,0]
	v_mfma_scale_f32_16x16x128_f8f6f4 v[90:93], v[26:33], v[202:209], v[90:93], v199, v199 op_sel_hi:[0,0,0]
	s_setprio 0
	s_setprio 1
	v_mfma_scale_f32_16x16x128_f8f6f4 v[58:61], v[180:187], v[202:209], v[58:61], v199, v199 op_sel_hi:[0,0,0]
	v_mfma_scale_f32_16x16x128_f8f6f4 v[50:53], v[180:187], v[210:217], v[50:53], v199, v199 op_sel_hi:[0,0,0]
	v_mfma_scale_f32_16x16x128_f8f6f4 v[42:45], v[180:187], v[218:225], v[42:45], v199, v199 op_sel_hi:[0,0,0]
	v_mfma_scale_f32_16x16x128_f8f6f4 v[34:37], v[180:187], v[226:233], v[34:37], v199, v199 op_sel_hi:[0,0,0]
	v_mfma_scale_f32_16x16x128_f8f6f4 v[38:41], v[2:9], v[226:233], v[38:41], v199, v199 op_sel_hi:[0,0,0]
	v_mfma_scale_f32_16x16x128_f8f6f4 v[46:49], v[2:9], v[218:225], v[46:49], v199, v199 op_sel_hi:[0,0,0]
	v_mfma_scale_f32_16x16x128_f8f6f4 v[54:57], v[2:9], v[210:217], v[54:57], v199, v199 op_sel_hi:[0,0,0]
	v_mfma_scale_f32_16x16x128_f8f6f4 v[62:65], v[2:9], v[202:209], v[62:65], v199, v199 op_sel_hi:[0,0,0]
	s_setprio 0
	s_barrier
	s_add_i32 s62, s62, 2
	s_add_u32 s72, s72, 0x100
	s_addc_u32 s73, s73, 0
	s_add_u32 s8, s8, 0x100
	s_addc_u32 s9, s9, 0
	s_cmp_gt_u32 s62, 29
	s_cbranch_scc0 .LBB0_438
	s_and_b64 vcc, exec, s[6:7]
	s_cbranch_vccz .LBB0_441
	s_barrier

.LBB0_600:
	s_ashr_i32 s55, s54, 31
	ds_read_b128 v[18:21], v200
	ds_read_b128 v[22:25], v200 offset:1024
	ds_read_b128 v[26:29], v200 offset:2048
	ds_read_b128 v[30:33], v200 offset:3072
	ds_read_b128 v[2:5], v200 offset:16384
	ds_read_b128 v[6:9], v200 offset:17408
	ds_read_b128 v[10:13], v200 offset:18432
	ds_read_b128 v[14:17], v200 offset:19456
	s_lshl_b64 s[4:5], s[54:55], 18
	s_add_u32 s72, s38, s4
	s_addc_u32 s73, s39, s5
	s_and_b64 s[4:5], s[2:3], exec
	s_cselect_b32 s4, s73, s81
	s_cselect_b32 s5, s72, s80
	s_ashr_i32 s53, s52, 31
	s_lshl_b64 s[8:9], s[52:53], 18
	s_add_u32 s74, s94, s8
	v_readlane_b32 s8, v254, 6
	s_addc_u32 s75, s8, s9
	s_and_b64 s[8:9], s[2:3], exec
	s_cselect_b32 s53, s75, s79
	s_cselect_b32 s55, s74, s78
	s_add_u32 s8, s80, 0x20080
	s_addc_u32 s9, s81, 0
	s_mov_b32 m0, s96
	v_lshl_add_u64 v[226:227], s[8:9], 0, v[162:163]
	ds_read_b128 v[182:185], v201
	ds_read_b128 v[186:189], v201 offset:1024
	ds_read_b128 v[202:205], v201 offset:2048
	ds_read_b128 v[206:209], v201 offset:3072
	ds_read_b128 v[210:213], v201 offset:4096
	ds_read_b128 v[214:217], v201 offset:5120
	ds_read_b128 v[218:221], v201 offset:6144
	ds_read_b128 v[222:225], v201 offset:7168
	global_load_lds_dwordx4 v[226:227], off
	v_lshl_add_u64 v[226:227], s[8:9], 0, v[166:167]
	s_mov_b32 m0, s61
	s_nop 0
	global_load_lds_dwordx4 v[226:227], off
	s_waitcnt vmcnt(8)
	s_waitcnt lgkmcnt(0)
	s_barrier
	s_setprio 1
	s_waitcnt lgkmcnt(0)
	v_mfma_scale_f32_16x16x128_f8f6f4 v[158:161], v[18:25], v[182:189], 0, v199, v199 op_sel_hi:[0,0,0]
	v_mfma_scale_f32_16x16x128_f8f6f4 v[150:153], v[18:25], v[202:209], 0, v199, v199 op_sel_hi:[0,0,0]
	v_mfma_scale_f32_16x16x128_f8f6f4 v[142:145], v[18:25], v[210:217], 0, v199, v199 op_sel_hi:[0,0,0]
	v_mfma_scale_f32_16x16x128_f8f6f4 v[134:137], v[18:25], v[218:225], 0, v199, v199 op_sel_hi:[0,0,0]
	v_mfma_scale_f32_16x16x128_f8f6f4 v[130:133], v[26:33], v[218:225], 0, v199, v199 op_sel_hi:[0,0,0]
	v_mfma_scale_f32_16x16x128_f8f6f4 v[138:141], v[26:33], v[210:217], 0, v199, v199 op_sel_hi:[0,0,0]
	v_mfma_scale_f32_16x16x128_f8f6f4 v[146:149], v[26:33], v[202:209], 0, v199, v199 op_sel_hi:[0,0,0]
	v_mfma_scale_f32_16x16x128_f8f6f4 v[154:157], v[26:33], v[182:189], 0, v199, v199 op_sel_hi:[0,0,0]
	s_setprio 0
	s_setprio 1
	v_mfma_scale_f32_16x16x128_f8f6f4 v[122:125], v[10:17], v[182:189], 0, v199, v199 op_sel_hi:[0,0,0]
	v_mfma_scale_f32_16x16x128_f8f6f4 v[114:117], v[10:17], v[202:209], 0, v199, v199 op_sel_hi:[0,0,0]
	v_mfma_scale_f32_16x16x128_f8f6f4 v[106:109], v[10:17], v[210:217], 0, v199, v199 op_sel_hi:[0,0,0]
	v_mfma_scale_f32_16x16x128_f8f6f4 v[98:101], v[10:17], v[218:225], 0, v199, v199 op_sel_hi:[0,0,0]
	v_mfma_scale_f32_16x16x128_f8f6f4 v[102:105], v[2:9], v[218:225], 0, v199, v199 op_sel_hi:[0,0,0]
	v_mfma_scale_f32_16x16x128_f8f6f4 v[110:113], v[2:9], v[210:217], 0, v199, v199 op_sel_hi:[0,0,0]
	v_mfma_scale_f32_16x16x128_f8f6f4 v[118:121], v[2:9], v[202:209], 0, v199, v199 op_sel_hi:[0,0,0]
	v_mfma_scale_f32_16x16x128_f8f6f4 v[126:129], v[2:9], v[182:189], 0, v199, v199 op_sel_hi:[0,0,0]
	s_setprio 0
	s_barrier
	v_lshl_add_u64 v[182:183], s[78:79], 0, v[164:165]
	s_mov_b32 m0, s68
	v_lshl_add_u64 v[184:185], v[182:183], 0, s[46:47]
	ds_read_b128 v[202:205], v201 offset:16384
	ds_read_b128 v[206:209], v201 offset:17408
	ds_read_b128 v[210:213], v201 offset:18432
	ds_read_b128 v[214:217], v201 offset:19456
	ds_read_b128 v[218:221], v201 offset:20480
	ds_read_b128 v[222:225], v201 offset:21504
	ds_read_b128 v[226:229], v201 offset:22528
	ds_read_b128 v[230:233], v201 offset:23552
	global_load_lds_dwordx4 v[184:185], off
	v_lshl_add_u64 v[184:185], s[78:79], 0, v[168:169]
	s_add_u32 s8, s78, 0x20100
	v_lshl_add_u64 v[186:187], v[184:185], 0, s[46:47]
	s_mov_b32 m0, s69
	s_addc_u32 s9, s79, 0
	global_load_lds_dwordx4 v[186:187], off
	v_lshl_add_u64 v[186:187], s[8:9], 0, v[164:165]
	s_mov_b32 m0, s77
	s_nop 0
	global_load_lds_dwordx4 v[186:187], off
	v_lshl_add_u64 v[186:187], s[8:9], 0, v[168:169]
	s_mov_b32 m0, s84
	s_nop 0
	global_load_lds_dwordx4 v[186:187], off
	v_lshl_add_u64 v[186:187], s[80:81], 0, v[162:163]
	v_lshl_add_u64 v[188:189], v[186:187], 0, s[46:47]
	s_mov_b32 m0, s33
	s_nop 0
	global_load_lds_dwordx4 v[188:189], off
	v_lshl_add_u64 v[188:189], s[80:81], 0, v[166:167]
	v_lshl_add_u64 v[234:235], v[188:189], 0, s[46:47]
	s_mov_b32 m0, s85
	s_nop 0
	global_load_lds_dwordx4 v[234:235], off
	s_waitcnt vmcnt(8)
	s_waitcnt lgkmcnt(0)
	s_barrier
	s_setprio 1
	s_waitcnt lgkmcnt(0)
	v_mfma_scale_f32_16x16x128_f8f6f4 v[94:97], v[18:25], v[202:209], 0, v199, v199 op_sel_hi:[0,0,0]
	v_mfma_scale_f32_16x16x128_f8f6f4 v[86:89], v[18:25], v[210:217], 0, v199, v199 op_sel_hi:[0,0,0]
	v_mfma_scale_f32_16x16x128_f8f6f4 v[78:81], v[18:25], v[218:225], 0, v199, v199 op_sel_hi:[0,0,0]
	v_mfma_scale_f32_16x16x128_f8f6f4 v[70:73], v[18:25], v[226:233], 0, v199, v199 op_sel_hi:[0,0,0]
	v_mfma_scale_f32_16x16x128_f8f6f4 v[66:69], v[26:33], v[226:233], 0, v199, v199 op_sel_hi:[0,0,0]
	v_mfma_scale_f32_16x16x128_f8f6f4 v[74:77], v[26:33], v[218:225], 0, v199, v199 op_sel_hi:[0,0,0]
	v_mfma_scale_f32_16x16x128_f8f6f4 v[82:85], v[26:33], v[210:217], 0, v199, v199 op_sel_hi:[0,0,0]
	v_mfma_scale_f32_16x16x128_f8f6f4 v[90:93], v[26:33], v[202:209], 0, v199, v199 op_sel_hi:[0,0,0]
	s_setprio 0
	s_setprio 1
	v_mfma_scale_f32_16x16x128_f8f6f4 v[58:61], v[10:17], v[202:209], 0, v199, v199 op_sel_hi:[0,0,0]
	v_mfma_scale_f32_16x16x128_f8f6f4 v[50:53], v[10:17], v[210:217], 0, v199, v199 op_sel_hi:[0,0,0]
	v_mfma_scale_f32_16x16x128_f8f6f4 v[42:45], v[10:17], v[218:225], 0, v199, v199 op_sel_hi:[0,0,0]
	v_mfma_scale_f32_16x16x128_f8f6f4 v[34:37], v[10:17], v[226:233], 0, v199, v199 op_sel_hi:[0,0,0]
	v_mfma_scale_f32_16x16x128_f8f6f4 v[38:41], v[2:9], v[226:233], 0, v199, v199 op_sel_hi:[0,0,0]
	v_mfma_scale_f32_16x16x128_f8f6f4 v[46:49], v[2:9], v[218:225], 0, v199, v199 op_sel_hi:[0,0,0]
	v_mfma_scale_f32_16x16x128_f8f6f4 v[54:57], v[2:9], v[210:217], 0, v199, v199 op_sel_hi:[0,0,0]
	v_mfma_scale_f32_16x16x128_f8f6f4 v[62:65], v[2:9], v[202:209], 0, v199, v199 op_sel_hi:[0,0,0]
	s_setprio 0
	s_barrier
	ds_read_b128 v[18:21], v200 offset:32768
	ds_read_b128 v[22:25], v200 offset:33792
	ds_read_b128 v[26:29], v200 offset:34816
	ds_read_b128 v[30:33], v200 offset:35840
	ds_read_b128 v[2:5], v200 offset:49152
	ds_read_b128 v[6:9], v200 offset:50176
	ds_read_b128 v[10:13], v200 offset:51200
	ds_read_b128 v[14:17], v200 offset:52224
	s_add_u32 s8, s80, 0x20100
	s_addc_u32 s9, s81, 0
	s_mov_b32 m0, s86
	v_lshl_add_u64 v[234:235], s[8:9], 0, v[162:163]
	ds_read_b128 v[202:205], v201 offset:32768
	ds_read_b128 v[206:209], v201 offset:33792
	ds_read_b128 v[210:213], v201 offset:34816
	ds_read_b128 v[214:217], v201 offset:35840
	ds_read_b128 v[218:221], v201 offset:36864
	ds_read_b128 v[222:225], v201 offset:37888
	ds_read_b128 v[226:229], v201 offset:38912
	ds_read_b128 v[230:233], v201 offset:39936
	global_load_lds_dwordx4 v[234:235], off
	v_lshl_add_u64 v[234:235], s[8:9], 0, v[166:167]
	s_mov_b32 m0, s87
	s_nop 0
	global_load_lds_dwordx4 v[234:235], off
	s_waitcnt vmcnt(8)
	s_waitcnt lgkmcnt(0)
	s_barrier
	s_setprio 1
	s_waitcnt lgkmcnt(0)
	v_mfma_scale_f32_16x16x128_f8f6f4 v[158:161], v[18:25], v[202:209], v[158:161], v199, v199 op_sel_hi:[0,0,0]
	v_mfma_scale_f32_16x16x128_f8f6f4 v[150:153], v[18:25], v[210:217], v[150:153], v199, v199 op_sel_hi:[0,0,0]
	v_mfma_scale_f32_16x16x128_f8f6f4 v[142:145], v[18:25], v[218:225], v[142:145], v199, v199 op_sel_hi:[0,0,0]
	v_mfma_scale_f32_16x16x128_f8f6f4 v[134:137], v[18:25], v[226:233], v[134:137], v199, v199 op_sel_hi:[0,0,0]
	v_mfma_scale_f32_16x16x128_f8f6f4 v[130:133], v[26:33], v[226:233], v[130:133], v199, v199 op_sel_hi:[0,0,0]
	v_mfma_scale_f32_16x16x128_f8f6f4 v[138:141], v[26:33], v[218:225], v[138:141], v199, v199 op_sel_hi:[0,0,0]
	v_mfma_scale_f32_16x16x128_f8f6f4 v[146:149], v[26:33], v[210:217], v[146:149], v199, v199 op_sel_hi:[0,0,0]
	v_mfma_scale_f32_16x16x128_f8f6f4 v[154:157], v[26:33], v[202:209], v[154:157], v199, v199 op_sel_hi:[0,0,0]
	s_setprio 0
	s_setprio 1
	v_mfma_scale_f32_16x16x128_f8f6f4 v[122:125], v[10:17], v[202:209], v[122:125], v199, v199 op_sel_hi:[0,0,0]
	v_mfma_scale_f32_16x16x128_f8f6f4 v[114:117], v[10:17], v[210:217], v[114:117], v199, v199 op_sel_hi:[0,0,0]
	v_mfma_scale_f32_16x16x128_f8f6f4 v[106:109], v[10:17], v[218:225], v[106:109], v199, v199 op_sel_hi:[0,0,0]
	v_mfma_scale_f32_16x16x128_f8f6f4 v[98:101], v[10:17], v[226:233], v[98:101], v199, v199 op_sel_hi:[0,0,0]
	v_mfma_scale_f32_16x16x128_f8f6f4 v[102:105], v[2:9], v[226:233], v[102:105], v199, v199 op_sel_hi:[0,0,0]
	v_mfma_scale_f32_16x16x128_f8f6f4 v[110:113], v[2:9], v[218:225], v[110:113], v199, v199 op_sel_hi:[0,0,0]
	v_mfma_scale_f32_16x16x128_f8f6f4 v[118:121], v[2:9], v[210:217], v[118:121], v199, v199 op_sel_hi:[0,0,0]
	v_mfma_scale_f32_16x16x128_f8f6f4 v[126:129], v[2:9], v[202:209], v[126:129], v199, v199 op_sel_hi:[0,0,0]
	s_setprio 0
	s_barrier
	s_mov_b32 m0, s89
	v_lshl_add_u64 v[182:183], v[182:183], 0, s[48:49]
	s_add_u32 s8, s78, 0x20180
	ds_read_b128 v[202:205], v201 offset:49152
	ds_read_b128 v[206:209], v201 offset:50176
	ds_read_b128 v[210:213], v201 offset:51200
	ds_read_b128 v[214:217], v201 offset:52224
	ds_read_b128 v[218:221], v201 offset:53248
	ds_read_b128 v[222:225], v201 offset:54272
	ds_read_b128 v[226:229], v201 offset:55296
	ds_read_b128 v[230:233], v201 offset:56320
	global_load_lds_dwordx4 v[182:183], off
	v_lshl_add_u64 v[182:183], v[184:185], 0, s[48:49]
	s_mov_b32 m0, s90
	s_addc_u32 s9, s79, 0
	global_load_lds_dwordx4 v[182:183], off
	v_lshl_add_u64 v[182:183], s[8:9], 0, v[164:165]
	s_mov_b32 m0, s93
	s_nop 0
	global_load_lds_dwordx4 v[182:183], off
	v_lshl_add_u64 v[182:183], s[8:9], 0, v[168:169]
	s_mov_b32 m0, s95
	s_nop 0
	global_load_lds_dwordx4 v[182:183], off
	v_lshl_add_u64 v[182:183], v[186:187], 0, s[48:49]
	s_mov_b32 m0, s91
	s_nop 0
	global_load_lds_dwordx4 v[182:183], off
	v_lshl_add_u64 v[182:183], v[188:189], 0, s[48:49]
	s_mov_b32 m0, s92
	s_nop 0
	global_load_lds_dwordx4 v[182:183], off
	s_waitcnt vmcnt(8)
	s_waitcnt lgkmcnt(0)
	s_barrier
	s_setprio 1
	s_waitcnt lgkmcnt(0)
	v_mfma_scale_f32_16x16x128_f8f6f4 v[94:97], v[18:25], v[202:209], v[94:97], v199, v199 op_sel_hi:[0,0,0]
	v_mfma_scale_f32_16x16x128_f8f6f4 v[86:89], v[18:25], v[210:217], v[86:89], v199, v199 op_sel_hi:[0,0,0]
	v_mfma_scale_f32_16x16x128_f8f6f4 v[78:81], v[18:25], v[218:225], v[78:81], v199, v199 op_sel_hi:[0,0,0]
	v_mfma_scale_f32_16x16x128_f8f6f4 v[70:73], v[18:25], v[226:233], v[70:73], v199, v199 op_sel_hi:[0,0,0]
	v_mfma_scale_f32_16x16x128_f8f6f4 v[66:69], v[26:33], v[226:233], v[66:69], v199, v199 op_sel_hi:[0,0,0]
	v_mfma_scale_f32_16x16x128_f8f6f4 v[74:77], v[26:33], v[218:225], v[74:77], v199, v199 op_sel_hi:[0,0,0]
	v_mfma_scale_f32_16x16x128_f8f6f4 v[82:85], v[26:33], v[210:217], v[82:85], v199, v199 op_sel_hi:[0,0,0]
	v_mfma_scale_f32_16x16x128_f8f6f4 v[90:93], v[26:33], v[202:209], v[90:93], v199, v199 op_sel_hi:[0,0,0]
	s_setprio 0
	s_setprio 1
	v_mfma_scale_f32_16x16x128_f8f6f4 v[58:61], v[10:17], v[202:209], v[58:61], v199, v199 op_sel_hi:[0,0,0]
	v_mfma_scale_f32_16x16x128_f8f6f4 v[50:53], v[10:17], v[210:217], v[50:53], v199, v199 op_sel_hi:[0,0,0]
	v_mfma_scale_f32_16x16x128_f8f6f4 v[42:45], v[10:17], v[218:225], v[42:45], v199, v199 op_sel_hi:[0,0,0]
	v_mfma_scale_f32_16x16x128_f8f6f4 v[34:37], v[10:17], v[226:233], v[34:37], v199, v199 op_sel_hi:[0,0,0]
	v_mfma_scale_f32_16x16x128_f8f6f4 v[38:41], v[2:9], v[226:233], v[38:41], v199, v199 op_sel_hi:[0,0,0]
	v_mfma_scale_f32_16x16x128_f8f6f4 v[46:49], v[2:9], v[218:225], v[46:49], v199, v199 op_sel_hi:[0,0,0]
	v_mfma_scale_f32_16x16x128_f8f6f4 v[54:57], v[2:9], v[210:217], v[54:57], v199, v199 op_sel_hi:[0,0,0]
	v_mfma_scale_f32_16x16x128_f8f6f4 v[62:65], v[2:9], v[202:209], v[62:65], v199, v199 op_sel_hi:[0,0,0]
	s_setprio 0
	s_barrier
	s_add_u32 s80, s80, 0x20180
	s_addc_u32 s81, s81, 0
	s_add_u32 s8, s78, 0x200
	s_addc_u32 s9, s79, 0
	s_mov_b32 s62, 0
.LBB0_601:
	ds_read_b128 v[2:5], v200
	ds_read_b128 v[6:9], v200 offset:1024
	ds_read_b128 v[18:21], v200 offset:2048
	ds_read_b128 v[22:25], v200 offset:3072
	ds_read_b128 v[26:29], v200 offset:16384
	ds_read_b128 v[30:33], v200 offset:17408
	ds_read_b128 v[182:185], v200 offset:18432
	ds_read_b128 v[186:189], v200 offset:19456
	s_add_u32 s63, s80, 0xfffe0080
	s_addc_u32 s71, s81, -1
	s_cmp_eq_u32 s62, 4
	s_cselect_b32 s83, s4, s71
	s_cselect_b32 s82, s5, s63
	s_cselect_b32 s79, s53, s9
	s_cselect_b32 s78, s55, s8
	s_mov_b32 m0, s96
	v_lshl_add_u64 v[226:227], s[80:81], 0, v[170:171]
	ds_read_b128 v[10:13], v201
	ds_read_b128 v[14:17], v201 offset:1024
	ds_read_b128 v[202:205], v201 offset:2048
	ds_read_b128 v[206:209], v201 offset:3072
	ds_read_b128 v[210:213], v201 offset:4096
	ds_read_b128 v[214:217], v201 offset:5120
	ds_read_b128 v[218:221], v201 offset:6144
	ds_read_b128 v[222:225], v201 offset:7168
	global_load_lds_dwordx4 v[226:227], off
	v_lshl_add_u64 v[226:227], s[80:81], 0, v[172:173]
	s_mov_b32 m0, s61
	s_nop 0
	global_load_lds_dwordx4 v[226:227], off
	s_waitcnt vmcnt(8)
	s_waitcnt lgkmcnt(0)
	s_barrier
	s_setprio 1
	s_waitcnt lgkmcnt(0)
	v_mfma_scale_f32_16x16x128_f8f6f4 v[158:161], v[2:9], v[10:17], v[158:161], v199, v199 op_sel_hi:[0,0,0]
	v_mfma_scale_f32_16x16x128_f8f6f4 v[150:153], v[2:9], v[202:209], v[150:153], v199, v199 op_sel_hi:[0,0,0]
	v_mfma_scale_f32_16x16x128_f8f6f4 v[142:145], v[2:9], v[210:217], v[142:145], v199, v199 op_sel_hi:[0,0,0]
	v_mfma_scale_f32_16x16x128_f8f6f4 v[134:137], v[2:9], v[218:225], v[134:137], v199, v199 op_sel_hi:[0,0,0]
	v_mfma_scale_f32_16x16x128_f8f6f4 v[130:133], v[18:25], v[218:225], v[130:133], v199, v199 op_sel_hi:[0,0,0]
	v_mfma_scale_f32_16x16x128_f8f6f4 v[138:141], v[18:25], v[210:217], v[138:141], v199, v199 op_sel_hi:[0,0,0]
	v_mfma_scale_f32_16x16x128_f8f6f4 v[146:149], v[18:25], v[202:209], v[146:149], v199, v199 op_sel_hi:[0,0,0]
	v_mfma_scale_f32_16x16x128_f8f6f4 v[154:157], v[18:25], v[10:17], v[154:157], v199, v199 op_sel_hi:[0,0,0]
	s_setprio 0
	s_setprio 1
	v_mfma_scale_f32_16x16x128_f8f6f4 v[122:125], v[182:189], v[10:17], v[122:125], v199, v199 op_sel_hi:[0,0,0]
	v_mfma_scale_f32_16x16x128_f8f6f4 v[114:117], v[182:189], v[202:209], v[114:117], v199, v199 op_sel_hi:[0,0,0]
	v_mfma_scale_f32_16x16x128_f8f6f4 v[106:109], v[182:189], v[210:217], v[106:109], v199, v199 op_sel_hi:[0,0,0]
	v_mfma_scale_f32_16x16x128_f8f6f4 v[98:101], v[182:189], v[218:225], v[98:101], v199, v199 op_sel_hi:[0,0,0]
	v_mfma_scale_f32_16x16x128_f8f6f4 v[102:105], v[26:33], v[218:225], v[102:105], v199, v199 op_sel_hi:[0,0,0]
	v_mfma_scale_f32_16x16x128_f8f6f4 v[110:113], v[26:33], v[210:217], v[110:113], v199, v199 op_sel_hi:[0,0,0]
	v_mfma_scale_f32_16x16x128_f8f6f4 v[118:121], v[26:33], v[202:209], v[118:121], v199, v199 op_sel_hi:[0,0,0]
	v_mfma_scale_f32_16x16x128_f8f6f4 v[126:129], v[26:33], v[10:17], v[126:129], v199, v199 op_sel_hi:[0,0,0]
	s_setprio 0
	s_barrier
	s_mov_b32 m0, s68
	v_lshl_add_u64 v[10:11], s[78:79], 0, v[164:165]
	s_add_u32 vcc_lo, s78, 0x20000
	ds_read_b128 v[202:205], v201 offset:16384
	ds_read_b128 v[206:209], v201 offset:17408
	ds_read_b128 v[210:213], v201 offset:18432
	ds_read_b128 v[214:217], v201 offset:19456
	ds_read_b128 v[218:221], v201 offset:20480
	ds_read_b128 v[222:225], v201 offset:21504
	ds_read_b128 v[226:229], v201 offset:22528
	ds_read_b128 v[230:233], v201 offset:23552
	global_load_lds_dwordx4 v[10:11], off
	v_lshl_add_u64 v[12:13], s[78:79], 0, v[168:169]
	s_mov_b32 m0, s69
	s_addc_u32 vcc_hi, s79, 0
	global_load_lds_dwordx4 v[12:13], off
	v_lshl_add_u64 v[14:15], vcc, 0, v[164:165]
	s_mov_b32 m0, s77
	v_lshl_add_u64 v[16:17], s[82:83], 0, v[166:167]
	global_load_lds_dwordx4 v[14:15], off
	v_lshl_add_u64 v[14:15], vcc, 0, v[168:169]
	s_mov_b32 m0, s84
	s_nop 0
	global_load_lds_dwordx4 v[14:15], off
	v_lshl_add_u64 v[14:15], s[82:83], 0, v[162:163]
	s_mov_b32 m0, s33
	s_nop 0
	global_load_lds_dwordx4 v[14:15], off
	s_mov_b32 m0, s85
	s_nop 0
	global_load_lds_dwordx4 v[16:17], off
	s_waitcnt vmcnt(8)
	s_waitcnt lgkmcnt(0)
	s_barrier
	s_setprio 1
	s_waitcnt lgkmcnt(0)
	v_mfma_scale_f32_16x16x128_f8f6f4 v[94:97], v[2:9], v[202:209], v[94:97], v199, v199 op_sel_hi:[0,0,0]
	v_mfma_scale_f32_16x16x128_f8f6f4 v[86:89], v[2:9], v[210:217], v[86:89], v199, v199 op_sel_hi:[0,0,0]
	v_mfma_scale_f32_16x16x128_f8f6f4 v[78:81], v[2:9], v[218:225], v[78:81], v199, v199 op_sel_hi:[0,0,0]
	v_mfma_scale_f32_16x16x128_f8f6f4 v[70:73], v[2:9], v[226:233], v[70:73], v199, v199 op_sel_hi:[0,0,0]
	v_mfma_scale_f32_16x16x128_f8f6f4 v[66:69], v[18:25], v[226:233], v[66:69], v199, v199 op_sel_hi:[0,0,0]
	v_mfma_scale_f32_16x16x128_f8f6f4 v[74:77], v[18:25], v[218:225], v[74:77], v199, v199 op_sel_hi:[0,0,0]
	v_mfma_scale_f32_16x16x128_f8f6f4 v[82:85], v[18:25], v[210:217], v[82:85], v199, v199 op_sel_hi:[0,0,0]
	v_mfma_scale_f32_16x16x128_f8f6f4 v[90:93], v[18:25], v[202:209], v[90:93], v199, v199 op_sel_hi:[0,0,0]
	s_setprio 0
	s_setprio 1
	v_mfma_scale_f32_16x16x128_f8f6f4 v[58:61], v[182:189], v[202:209], v[58:61], v199, v199 op_sel_hi:[0,0,0]
	v_mfma_scale_f32_16x16x128_f8f6f4 v[50:53], v[182:189], v[210:217], v[50:53], v199, v199 op_sel_hi:[0,0,0]
	v_mfma_scale_f32_16x16x128_f8f6f4 v[42:45], v[182:189], v[218:225], v[42:45], v199, v199 op_sel_hi:[0,0,0]
	v_mfma_scale_f32_16x16x128_f8f6f4 v[34:37], v[182:189], v[226:233], v[34:37], v199, v199 op_sel_hi:[0,0,0]
	v_mfma_scale_f32_16x16x128_f8f6f4 v[38:41], v[26:33], v[226:233], v[38:41], v199, v199 op_sel_hi:[0,0,0]
	v_mfma_scale_f32_16x16x128_f8f6f4 v[46:49], v[26:33], v[218:225], v[46:49], v199, v199 op_sel_hi:[0,0,0]
	v_mfma_scale_f32_16x16x128_f8f6f4 v[54:57], v[26:33], v[210:217], v[54:57], v199, v199 op_sel_hi:[0,0,0]
	v_mfma_scale_f32_16x16x128_f8f6f4 v[62:65], v[26:33], v[202:209], v[62:65], v199, v199 op_sel_hi:[0,0,0]
	s_setprio 0
	s_barrier
	ds_read_b128 v[18:21], v200 offset:32768
	ds_read_b128 v[22:25], v200 offset:33792
	ds_read_b128 v[26:29], v200 offset:34816
	ds_read_b128 v[30:33], v200 offset:35840
	ds_read_b128 v[2:5], v200 offset:49152
	ds_read_b128 v[6:9], v200 offset:50176
	ds_read_b128 v[182:185], v200 offset:51200
	ds_read_b128 v[186:189], v200 offset:52224
	s_add_u32 s82, s82, 0x20000
	s_addc_u32 s83, s83, 0
	s_mov_b32 m0, s86
	v_lshl_add_u64 v[234:235], s[82:83], 0, v[162:163]
	ds_read_b128 v[202:205], v201 offset:32768
	ds_read_b128 v[206:209], v201 offset:33792
	ds_read_b128 v[210:213], v201 offset:34816
	ds_read_b128 v[214:217], v201 offset:35840
	ds_read_b128 v[218:221], v201 offset:36864
	ds_read_b128 v[222:225], v201 offset:37888
	ds_read_b128 v[226:229], v201 offset:38912
	ds_read_b128 v[230:233], v201 offset:39936
	global_load_lds_dwordx4 v[234:235], off
	v_lshl_add_u64 v[234:235], s[82:83], 0, v[166:167]
	s_mov_b32 m0, s87
	s_nop 0
	global_load_lds_dwordx4 v[234:235], off
	s_waitcnt vmcnt(8)
	s_waitcnt lgkmcnt(0)
	s_barrier
	s_setprio 1
	s_waitcnt lgkmcnt(0)
	v_mfma_scale_f32_16x16x128_f8f6f4 v[158:161], v[18:25], v[202:209], v[158:161], v199, v199 op_sel_hi:[0,0,0]
	v_mfma_scale_f32_16x16x128_f8f6f4 v[150:153], v[18:25], v[210:217], v[150:153], v199, v199 op_sel_hi:[0,0,0]
	v_mfma_scale_f32_16x16x128_f8f6f4 v[142:145], v[18:25], v[218:225], v[142:145], v199, v199 op_sel_hi:[0,0,0]
	v_mfma_scale_f32_16x16x128_f8f6f4 v[134:137], v[18:25], v[226:233], v[134:137], v199, v199 op_sel_hi:[0,0,0]
	v_mfma_scale_f32_16x16x128_f8f6f4 v[130:133], v[26:33], v[226:233], v[130:133], v199, v199 op_sel_hi:[0,0,0]
	v_mfma_scale_f32_16x16x128_f8f6f4 v[138:141], v[26:33], v[218:225], v[138:141], v199, v199 op_sel_hi:[0,0,0]
	v_mfma_scale_f32_16x16x128_f8f6f4 v[146:149], v[26:33], v[210:217], v[146:149], v199, v199 op_sel_hi:[0,0,0]
	v_mfma_scale_f32_16x16x128_f8f6f4 v[154:157], v[26:33], v[202:209], v[154:157], v199, v199 op_sel_hi:[0,0,0]
	s_setprio 0
	s_setprio 1
	v_mfma_scale_f32_16x16x128_f8f6f4 v[122:125], v[182:189], v[202:209], v[122:125], v199, v199 op_sel_hi:[0,0,0]
	v_mfma_scale_f32_16x16x128_f8f6f4 v[114:117], v[182:189], v[210:217], v[114:117], v199, v199 op_sel_hi:[0,0,0]
	v_mfma_scale_f32_16x16x128_f8f6f4 v[106:109], v[182:189], v[218:225], v[106:109], v199, v199 op_sel_hi:[0,0,0]
	v_mfma_scale_f32_16x16x128_f8f6f4 v[98:101], v[182:189], v[226:233], v[98:101], v199, v199 op_sel_hi:[0,0,0]
	v_mfma_scale_f32_16x16x128_f8f6f4 v[102:105], v[2:9], v[226:233], v[102:105], v199, v199 op_sel_hi:[0,0,0]
	v_mfma_scale_f32_16x16x128_f8f6f4 v[110:113], v[2:9], v[218:225], v[110:113], v199, v199 op_sel_hi:[0,0,0]
	v_mfma_scale_f32_16x16x128_f8f6f4 v[118:121], v[2:9], v[210:217], v[118:121], v199, v199 op_sel_hi:[0,0,0]
	v_mfma_scale_f32_16x16x128_f8f6f4 v[126:129], v[2:9], v[202:209], v[126:129], v199, v199 op_sel_hi:[0,0,0]
	s_setprio 0
	s_barrier
	s_mov_b32 m0, s89
	v_lshl_add_u64 v[10:11], v[10:11], 0, s[42:43]
	s_add_u32 s78, s78, 0x20080
	ds_read_b128 v[202:205], v201 offset:49152
	ds_read_b128 v[206:209], v201 offset:50176
	ds_read_b128 v[210:213], v201 offset:51200
	ds_read_b128 v[214:217], v201 offset:52224
	ds_read_b128 v[218:221], v201 offset:53248
	ds_read_b128 v[222:225], v201 offset:54272
	ds_read_b128 v[226:229], v201 offset:55296
	ds_read_b128 v[230:233], v201 offset:56320
	global_load_lds_dwordx4 v[10:11], off
	v_lshl_add_u64 v[10:11], v[12:13], 0, s[42:43]
	s_mov_b32 m0, s90
	s_addc_u32 s79, s79, 0
	global_load_lds_dwordx4 v[10:11], off
	v_lshl_add_u64 v[10:11], s[78:79], 0, v[164:165]
	s_mov_b32 m0, s93
	s_nop 0
	global_load_lds_dwordx4 v[10:11], off
	v_lshl_add_u64 v[10:11], s[78:79], 0, v[168:169]
	s_mov_b32 m0, s95
	s_nop 0
	global_load_lds_dwordx4 v[10:11], off
	v_lshl_add_u64 v[10:11], v[14:15], 0, s[42:43]
	s_mov_b32 m0, s91
	s_nop 0
	global_load_lds_dwordx4 v[10:11], off
	v_lshl_add_u64 v[10:11], v[16:17], 0, s[42:43]
	s_mov_b32 m0, s92
	s_nop 0
	global_load_lds_dwordx4 v[10:11], off
	s_waitcnt vmcnt(8)
	s_waitcnt lgkmcnt(0)
	s_barrier
	s_setprio 1
	s_waitcnt lgkmcnt(0)
	v_mfma_scale_f32_16x16x128_f8f6f4 v[94:97], v[18:25], v[202:209], v[94:97], v199, v199 op_sel_hi:[0,0,0]
	v_mfma_scale_f32_16x16x128_f8f6f4 v[86:89], v[18:25], v[210:217], v[86:89], v199, v199 op_sel_hi:[0,0,0]
	v_mfma_scale_f32_16x16x128_f8f6f4 v[78:81], v[18:25], v[218:225], v[78:81], v199, v199 op_sel_hi:[0,0,0]
	v_mfma_scale_f32_16x16x128_f8f6f4 v[70:73], v[18:25], v[226:233], v[70:73], v199, v199 op_sel_hi:[0,0,0]
	v_mfma_scale_f32_16x16x128_f8f6f4 v[66:69], v[26:33], v[226:233], v[66:69], v199, v199 op_sel_hi:[0,0,0]
	v_mfma_scale_f32_16x16x128_f8f6f4 v[74:77], v[26:33], v[218:225], v[74:77], v199, v199 op_sel_hi:[0,0,0]
	v_mfma_scale_f32_16x16x128_f8f6f4 v[82:85], v[26:33], v[210:217], v[82:85], v199, v199 op_sel_hi:[0,0,0]
	v_mfma_scale_f32_16x16x128_f8f6f4 v[90:93], v[26:33], v[202:209], v[90:93], v199, v199 op_sel_hi:[0,0,0]
	s_setprio 0
	s_setprio 1
	v_mfma_scale_f32_16x16x128_f8f6f4 v[58:61], v[182:189], v[202:209], v[58:61], v199, v199 op_sel_hi:[0,0,0]
	v_mfma_scale_f32_16x16x128_f8f6f4 v[50:53], v[182:189], v[210:217], v[50:53], v199, v199 op_sel_hi:[0,0,0]
	v_mfma_scale_f32_16x16x128_f8f6f4 v[42:45], v[182:189], v[218:225], v[42:45], v199, v199 op_sel_hi:[0,0,0]
	v_mfma_scale_f32_16x16x128_f8f6f4 v[34:37], v[182:189], v[226:233], v[34:37], v199, v199 op_sel_hi:[0,0,0]
	v_mfma_scale_f32_16x16x128_f8f6f4 v[38:41], v[2:9], v[226:233], v[38:41], v199, v199 op_sel_hi:[0,0,0]
	v_mfma_scale_f32_16x16x128_f8f6f4 v[46:49], v[2:9], v[218:225], v[46:49], v199, v199 op_sel_hi:[0,0,0]
	v_mfma_scale_f32_16x16x128_f8f6f4 v[54:57], v[2:9], v[210:217], v[54:57], v199, v199 op_sel_hi:[0,0,0]
	v_mfma_scale_f32_16x16x128_f8f6f4 v[62:65], v[2:9], v[202:209], v[62:65], v199, v199 op_sel_hi:[0,0,0]
	s_setprio 0
	s_barrier
	s_add_i32 s62, s62, 2
	s_add_u32 s80, s80, 0x100
	s_addc_u32 s81, s81, 0
	s_add_u32 s8, s8, 0x100
	s_addc_u32 s9, s9, 0
	s_cmp_gt_u32 s62, 5
	s_cbranch_scc0 .LBB0_601
	s_and_b64 vcc, exec, s[44:45]
	s_cbranch_vccz .LBB0_604
	s_barrier

.LBB0_616:
	ds_read_b128 v[18:21], v188
	ds_read_b128 v[22:25], v188 offset:1024
	ds_read_b128 v[26:29], v188 offset:2048
	ds_read_b128 v[30:33], v188 offset:3072
	ds_read_b128 v[2:5], v188 offset:16384
	ds_read_b128 v[6:9], v188 offset:17408
	ds_read_b128 v[10:13], v188 offset:18432
	ds_read_b128 v[14:17], v188 offset:19456
	s_ashr_i32 s55, s54, 31
	s_lshl_b64 s[62:63], s[54:55], 17
	s_add_u32 s72, s36, s62
	s_addc_u32 s73, s37, s63
	s_and_b64 s[62:63], s[2:3], exec
	s_cselect_b32 s85, s73, s79
	s_cselect_b32 s84, s72, s78
	s_ashr_i32 s53, s52, 31
	s_lshl_b64 s[62:63], s[52:53], 17
	s_add_u32 s74, s94, s62
	v_readlane_b32 s5, v254, 8
	s_addc_u32 s75, s5, s63
	s_and_b64 s[62:63], s[2:3], exec
	s_cselect_b32 s83, s75, s81
	s_cselect_b32 s82, s74, s80
	s_add_u32 s62, s78, 0x10080
	s_addc_u32 s63, s79, 0
	s_mov_b32 m0, s96
	v_lshl_add_u64 v[174:175], s[62:63], 0, v[166:167]
	ds_read_b128 v[196:199], v189
	ds_read_b128 v[200:203], v189 offset:1024
	ds_read_b128 v[204:207], v189 offset:2048
	ds_read_b128 v[208:211], v189 offset:3072
	ds_read_b128 v[212:215], v189 offset:4096
	ds_read_b128 v[216:219], v189 offset:5120
	ds_read_b128 v[220:223], v189 offset:6144
	ds_read_b128 v[224:227], v189 offset:7168
	global_load_lds_dwordx4 v[174:175], off
	v_lshl_add_u64 v[174:175], s[62:63], 0, v[168:169]
	s_mov_b32 m0, s97
	s_nop 0
	global_load_lds_dwordx4 v[174:175], off
	s_waitcnt vmcnt(8)
	s_waitcnt lgkmcnt(0)
	s_barrier
	s_setprio 1
	s_waitcnt lgkmcnt(0)
	v_mfma_scale_f32_16x16x128_f8f6f4 v[158:161], v[18:25], v[196:203], 0, v195, v195 op_sel_hi:[0,0,0]
	v_mfma_scale_f32_16x16x128_f8f6f4 v[150:153], v[18:25], v[204:211], 0, v195, v195 op_sel_hi:[0,0,0]
	v_mfma_scale_f32_16x16x128_f8f6f4 v[142:145], v[18:25], v[212:219], 0, v195, v195 op_sel_hi:[0,0,0]
	v_mfma_scale_f32_16x16x128_f8f6f4 v[134:137], v[18:25], v[220:227], 0, v195, v195 op_sel_hi:[0,0,0]
	v_mfma_scale_f32_16x16x128_f8f6f4 v[130:133], v[26:33], v[220:227], 0, v195, v195 op_sel_hi:[0,0,0]
	v_mfma_scale_f32_16x16x128_f8f6f4 v[138:141], v[26:33], v[212:219], 0, v195, v195 op_sel_hi:[0,0,0]
	v_mfma_scale_f32_16x16x128_f8f6f4 v[146:149], v[26:33], v[204:211], 0, v195, v195 op_sel_hi:[0,0,0]
	v_mfma_scale_f32_16x16x128_f8f6f4 v[154:157], v[26:33], v[196:203], 0, v195, v195 op_sel_hi:[0,0,0]
	s_setprio 0
	s_setprio 1
	v_mfma_scale_f32_16x16x128_f8f6f4 v[122:125], v[10:17], v[196:203], 0, v195, v195 op_sel_hi:[0,0,0]
	v_mfma_scale_f32_16x16x128_f8f6f4 v[114:117], v[10:17], v[204:211], 0, v195, v195 op_sel_hi:[0,0,0]
	v_mfma_scale_f32_16x16x128_f8f6f4 v[106:109], v[10:17], v[212:219], 0, v195, v195 op_sel_hi:[0,0,0]
	v_mfma_scale_f32_16x16x128_f8f6f4 v[98:101], v[10:17], v[220:227], 0, v195, v195 op_sel_hi:[0,0,0]
	v_mfma_scale_f32_16x16x128_f8f6f4 v[102:105], v[2:9], v[220:227], 0, v195, v195 op_sel_hi:[0,0,0]
	v_mfma_scale_f32_16x16x128_f8f6f4 v[110:113], v[2:9], v[212:219], 0, v195, v195 op_sel_hi:[0,0,0]
	v_mfma_scale_f32_16x16x128_f8f6f4 v[118:121], v[2:9], v[204:211], 0, v195, v195 op_sel_hi:[0,0,0]
	v_mfma_scale_f32_16x16x128_f8f6f4 v[126:129], v[2:9], v[196:203], 0, v195, v195 op_sel_hi:[0,0,0]
	s_setprio 0
	s_barrier
	v_lshl_add_u64 v[174:175], s[80:81], 0, v[162:163]
	s_mov_b32 m0, s61
	v_lshl_add_u64 v[176:177], v[174:175], 0, s[46:47]
	ds_read_b128 v[196:199], v189 offset:16384
	ds_read_b128 v[200:203], v189 offset:17408
	ds_read_b128 v[204:207], v189 offset:18432
	ds_read_b128 v[208:211], v189 offset:19456
	ds_read_b128 v[212:215], v189 offset:20480
	ds_read_b128 v[216:219], v189 offset:21504
	ds_read_b128 v[220:223], v189 offset:22528
	ds_read_b128 v[224:227], v189 offset:23552
	global_load_lds_dwordx4 v[176:177], off
	v_lshl_add_u64 v[176:177], s[80:81], 0, v[164:165]
	s_add_u32 s62, s80, 0x10100
	v_lshl_add_u64 v[182:183], v[176:177], 0, s[46:47]
	s_mov_b32 m0, s68
	s_addc_u32 s63, s81, 0
	global_load_lds_dwordx4 v[182:183], off
	v_lshl_add_u64 v[182:183], s[62:63], 0, v[162:163]
	s_mov_b32 m0, s69
	s_nop 0
	global_load_lds_dwordx4 v[182:183], off
	v_lshl_add_u64 v[182:183], s[62:63], 0, v[164:165]
	s_mov_b32 m0, s77
	s_nop 0
	global_load_lds_dwordx4 v[182:183], off
	v_lshl_add_u64 v[182:183], s[78:79], 0, v[166:167]
	v_lshl_add_u64 v[184:185], v[182:183], 0, s[46:47]
	s_mov_b32 m0, s51
	s_nop 0
	global_load_lds_dwordx4 v[184:185], off
	v_lshl_add_u64 v[184:185], s[78:79], 0, v[168:169]
	v_lshl_add_u64 v[228:229], v[184:185], 0, s[46:47]
	s_mov_b32 m0, s86
	s_nop 0
	global_load_lds_dwordx4 v[228:229], off
	s_waitcnt vmcnt(8)
	s_waitcnt lgkmcnt(0)
	s_barrier
	s_setprio 1
	s_waitcnt lgkmcnt(0)
	v_mfma_scale_f32_16x16x128_f8f6f4 v[94:97], v[18:25], v[196:203], 0, v195, v195 op_sel_hi:[0,0,0]
	v_mfma_scale_f32_16x16x128_f8f6f4 v[86:89], v[18:25], v[204:211], 0, v195, v195 op_sel_hi:[0,0,0]
	v_mfma_scale_f32_16x16x128_f8f6f4 v[78:81], v[18:25], v[212:219], 0, v195, v195 op_sel_hi:[0,0,0]
	v_mfma_scale_f32_16x16x128_f8f6f4 v[70:73], v[18:25], v[220:227], 0, v195, v195 op_sel_hi:[0,0,0]
	v_mfma_scale_f32_16x16x128_f8f6f4 v[66:69], v[26:33], v[220:227], 0, v195, v195 op_sel_hi:[0,0,0]
	v_mfma_scale_f32_16x16x128_f8f6f4 v[74:77], v[26:33], v[212:219], 0, v195, v195 op_sel_hi:[0,0,0]
	v_mfma_scale_f32_16x16x128_f8f6f4 v[82:85], v[26:33], v[204:211], 0, v195, v195 op_sel_hi:[0,0,0]
	v_mfma_scale_f32_16x16x128_f8f6f4 v[90:93], v[26:33], v[196:203], 0, v195, v195 op_sel_hi:[0,0,0]
	s_setprio 0
	s_setprio 1
	v_mfma_scale_f32_16x16x128_f8f6f4 v[58:61], v[10:17], v[196:203], 0, v195, v195 op_sel_hi:[0,0,0]
	v_mfma_scale_f32_16x16x128_f8f6f4 v[50:53], v[10:17], v[204:211], 0, v195, v195 op_sel_hi:[0,0,0]
	v_mfma_scale_f32_16x16x128_f8f6f4 v[42:45], v[10:17], v[212:219], 0, v195, v195 op_sel_hi:[0,0,0]
	v_mfma_scale_f32_16x16x128_f8f6f4 v[34:37], v[10:17], v[220:227], 0, v195, v195 op_sel_hi:[0,0,0]
	v_mfma_scale_f32_16x16x128_f8f6f4 v[38:41], v[2:9], v[220:227], 0, v195, v195 op_sel_hi:[0,0,0]
	v_mfma_scale_f32_16x16x128_f8f6f4 v[46:49], v[2:9], v[212:219], 0, v195, v195 op_sel_hi:[0,0,0]
	v_mfma_scale_f32_16x16x128_f8f6f4 v[54:57], v[2:9], v[204:211], 0, v195, v195 op_sel_hi:[0,0,0]
	v_mfma_scale_f32_16x16x128_f8f6f4 v[62:65], v[2:9], v[196:203], 0, v195, v195 op_sel_hi:[0,0,0]
	s_setprio 0
	s_barrier
	ds_read_b128 v[2:5], v188 offset:32768
	ds_read_b128 v[6:9], v188 offset:33792
	ds_read_b128 v[10:13], v188 offset:34816
	ds_read_b128 v[14:17], v188 offset:35840
	ds_read_b128 v[18:21], v188 offset:49152
	ds_read_b128 v[22:25], v188 offset:50176
	ds_read_b128 v[26:29], v188 offset:51200
	ds_read_b128 v[30:33], v188 offset:52224
	s_add_u32 s62, s78, 0x10100
	s_addc_u32 s63, s79, 0
	s_mov_b32 m0, s87
	v_lshl_add_u64 v[228:229], s[62:63], 0, v[166:167]
	ds_read_b128 v[196:199], v189 offset:32768
	ds_read_b128 v[200:203], v189 offset:33792
	ds_read_b128 v[204:207], v189 offset:34816
	ds_read_b128 v[208:211], v189 offset:35840
	ds_read_b128 v[212:215], v189 offset:36864
	ds_read_b128 v[216:219], v189 offset:37888
	ds_read_b128 v[220:223], v189 offset:38912
	ds_read_b128 v[224:227], v189 offset:39936
	global_load_lds_dwordx4 v[228:229], off
	v_lshl_add_u64 v[228:229], s[62:63], 0, v[168:169]
	s_mov_b32 m0, s88
	s_nop 0
	global_load_lds_dwordx4 v[228:229], off
	s_waitcnt vmcnt(8)
	s_waitcnt lgkmcnt(0)
	s_barrier
	s_setprio 1
	s_waitcnt lgkmcnt(0)
	v_mfma_scale_f32_16x16x128_f8f6f4 v[158:161], v[2:9], v[196:203], v[158:161], v195, v195 op_sel_hi:[0,0,0]
	v_mfma_scale_f32_16x16x128_f8f6f4 v[150:153], v[2:9], v[204:211], v[150:153], v195, v195 op_sel_hi:[0,0,0]
	v_mfma_scale_f32_16x16x128_f8f6f4 v[142:145], v[2:9], v[212:219], v[142:145], v195, v195 op_sel_hi:[0,0,0]
	v_mfma_scale_f32_16x16x128_f8f6f4 v[134:137], v[2:9], v[220:227], v[134:137], v195, v195 op_sel_hi:[0,0,0]
	v_mfma_scale_f32_16x16x128_f8f6f4 v[130:133], v[10:17], v[220:227], v[130:133], v195, v195 op_sel_hi:[0,0,0]
	v_mfma_scale_f32_16x16x128_f8f6f4 v[138:141], v[10:17], v[212:219], v[138:141], v195, v195 op_sel_hi:[0,0,0]
	v_mfma_scale_f32_16x16x128_f8f6f4 v[146:149], v[10:17], v[204:211], v[146:149], v195, v195 op_sel_hi:[0,0,0]
	v_mfma_scale_f32_16x16x128_f8f6f4 v[154:157], v[10:17], v[196:203], v[154:157], v195, v195 op_sel_hi:[0,0,0]
	s_setprio 0
	s_setprio 1
	v_mfma_scale_f32_16x16x128_f8f6f4 v[122:125], v[26:33], v[196:203], v[122:125], v195, v195 op_sel_hi:[0,0,0]
	v_mfma_scale_f32_16x16x128_f8f6f4 v[114:117], v[26:33], v[204:211], v[114:117], v195, v195 op_sel_hi:[0,0,0]
	v_mfma_scale_f32_16x16x128_f8f6f4 v[106:109], v[26:33], v[212:219], v[106:109], v195, v195 op_sel_hi:[0,0,0]
	v_mfma_scale_f32_16x16x128_f8f6f4 v[98:101], v[26:33], v[220:227], v[98:101], v195, v195 op_sel_hi:[0,0,0]
	v_mfma_scale_f32_16x16x128_f8f6f4 v[102:105], v[18:25], v[220:227], v[102:105], v195, v195 op_sel_hi:[0,0,0]
	v_mfma_scale_f32_16x16x128_f8f6f4 v[110:113], v[18:25], v[212:219], v[110:113], v195, v195 op_sel_hi:[0,0,0]
	v_mfma_scale_f32_16x16x128_f8f6f4 v[118:121], v[18:25], v[204:211], v[118:121], v195, v195 op_sel_hi:[0,0,0]
	v_mfma_scale_f32_16x16x128_f8f6f4 v[126:129], v[18:25], v[196:203], v[126:129], v195, v195 op_sel_hi:[0,0,0]
	s_setprio 0
	s_barrier
	s_mov_b32 m0, s89
	v_lshl_add_u64 v[174:175], v[174:175], 0, s[48:49]
	s_add_u32 s62, s80, 0x10180
	ds_read_b128 v[196:199], v189 offset:49152
	ds_read_b128 v[200:203], v189 offset:50176
	ds_read_b128 v[204:207], v189 offset:51200
	ds_read_b128 v[208:211], v189 offset:52224
	ds_read_b128 v[212:215], v189 offset:53248
	ds_read_b128 v[216:219], v189 offset:54272
	ds_read_b128 v[220:223], v189 offset:55296
	ds_read_b128 v[224:227], v189 offset:56320
	global_load_lds_dwordx4 v[174:175], off
	v_lshl_add_u64 v[174:175], v[176:177], 0, s[48:49]
	s_mov_b32 m0, s90
	s_addc_u32 s63, s81, 0
	global_load_lds_dwordx4 v[174:175], off
	v_lshl_add_u64 v[174:175], s[62:63], 0, v[162:163]
	s_mov_b32 m0, s93
	s_nop 0
	global_load_lds_dwordx4 v[174:175], off
	v_lshl_add_u64 v[174:175], s[62:63], 0, v[164:165]
	s_mov_b32 m0, s95
	s_nop 0
	global_load_lds_dwordx4 v[174:175], off
	v_lshl_add_u64 v[174:175], v[182:183], 0, s[48:49]
	s_mov_b32 m0, s91
	s_nop 0
	global_load_lds_dwordx4 v[174:175], off
	v_lshl_add_u64 v[174:175], v[184:185], 0, s[48:49]
	s_mov_b32 m0, s92
	s_nop 0
	global_load_lds_dwordx4 v[174:175], off
	s_waitcnt vmcnt(8)
	s_waitcnt lgkmcnt(0)
	s_barrier
	s_setprio 1
	s_waitcnt lgkmcnt(0)
	v_mfma_scale_f32_16x16x128_f8f6f4 v[94:97], v[2:9], v[196:203], v[94:97], v195, v195 op_sel_hi:[0,0,0]
	v_mfma_scale_f32_16x16x128_f8f6f4 v[86:89], v[2:9], v[204:211], v[86:89], v195, v195 op_sel_hi:[0,0,0]
	v_mfma_scale_f32_16x16x128_f8f6f4 v[78:81], v[2:9], v[212:219], v[78:81], v195, v195 op_sel_hi:[0,0,0]
	v_mfma_scale_f32_16x16x128_f8f6f4 v[70:73], v[2:9], v[220:227], v[70:73], v195, v195 op_sel_hi:[0,0,0]
	v_mfma_scale_f32_16x16x128_f8f6f4 v[66:69], v[10:17], v[220:227], v[66:69], v195, v195 op_sel_hi:[0,0,0]
	v_mfma_scale_f32_16x16x128_f8f6f4 v[74:77], v[10:17], v[212:219], v[74:77], v195, v195 op_sel_hi:[0,0,0]
	v_mfma_scale_f32_16x16x128_f8f6f4 v[82:85], v[10:17], v[204:211], v[82:85], v195, v195 op_sel_hi:[0,0,0]
	v_mfma_scale_f32_16x16x128_f8f6f4 v[90:93], v[10:17], v[196:203], v[90:93], v195, v195 op_sel_hi:[0,0,0]
	s_setprio 0
	s_setprio 1
	v_mfma_scale_f32_16x16x128_f8f6f4 v[58:61], v[26:33], v[196:203], v[58:61], v195, v195 op_sel_hi:[0,0,0]
	v_mfma_scale_f32_16x16x128_f8f6f4 v[50:53], v[26:33], v[204:211], v[50:53], v195, v195 op_sel_hi:[0,0,0]
	v_mfma_scale_f32_16x16x128_f8f6f4 v[42:45], v[26:33], v[212:219], v[42:45], v195, v195 op_sel_hi:[0,0,0]
	v_mfma_scale_f32_16x16x128_f8f6f4 v[34:37], v[26:33], v[220:227], v[34:37], v195, v195 op_sel_hi:[0,0,0]
	v_mfma_scale_f32_16x16x128_f8f6f4 v[38:41], v[18:25], v[220:227], v[38:41], v195, v195 op_sel_hi:[0,0,0]
	v_mfma_scale_f32_16x16x128_f8f6f4 v[46:49], v[18:25], v[212:219], v[46:49], v195, v195 op_sel_hi:[0,0,0]
	v_mfma_scale_f32_16x16x128_f8f6f4 v[54:57], v[18:25], v[204:211], v[54:57], v195, v195 op_sel_hi:[0,0,0]
	v_mfma_scale_f32_16x16x128_f8f6f4 v[62:65], v[18:25], v[196:203], v[62:65], v195, v195 op_sel_hi:[0,0,0]
	s_setprio 0
	s_barrier
	ds_read_b128 v[2:5], v188
	ds_read_b128 v[6:9], v188 offset:1024
	ds_read_b128 v[10:13], v188 offset:2048
	ds_read_b128 v[14:17], v188 offset:3072
	ds_read_b128 v[18:21], v188 offset:16384
	ds_read_b128 v[22:25], v188 offset:17408
	ds_read_b128 v[26:29], v188 offset:18432
	ds_read_b128 v[30:33], v188 offset:19456
	s_add_u32 s62, s78, 0x10180
	s_addc_u32 s63, s79, 0
	s_mov_b32 m0, s96
	v_lshl_add_u64 v[174:175], s[62:63], 0, v[166:167]
	ds_read_b128 v[196:199], v189
	ds_read_b128 v[200:203], v189 offset:1024
	ds_read_b128 v[204:207], v189 offset:2048
	ds_read_b128 v[208:211], v189 offset:3072
	ds_read_b128 v[212:215], v189 offset:4096
	ds_read_b128 v[216:219], v189 offset:5120
	ds_read_b128 v[220:223], v189 offset:6144
	ds_read_b128 v[224:227], v189 offset:7168
	global_load_lds_dwordx4 v[174:175], off
	v_lshl_add_u64 v[174:175], s[62:63], 0, v[168:169]
	s_mov_b32 m0, s97
	s_nop 0
	global_load_lds_dwordx4 v[174:175], off
	s_waitcnt vmcnt(8)
	s_waitcnt lgkmcnt(0)
	s_barrier
	s_setprio 1
	s_waitcnt lgkmcnt(0)
	v_mfma_scale_f32_16x16x128_f8f6f4 v[158:161], v[2:9], v[196:203], v[158:161], v195, v195 op_sel_hi:[0,0,0]
	v_mfma_scale_f32_16x16x128_f8f6f4 v[150:153], v[2:9], v[204:211], v[150:153], v195, v195 op_sel_hi:[0,0,0]
	v_mfma_scale_f32_16x16x128_f8f6f4 v[142:145], v[2:9], v[212:219], v[142:145], v195, v195 op_sel_hi:[0,0,0]
	v_mfma_scale_f32_16x16x128_f8f6f4 v[134:137], v[2:9], v[220:227], v[134:137], v195, v195 op_sel_hi:[0,0,0]
	v_mfma_scale_f32_16x16x128_f8f6f4 v[130:133], v[10:17], v[220:227], v[130:133], v195, v195 op_sel_hi:[0,0,0]
	v_mfma_scale_f32_16x16x128_f8f6f4 v[138:141], v[10:17], v[212:219], v[138:141], v195, v195 op_sel_hi:[0,0,0]
	v_mfma_scale_f32_16x16x128_f8f6f4 v[146:149], v[10:17], v[204:211], v[146:149], v195, v195 op_sel_hi:[0,0,0]
	v_mfma_scale_f32_16x16x128_f8f6f4 v[154:157], v[10:17], v[196:203], v[154:157], v195, v195 op_sel_hi:[0,0,0]
	s_setprio 0
	s_setprio 1
	v_mfma_scale_f32_16x16x128_f8f6f4 v[122:125], v[26:33], v[196:203], v[122:125], v195, v195 op_sel_hi:[0,0,0]
	v_mfma_scale_f32_16x16x128_f8f6f4 v[114:117], v[26:33], v[204:211], v[114:117], v195, v195 op_sel_hi:[0,0,0]
	v_mfma_scale_f32_16x16x128_f8f6f4 v[106:109], v[26:33], v[212:219], v[106:109], v195, v195 op_sel_hi:[0,0,0]
	v_mfma_scale_f32_16x16x128_f8f6f4 v[98:101], v[26:33], v[220:227], v[98:101], v195, v195 op_sel_hi:[0,0,0]
	v_mfma_scale_f32_16x16x128_f8f6f4 v[102:105], v[18:25], v[220:227], v[102:105], v195, v195 op_sel_hi:[0,0,0]
	v_mfma_scale_f32_16x16x128_f8f6f4 v[110:113], v[18:25], v[212:219], v[110:113], v195, v195 op_sel_hi:[0,0,0]
	v_mfma_scale_f32_16x16x128_f8f6f4 v[118:121], v[18:25], v[204:211], v[118:121], v195, v195 op_sel_hi:[0,0,0]
	v_mfma_scale_f32_16x16x128_f8f6f4 v[126:129], v[18:25], v[196:203], v[126:129], v195, v195 op_sel_hi:[0,0,0]
	s_setprio 0
	s_barrier
	s_mov_b32 m0, s61
	v_lshl_add_u64 v[174:175], s[82:83], 0, v[162:163]
	s_add_u32 s62, s82, 0x10000
	ds_read_b128 v[196:199], v189 offset:16384
	ds_read_b128 v[200:203], v189 offset:17408
	ds_read_b128 v[204:207], v189 offset:18432
	ds_read_b128 v[208:211], v189 offset:19456
	ds_read_b128 v[212:215], v189 offset:20480
	ds_read_b128 v[216:219], v189 offset:21504
	ds_read_b128 v[220:223], v189 offset:22528
	ds_read_b128 v[224:227], v189 offset:23552
	global_load_lds_dwordx4 v[174:175], off
	v_lshl_add_u64 v[176:177], s[82:83], 0, v[164:165]
	s_mov_b32 m0, s68
	s_addc_u32 s63, s83, 0
	global_load_lds_dwordx4 v[176:177], off
	v_lshl_add_u64 v[182:183], s[62:63], 0, v[162:163]
	s_mov_b32 m0, s69
	v_lshl_add_u64 v[184:185], s[84:85], 0, v[168:169]
	global_load_lds_dwordx4 v[182:183], off
	v_lshl_add_u64 v[182:183], s[62:63], 0, v[164:165]
	s_mov_b32 m0, s77
	s_nop 0
	global_load_lds_dwordx4 v[182:183], off
	v_lshl_add_u64 v[182:183], s[84:85], 0, v[166:167]
	s_mov_b32 m0, s51
	s_nop 0
	global_load_lds_dwordx4 v[182:183], off
	s_mov_b32 m0, s86
	s_nop 0
	global_load_lds_dwordx4 v[184:185], off
	s_waitcnt vmcnt(8)
	s_waitcnt lgkmcnt(0)
	s_barrier
	s_setprio 1
	s_waitcnt lgkmcnt(0)
	v_mfma_scale_f32_16x16x128_f8f6f4 v[94:97], v[2:9], v[196:203], v[94:97], v195, v195 op_sel_hi:[0,0,0]
	v_mfma_scale_f32_16x16x128_f8f6f4 v[86:89], v[2:9], v[204:211], v[86:89], v195, v195 op_sel_hi:[0,0,0]
	v_mfma_scale_f32_16x16x128_f8f6f4 v[78:81], v[2:9], v[212:219], v[78:81], v195, v195 op_sel_hi:[0,0,0]
	v_mfma_scale_f32_16x16x128_f8f6f4 v[70:73], v[2:9], v[220:227], v[70:73], v195, v195 op_sel_hi:[0,0,0]
	v_mfma_scale_f32_16x16x128_f8f6f4 v[66:69], v[10:17], v[220:227], v[66:69], v195, v195 op_sel_hi:[0,0,0]
	v_mfma_scale_f32_16x16x128_f8f6f4 v[74:77], v[10:17], v[212:219], v[74:77], v195, v195 op_sel_hi:[0,0,0]
	v_mfma_scale_f32_16x16x128_f8f6f4 v[82:85], v[10:17], v[204:211], v[82:85], v195, v195 op_sel_hi:[0,0,0]
	v_mfma_scale_f32_16x16x128_f8f6f4 v[90:93], v[10:17], v[196:203], v[90:93], v195, v195 op_sel_hi:[0,0,0]
	s_setprio 0
	s_setprio 1
	v_mfma_scale_f32_16x16x128_f8f6f4 v[58:61], v[26:33], v[196:203], v[58:61], v195, v195 op_sel_hi:[0,0,0]
	v_mfma_scale_f32_16x16x128_f8f6f4 v[50:53], v[26:33], v[204:211], v[50:53], v195, v195 op_sel_hi:[0,0,0]
	v_mfma_scale_f32_16x16x128_f8f6f4 v[42:45], v[26:33], v[212:219], v[42:45], v195, v195 op_sel_hi:[0,0,0]
	v_mfma_scale_f32_16x16x128_f8f6f4 v[34:37], v[26:33], v[220:227], v[34:37], v195, v195 op_sel_hi:[0,0,0]
	v_mfma_scale_f32_16x16x128_f8f6f4 v[38:41], v[18:25], v[220:227], v[38:41], v195, v195 op_sel_hi:[0,0,0]
	v_mfma_scale_f32_16x16x128_f8f6f4 v[46:49], v[18:25], v[212:219], v[46:49], v195, v195 op_sel_hi:[0,0,0]
	v_mfma_scale_f32_16x16x128_f8f6f4 v[54:57], v[18:25], v[204:211], v[54:57], v195, v195 op_sel_hi:[0,0,0]
	v_mfma_scale_f32_16x16x128_f8f6f4 v[62:65], v[18:25], v[196:203], v[62:65], v195, v195 op_sel_hi:[0,0,0]
	s_setprio 0
	s_barrier
	ds_read_b128 v[2:5], v188 offset:32768
	ds_read_b128 v[6:9], v188 offset:33792
	ds_read_b128 v[10:13], v188 offset:34816
	ds_read_b128 v[14:17], v188 offset:35840
	ds_read_b128 v[18:21], v188 offset:49152
	ds_read_b128 v[22:25], v188 offset:50176
	ds_read_b128 v[26:29], v188 offset:51200
	ds_read_b128 v[30:33], v188 offset:52224
	s_add_u32 s62, s84, 0x10000
	s_addc_u32 s63, s85, 0
	s_mov_b32 m0, s87
	v_lshl_add_u64 v[228:229], s[62:63], 0, v[166:167]
	ds_read_b128 v[196:199], v189 offset:32768
	ds_read_b128 v[200:203], v189 offset:33792
	ds_read_b128 v[204:207], v189 offset:34816
	ds_read_b128 v[208:211], v189 offset:35840
	ds_read_b128 v[212:215], v189 offset:36864
	ds_read_b128 v[216:219], v189 offset:37888
	ds_read_b128 v[220:223], v189 offset:38912
	ds_read_b128 v[224:227], v189 offset:39936
	global_load_lds_dwordx4 v[228:229], off
	v_lshl_add_u64 v[228:229], s[62:63], 0, v[168:169]
	s_mov_b32 m0, s88
	s_nop 0
	global_load_lds_dwordx4 v[228:229], off
	s_waitcnt vmcnt(8)
	s_waitcnt lgkmcnt(0)
	s_barrier
	s_setprio 1
	s_waitcnt lgkmcnt(0)
	v_mfma_scale_f32_16x16x128_f8f6f4 v[158:161], v[2:9], v[196:203], v[158:161], v195, v195 op_sel_hi:[0,0,0]
	v_mfma_scale_f32_16x16x128_f8f6f4 v[150:153], v[2:9], v[204:211], v[150:153], v195, v195 op_sel_hi:[0,0,0]
	v_mfma_scale_f32_16x16x128_f8f6f4 v[142:145], v[2:9], v[212:219], v[142:145], v195, v195 op_sel_hi:[0,0,0]
	v_mfma_scale_f32_16x16x128_f8f6f4 v[134:137], v[2:9], v[220:227], v[134:137], v195, v195 op_sel_hi:[0,0,0]
	v_mfma_scale_f32_16x16x128_f8f6f4 v[130:133], v[10:17], v[220:227], v[130:133], v195, v195 op_sel_hi:[0,0,0]
	v_mfma_scale_f32_16x16x128_f8f6f4 v[138:141], v[10:17], v[212:219], v[138:141], v195, v195 op_sel_hi:[0,0,0]
	v_mfma_scale_f32_16x16x128_f8f6f4 v[146:149], v[10:17], v[204:211], v[146:149], v195, v195 op_sel_hi:[0,0,0]
	v_mfma_scale_f32_16x16x128_f8f6f4 v[154:157], v[10:17], v[196:203], v[154:157], v195, v195 op_sel_hi:[0,0,0]
	s_setprio 0
	s_setprio 1
	v_mfma_scale_f32_16x16x128_f8f6f4 v[122:125], v[26:33], v[196:203], v[122:125], v195, v195 op_sel_hi:[0,0,0]
	v_mfma_scale_f32_16x16x128_f8f6f4 v[114:117], v[26:33], v[204:211], v[114:117], v195, v195 op_sel_hi:[0,0,0]
	v_mfma_scale_f32_16x16x128_f8f6f4 v[106:109], v[26:33], v[212:219], v[106:109], v195, v195 op_sel_hi:[0,0,0]
	v_mfma_scale_f32_16x16x128_f8f6f4 v[98:101], v[26:33], v[220:227], v[98:101], v195, v195 op_sel_hi:[0,0,0]
	v_mfma_scale_f32_16x16x128_f8f6f4 v[102:105], v[18:25], v[220:227], v[102:105], v195, v195 op_sel_hi:[0,0,0]
	v_mfma_scale_f32_16x16x128_f8f6f4 v[110:113], v[18:25], v[212:219], v[110:113], v195, v195 op_sel_hi:[0,0,0]
	v_mfma_scale_f32_16x16x128_f8f6f4 v[118:121], v[18:25], v[204:211], v[118:121], v195, v195 op_sel_hi:[0,0,0]
	v_mfma_scale_f32_16x16x128_f8f6f4 v[126:129], v[18:25], v[196:203], v[126:129], v195, v195 op_sel_hi:[0,0,0]
	s_setprio 0
	s_barrier
	s_mov_b32 m0, s89
	v_lshl_add_u64 v[174:175], v[174:175], 0, s[40:41]
	s_add_u32 s62, s82, 0x10080
	ds_read_b128 v[196:199], v189 offset:49152
	ds_read_b128 v[200:203], v189 offset:50176
	ds_read_b128 v[204:207], v189 offset:51200
	ds_read_b128 v[208:211], v189 offset:52224
	ds_read_b128 v[212:215], v189 offset:53248
	ds_read_b128 v[216:219], v189 offset:54272
	ds_read_b128 v[220:223], v189 offset:55296
	ds_read_b128 v[224:227], v189 offset:56320
	global_load_lds_dwordx4 v[174:175], off
	v_lshl_add_u64 v[174:175], v[176:177], 0, s[40:41]
	s_mov_b32 m0, s90
	s_addc_u32 s63, s83, 0
	global_load_lds_dwordx4 v[174:175], off
	v_lshl_add_u64 v[174:175], s[62:63], 0, v[162:163]
	s_mov_b32 m0, s93
	s_nop 0
	global_load_lds_dwordx4 v[174:175], off
	v_lshl_add_u64 v[174:175], s[62:63], 0, v[164:165]
	s_mov_b32 m0, s95
	s_nop 0
	global_load_lds_dwordx4 v[174:175], off
	v_lshl_add_u64 v[174:175], v[182:183], 0, s[40:41]
	s_mov_b32 m0, s91
	s_nop 0
	global_load_lds_dwordx4 v[174:175], off
	v_lshl_add_u64 v[174:175], v[184:185], 0, s[40:41]
	s_mov_b32 m0, s92
	s_nop 0
	global_load_lds_dwordx4 v[174:175], off
	s_waitcnt vmcnt(8)
	s_waitcnt lgkmcnt(0)
	s_barrier
	s_setprio 1
	s_waitcnt lgkmcnt(0)
	v_mfma_scale_f32_16x16x128_f8f6f4 v[94:97], v[2:9], v[196:203], v[94:97], v195, v195 op_sel_hi:[0,0,0]
	v_mfma_scale_f32_16x16x128_f8f6f4 v[86:89], v[2:9], v[204:211], v[86:89], v195, v195 op_sel_hi:[0,0,0]
	v_mfma_scale_f32_16x16x128_f8f6f4 v[78:81], v[2:9], v[212:219], v[78:81], v195, v195 op_sel_hi:[0,0,0]
	v_mfma_scale_f32_16x16x128_f8f6f4 v[70:73], v[2:9], v[220:227], v[70:73], v195, v195 op_sel_hi:[0,0,0]
	v_mfma_scale_f32_16x16x128_f8f6f4 v[66:69], v[10:17], v[220:227], v[66:69], v195, v195 op_sel_hi:[0,0,0]
	v_mfma_scale_f32_16x16x128_f8f6f4 v[74:77], v[10:17], v[212:219], v[74:77], v195, v195 op_sel_hi:[0,0,0]
	v_mfma_scale_f32_16x16x128_f8f6f4 v[82:85], v[10:17], v[204:211], v[82:85], v195, v195 op_sel_hi:[0,0,0]
	v_mfma_scale_f32_16x16x128_f8f6f4 v[90:93], v[10:17], v[196:203], v[90:93], v195, v195 op_sel_hi:[0,0,0]
	s_setprio 0
	s_setprio 1
	v_mfma_scale_f32_16x16x128_f8f6f4 v[58:61], v[26:33], v[196:203], v[58:61], v195, v195 op_sel_hi:[0,0,0]
	v_mfma_scale_f32_16x16x128_f8f6f4 v[50:53], v[26:33], v[204:211], v[50:53], v195, v195 op_sel_hi:[0,0,0]
	v_mfma_scale_f32_16x16x128_f8f6f4 v[42:45], v[26:33], v[212:219], v[42:45], v195, v195 op_sel_hi:[0,0,0]
	v_mfma_scale_f32_16x16x128_f8f6f4 v[34:37], v[26:33], v[220:227], v[34:37], v195, v195 op_sel_hi:[0,0,0]
	v_mfma_scale_f32_16x16x128_f8f6f4 v[38:41], v[18:25], v[220:227], v[38:41], v195, v195 op_sel_hi:[0,0,0]
	v_mfma_scale_f32_16x16x128_f8f6f4 v[46:49], v[18:25], v[212:219], v[46:49], v195, v195 op_sel_hi:[0,0,0]
	v_mfma_scale_f32_16x16x128_f8f6f4 v[54:57], v[18:25], v[204:211], v[54:57], v195, v195 op_sel_hi:[0,0,0]
	v_mfma_scale_f32_16x16x128_f8f6f4 v[62:65], v[18:25], v[196:203], v[62:65], v195, v195 op_sel_hi:[0,0,0]
	s_setprio 0
	s_barrier
	s_andn2_b64 vcc, exec, s[42:43]
	s_cbranch_vccnz .LBB0_618
	s_barrier

.LBB0_630:
	s_ashr_i32 s54, s48, 1
	s_ashr_i32 s51, s50, 31
	s_ashr_i32 s55, s54, 31
	s_lshl_b64 s[52:53], s[50:51], 19
	s_lshl_b64 s[54:55], s[54:55], 9
	s_waitcnt vmcnt(0)
	ds_read_b128 v[18:21], v181
	ds_read_b128 v[22:25], v181 offset:1024
	ds_read_b128 v[26:29], v181 offset:2048
	ds_read_b128 v[30:33], v181 offset:3072
	ds_read_b128 v[2:5], v181 offset:16384
	ds_read_b128 v[6:9], v181 offset:17408
	ds_read_b128 v[10:13], v181 offset:18432
	ds_read_b128 v[14:17], v181 offset:19456
	s_add_u32 s5, s26, s52
	s_addc_u32 s33, s27, s53
	s_add_u32 s52, s5, s54
	s_addc_u32 s53, s33, s55
	s_and_b64 s[54:55], s[2:3], exec
	s_cselect_b32 s81, s53, s75
	s_cselect_b32 s80, s52, s74
	s_ashr_i32 s49, s48, 31
	s_lshl_b64 s[54:55], s[48:49], 17
	v_readlane_b32 s5, v254, 9
	s_add_u32 s54, s5, s54
	v_readlane_b32 s5, v254, 10
	s_addc_u32 s55, s5, s55
	s_and_b64 s[62:63], s[2:3], exec
	s_cselect_b32 s79, s55, s77
	s_cselect_b32 s78, s54, s76
	s_add_u32 s62, s74, 0x40080
	s_addc_u32 s63, s75, 0
	s_add_i32 s33, s8, 0xc000
	v_lshl_add_u64 v[174:175], s[62:63], 0, v[166:167]
	s_mov_b32 m0, s33
	s_add_i32 s5, s8, 0xe000
	ds_read_b128 v[190:193], v187
	ds_read_b128 v[194:197], v187 offset:1024
	ds_read_b128 v[198:201], v187 offset:2048
	ds_read_b128 v[202:205], v187 offset:3072
	ds_read_b128 v[206:209], v187 offset:4096
	ds_read_b128 v[210:213], v187 offset:5120
	ds_read_b128 v[214:217], v187 offset:6144
	ds_read_b128 v[218:221], v187 offset:7168
	global_load_lds_dwordx4 v[174:175], off
	v_lshl_add_u64 v[174:175], s[62:63], 0, v[168:169]
	s_mov_b32 m0, s5
	s_nop 0
	global_load_lds_dwordx4 v[174:175], off
	s_waitcnt vmcnt(8)
	s_waitcnt lgkmcnt(0)
	s_barrier
	s_setprio 1
	s_waitcnt lgkmcnt(0)
	v_mfma_scale_f32_16x16x128_f8f6f4 v[158:161], v[18:25], v[190:197], 0, v188, v188 op_sel_hi:[0,0,0]
	v_mfma_scale_f32_16x16x128_f8f6f4 v[150:153], v[18:25], v[198:205], 0, v188, v188 op_sel_hi:[0,0,0]
	v_mfma_scale_f32_16x16x128_f8f6f4 v[142:145], v[18:25], v[206:213], 0, v188, v188 op_sel_hi:[0,0,0]
	v_mfma_scale_f32_16x16x128_f8f6f4 v[134:137], v[18:25], v[214:221], 0, v188, v188 op_sel_hi:[0,0,0]
	v_mfma_scale_f32_16x16x128_f8f6f4 v[130:133], v[26:33], v[214:221], 0, v188, v188 op_sel_hi:[0,0,0]
	v_mfma_scale_f32_16x16x128_f8f6f4 v[138:141], v[26:33], v[206:213], 0, v188, v188 op_sel_hi:[0,0,0]
	v_mfma_scale_f32_16x16x128_f8f6f4 v[146:149], v[26:33], v[198:205], 0, v188, v188 op_sel_hi:[0,0,0]
	v_mfma_scale_f32_16x16x128_f8f6f4 v[154:157], v[26:33], v[190:197], 0, v188, v188 op_sel_hi:[0,0,0]
	s_setprio 0
	s_setprio 1
	v_mfma_scale_f32_16x16x128_f8f6f4 v[122:125], v[10:17], v[190:197], 0, v188, v188 op_sel_hi:[0,0,0]
	v_mfma_scale_f32_16x16x128_f8f6f4 v[114:117], v[10:17], v[198:205], 0, v188, v188 op_sel_hi:[0,0,0]
	v_mfma_scale_f32_16x16x128_f8f6f4 v[106:109], v[10:17], v[206:213], 0, v188, v188 op_sel_hi:[0,0,0]
	v_mfma_scale_f32_16x16x128_f8f6f4 v[98:101], v[10:17], v[214:221], 0, v188, v188 op_sel_hi:[0,0,0]
	v_mfma_scale_f32_16x16x128_f8f6f4 v[102:105], v[2:9], v[214:221], 0, v188, v188 op_sel_hi:[0,0,0]
	v_mfma_scale_f32_16x16x128_f8f6f4 v[110:113], v[2:9], v[206:213], 0, v188, v188 op_sel_hi:[0,0,0]
	v_mfma_scale_f32_16x16x128_f8f6f4 v[118:121], v[2:9], v[198:205], 0, v188, v188 op_sel_hi:[0,0,0]
	v_mfma_scale_f32_16x16x128_f8f6f4 v[126:129], v[2:9], v[190:197], 0, v188, v188 op_sel_hi:[0,0,0]
	s_setprio 0
	s_barrier
	v_lshl_add_u64 v[174:175], s[76:77], 0, v[162:163]
	s_mov_b32 m0, s9
	v_lshl_add_u64 v[176:177], v[174:175], 0, s[44:45]
	ds_read_b128 v[190:193], v187 offset:16384
	ds_read_b128 v[194:197], v187 offset:17408
	ds_read_b128 v[198:201], v187 offset:18432
	ds_read_b128 v[202:205], v187 offset:19456
	ds_read_b128 v[206:209], v187 offset:20480
	ds_read_b128 v[210:213], v187 offset:21504
	ds_read_b128 v[214:217], v187 offset:22528
	ds_read_b128 v[218:221], v187 offset:23552
	global_load_lds_dwordx4 v[176:177], off
	v_lshl_add_u64 v[176:177], s[76:77], 0, v[164:165]
	s_add_u32 s62, s76, 0x10100
	v_lshl_add_u64 v[182:183], v[176:177], 0, s[44:45]
	s_mov_b32 m0, s61
	s_addc_u32 s63, s77, 0
	global_load_lds_dwordx4 v[182:183], off
	v_lshl_add_u64 v[182:183], s[62:63], 0, v[162:163]
	s_mov_b32 m0, s68
	s_nop 0
	global_load_lds_dwordx4 v[182:183], off
	v_lshl_add_u64 v[182:183], s[62:63], 0, v[164:165]
	s_mov_b32 m0, s69
	s_nop 0
	global_load_lds_dwordx4 v[182:183], off
	v_lshl_add_u64 v[182:183], s[74:75], 0, v[166:167]
	v_lshl_add_u64 v[184:185], v[182:183], 0, s[44:45]
	s_mov_b32 m0, s8
	s_nop 0
	global_load_lds_dwordx4 v[184:185], off
	v_lshl_add_u64 v[184:185], s[74:75], 0, v[168:169]
	v_lshl_add_u64 v[222:223], v[184:185], 0, s[44:45]
	s_mov_b32 m0, s71
	s_nop 0
	global_load_lds_dwordx4 v[222:223], off
	s_waitcnt vmcnt(8)
	s_waitcnt lgkmcnt(0)
	s_barrier
	s_setprio 1
	s_waitcnt lgkmcnt(0)
	v_mfma_scale_f32_16x16x128_f8f6f4 v[94:97], v[18:25], v[190:197], 0, v188, v188 op_sel_hi:[0,0,0]
	v_mfma_scale_f32_16x16x128_f8f6f4 v[86:89], v[18:25], v[198:205], 0, v188, v188 op_sel_hi:[0,0,0]
	v_mfma_scale_f32_16x16x128_f8f6f4 v[78:81], v[18:25], v[206:213], 0, v188, v188 op_sel_hi:[0,0,0]
	v_mfma_scale_f32_16x16x128_f8f6f4 v[70:73], v[18:25], v[214:221], 0, v188, v188 op_sel_hi:[0,0,0]
	v_mfma_scale_f32_16x16x128_f8f6f4 v[66:69], v[26:33], v[214:221], 0, v188, v188 op_sel_hi:[0,0,0]
	v_mfma_scale_f32_16x16x128_f8f6f4 v[74:77], v[26:33], v[206:213], 0, v188, v188 op_sel_hi:[0,0,0]
	v_mfma_scale_f32_16x16x128_f8f6f4 v[82:85], v[26:33], v[198:205], 0, v188, v188 op_sel_hi:[0,0,0]
	v_mfma_scale_f32_16x16x128_f8f6f4 v[90:93], v[26:33], v[190:197], 0, v188, v188 op_sel_hi:[0,0,0]
	s_setprio 0
	s_setprio 1
	v_mfma_scale_f32_16x16x128_f8f6f4 v[58:61], v[10:17], v[190:197], 0, v188, v188 op_sel_hi:[0,0,0]
	v_mfma_scale_f32_16x16x128_f8f6f4 v[50:53], v[10:17], v[198:205], 0, v188, v188 op_sel_hi:[0,0,0]
	v_mfma_scale_f32_16x16x128_f8f6f4 v[42:45], v[10:17], v[206:213], 0, v188, v188 op_sel_hi:[0,0,0]
	v_mfma_scale_f32_16x16x128_f8f6f4 v[34:37], v[10:17], v[214:221], 0, v188, v188 op_sel_hi:[0,0,0]
	v_mfma_scale_f32_16x16x128_f8f6f4 v[38:41], v[2:9], v[214:221], 0, v188, v188 op_sel_hi:[0,0,0]
	v_mfma_scale_f32_16x16x128_f8f6f4 v[46:49], v[2:9], v[206:213], 0, v188, v188 op_sel_hi:[0,0,0]
	v_mfma_scale_f32_16x16x128_f8f6f4 v[54:57], v[2:9], v[198:205], 0, v188, v188 op_sel_hi:[0,0,0]
	v_mfma_scale_f32_16x16x128_f8f6f4 v[62:65], v[2:9], v[190:197], 0, v188, v188 op_sel_hi:[0,0,0]
	s_setprio 0
	s_barrier
	ds_read_b128 v[2:5], v181 offset:32768
	ds_read_b128 v[6:9], v181 offset:33792
	ds_read_b128 v[10:13], v181 offset:34816
	ds_read_b128 v[14:17], v181 offset:35840
	ds_read_b128 v[18:21], v181 offset:49152
	ds_read_b128 v[22:25], v181 offset:50176
	ds_read_b128 v[26:29], v181 offset:51200
	ds_read_b128 v[30:33], v181 offset:52224
	s_add_u32 s62, s74, 0x40100
	s_addc_u32 s63, s75, 0
	s_mov_b32 m0, s73
	v_lshl_add_u64 v[222:223], s[62:63], 0, v[166:167]
	ds_read_b128 v[190:193], v187 offset:32768
	ds_read_b128 v[194:197], v187 offset:33792
	ds_read_b128 v[198:201], v187 offset:34816
	ds_read_b128 v[202:205], v187 offset:35840
	ds_read_b128 v[206:209], v187 offset:36864
	ds_read_b128 v[210:213], v187 offset:37888
	ds_read_b128 v[214:217], v187 offset:38912
	ds_read_b128 v[218:221], v187 offset:39936
	global_load_lds_dwordx4 v[222:223], off
	v_lshl_add_u64 v[222:223], s[62:63], 0, v[168:169]
	s_mov_b32 m0, s82
	s_nop 0
	global_load_lds_dwordx4 v[222:223], off
	s_waitcnt vmcnt(8)
	s_waitcnt lgkmcnt(0)
	s_barrier
	s_setprio 1
	s_waitcnt lgkmcnt(0)
	v_mfma_scale_f32_16x16x128_f8f6f4 v[158:161], v[2:9], v[190:197], v[158:161], v188, v188 op_sel_hi:[0,0,0]
	v_mfma_scale_f32_16x16x128_f8f6f4 v[150:153], v[2:9], v[198:205], v[150:153], v188, v188 op_sel_hi:[0,0,0]
	v_mfma_scale_f32_16x16x128_f8f6f4 v[142:145], v[2:9], v[206:213], v[142:145], v188, v188 op_sel_hi:[0,0,0]
	v_mfma_scale_f32_16x16x128_f8f6f4 v[134:137], v[2:9], v[214:221], v[134:137], v188, v188 op_sel_hi:[0,0,0]
	v_mfma_scale_f32_16x16x128_f8f6f4 v[130:133], v[10:17], v[214:221], v[130:133], v188, v188 op_sel_hi:[0,0,0]
	v_mfma_scale_f32_16x16x128_f8f6f4 v[138:141], v[10:17], v[206:213], v[138:141], v188, v188 op_sel_hi:[0,0,0]
	v_mfma_scale_f32_16x16x128_f8f6f4 v[146:149], v[10:17], v[198:205], v[146:149], v188, v188 op_sel_hi:[0,0,0]
	v_mfma_scale_f32_16x16x128_f8f6f4 v[154:157], v[10:17], v[190:197], v[154:157], v188, v188 op_sel_hi:[0,0,0]
	s_setprio 0
	s_setprio 1
	v_mfma_scale_f32_16x16x128_f8f6f4 v[122:125], v[26:33], v[190:197], v[122:125], v188, v188 op_sel_hi:[0,0,0]
	v_mfma_scale_f32_16x16x128_f8f6f4 v[114:117], v[26:33], v[198:205], v[114:117], v188, v188 op_sel_hi:[0,0,0]
	v_mfma_scale_f32_16x16x128_f8f6f4 v[106:109], v[26:33], v[206:213], v[106:109], v188, v188 op_sel_hi:[0,0,0]
	v_mfma_scale_f32_16x16x128_f8f6f4 v[98:101], v[26:33], v[214:221], v[98:101], v188, v188 op_sel_hi:[0,0,0]
	v_mfma_scale_f32_16x16x128_f8f6f4 v[102:105], v[18:25], v[214:221], v[102:105], v188, v188 op_sel_hi:[0,0,0]
	v_mfma_scale_f32_16x16x128_f8f6f4 v[110:113], v[18:25], v[206:213], v[110:113], v188, v188 op_sel_hi:[0,0,0]
	v_mfma_scale_f32_16x16x128_f8f6f4 v[118:121], v[18:25], v[198:205], v[118:121], v188, v188 op_sel_hi:[0,0,0]
	v_mfma_scale_f32_16x16x128_f8f6f4 v[126:129], v[18:25], v[190:197], v[126:129], v188, v188 op_sel_hi:[0,0,0]
	s_setprio 0
	s_barrier
	s_mov_b32 m0, s83
	v_lshl_add_u64 v[174:175], v[174:175], 0, s[46:47]
	s_add_u32 s62, s76, 0x10180
	ds_read_b128 v[190:193], v187 offset:49152
	ds_read_b128 v[194:197], v187 offset:50176
	ds_read_b128 v[198:201], v187 offset:51200
	ds_read_b128 v[202:205], v187 offset:52224
	ds_read_b128 v[206:209], v187 offset:53248
	ds_read_b128 v[210:213], v187 offset:54272
	ds_read_b128 v[214:217], v187 offset:55296
	ds_read_b128 v[218:221], v187 offset:56320
	global_load_lds_dwordx4 v[174:175], off
	v_lshl_add_u64 v[174:175], v[176:177], 0, s[46:47]
	s_mov_b32 m0, s84
	s_addc_u32 s63, s77, 0
	global_load_lds_dwordx4 v[174:175], off
	v_lshl_add_u64 v[174:175], s[62:63], 0, v[162:163]
	s_mov_b32 m0, s87
	s_nop 0
	global_load_lds_dwordx4 v[174:175], off
	v_lshl_add_u64 v[174:175], s[62:63], 0, v[164:165]
	s_mov_b32 m0, s88
	s_nop 0
	global_load_lds_dwordx4 v[174:175], off
	v_lshl_add_u64 v[174:175], v[182:183], 0, s[46:47]
	s_mov_b32 m0, s85
	s_nop 0
	global_load_lds_dwordx4 v[174:175], off
	v_lshl_add_u64 v[174:175], v[184:185], 0, s[46:47]
	s_mov_b32 m0, s86
	s_nop 0
	global_load_lds_dwordx4 v[174:175], off
	s_waitcnt vmcnt(8)
	s_waitcnt lgkmcnt(0)
	s_barrier
	s_setprio 1
	s_waitcnt lgkmcnt(0)
	v_mfma_scale_f32_16x16x128_f8f6f4 v[94:97], v[2:9], v[190:197], v[94:97], v188, v188 op_sel_hi:[0,0,0]
	v_mfma_scale_f32_16x16x128_f8f6f4 v[86:89], v[2:9], v[198:205], v[86:89], v188, v188 op_sel_hi:[0,0,0]
	v_mfma_scale_f32_16x16x128_f8f6f4 v[78:81], v[2:9], v[206:213], v[78:81], v188, v188 op_sel_hi:[0,0,0]
	v_mfma_scale_f32_16x16x128_f8f6f4 v[70:73], v[2:9], v[214:221], v[70:73], v188, v188 op_sel_hi:[0,0,0]
	v_mfma_scale_f32_16x16x128_f8f6f4 v[66:69], v[10:17], v[214:221], v[66:69], v188, v188 op_sel_hi:[0,0,0]
	v_mfma_scale_f32_16x16x128_f8f6f4 v[74:77], v[10:17], v[206:213], v[74:77], v188, v188 op_sel_hi:[0,0,0]
	v_mfma_scale_f32_16x16x128_f8f6f4 v[82:85], v[10:17], v[198:205], v[82:85], v188, v188 op_sel_hi:[0,0,0]
	v_mfma_scale_f32_16x16x128_f8f6f4 v[90:93], v[10:17], v[190:197], v[90:93], v188, v188 op_sel_hi:[0,0,0]
	s_setprio 0
	s_setprio 1
	v_mfma_scale_f32_16x16x128_f8f6f4 v[58:61], v[26:33], v[190:197], v[58:61], v188, v188 op_sel_hi:[0,0,0]
	v_mfma_scale_f32_16x16x128_f8f6f4 v[50:53], v[26:33], v[198:205], v[50:53], v188, v188 op_sel_hi:[0,0,0]
	v_mfma_scale_f32_16x16x128_f8f6f4 v[42:45], v[26:33], v[206:213], v[42:45], v188, v188 op_sel_hi:[0,0,0]
	v_mfma_scale_f32_16x16x128_f8f6f4 v[34:37], v[26:33], v[214:221], v[34:37], v188, v188 op_sel_hi:[0,0,0]
	v_mfma_scale_f32_16x16x128_f8f6f4 v[38:41], v[18:25], v[214:221], v[38:41], v188, v188 op_sel_hi:[0,0,0]
	v_mfma_scale_f32_16x16x128_f8f6f4 v[46:49], v[18:25], v[206:213], v[46:49], v188, v188 op_sel_hi:[0,0,0]
	v_mfma_scale_f32_16x16x128_f8f6f4 v[54:57], v[18:25], v[198:205], v[54:57], v188, v188 op_sel_hi:[0,0,0]
	v_mfma_scale_f32_16x16x128_f8f6f4 v[62:65], v[18:25], v[190:197], v[62:65], v188, v188 op_sel_hi:[0,0,0]
	s_setprio 0
	s_barrier
	ds_read_b128 v[2:5], v181
	ds_read_b128 v[6:9], v181 offset:1024
	ds_read_b128 v[10:13], v181 offset:2048
	ds_read_b128 v[14:17], v181 offset:3072
	ds_read_b128 v[18:21], v181 offset:16384
	ds_read_b128 v[22:25], v181 offset:17408
	ds_read_b128 v[26:29], v181 offset:18432
	ds_read_b128 v[30:33], v181 offset:19456
	s_add_u32 s62, s74, 0x40180
	s_addc_u32 s63, s75, 0
	s_mov_b32 m0, s33
	v_lshl_add_u64 v[174:175], s[62:63], 0, v[166:167]
	ds_read_b128 v[190:193], v187
	ds_read_b128 v[194:197], v187 offset:1024
	ds_read_b128 v[198:201], v187 offset:2048
	ds_read_b128 v[202:205], v187 offset:3072
	ds_read_b128 v[206:209], v187 offset:4096
	ds_read_b128 v[210:213], v187 offset:5120
	ds_read_b128 v[214:217], v187 offset:6144
	ds_read_b128 v[218:221], v187 offset:7168
	global_load_lds_dwordx4 v[174:175], off
	v_lshl_add_u64 v[174:175], s[62:63], 0, v[168:169]
	s_mov_b32 m0, s5
	s_nop 0
	global_load_lds_dwordx4 v[174:175], off
	s_waitcnt vmcnt(8)
	s_waitcnt lgkmcnt(0)
	s_barrier
	s_setprio 1
	s_waitcnt lgkmcnt(0)
	v_mfma_scale_f32_16x16x128_f8f6f4 v[158:161], v[2:9], v[190:197], v[158:161], v188, v188 op_sel_hi:[0,0,0]
	v_mfma_scale_f32_16x16x128_f8f6f4 v[150:153], v[2:9], v[198:205], v[150:153], v188, v188 op_sel_hi:[0,0,0]
	v_mfma_scale_f32_16x16x128_f8f6f4 v[142:145], v[2:9], v[206:213], v[142:145], v188, v188 op_sel_hi:[0,0,0]
	v_mfma_scale_f32_16x16x128_f8f6f4 v[134:137], v[2:9], v[214:221], v[134:137], v188, v188 op_sel_hi:[0,0,0]
	v_mfma_scale_f32_16x16x128_f8f6f4 v[130:133], v[10:17], v[214:221], v[130:133], v188, v188 op_sel_hi:[0,0,0]
	v_mfma_scale_f32_16x16x128_f8f6f4 v[138:141], v[10:17], v[206:213], v[138:141], v188, v188 op_sel_hi:[0,0,0]
	v_mfma_scale_f32_16x16x128_f8f6f4 v[146:149], v[10:17], v[198:205], v[146:149], v188, v188 op_sel_hi:[0,0,0]
	v_mfma_scale_f32_16x16x128_f8f6f4 v[154:157], v[10:17], v[190:197], v[154:157], v188, v188 op_sel_hi:[0,0,0]
	s_setprio 0
	s_setprio 1
	v_mfma_scale_f32_16x16x128_f8f6f4 v[122:125], v[26:33], v[190:197], v[122:125], v188, v188 op_sel_hi:[0,0,0]
	v_mfma_scale_f32_16x16x128_f8f6f4 v[114:117], v[26:33], v[198:205], v[114:117], v188, v188 op_sel_hi:[0,0,0]
	v_mfma_scale_f32_16x16x128_f8f6f4 v[106:109], v[26:33], v[206:213], v[106:109], v188, v188 op_sel_hi:[0,0,0]
	v_mfma_scale_f32_16x16x128_f8f6f4 v[98:101], v[26:33], v[214:221], v[98:101], v188, v188 op_sel_hi:[0,0,0]
	v_mfma_scale_f32_16x16x128_f8f6f4 v[102:105], v[18:25], v[214:221], v[102:105], v188, v188 op_sel_hi:[0,0,0]
	v_mfma_scale_f32_16x16x128_f8f6f4 v[110:113], v[18:25], v[206:213], v[110:113], v188, v188 op_sel_hi:[0,0,0]
	v_mfma_scale_f32_16x16x128_f8f6f4 v[118:121], v[18:25], v[198:205], v[118:121], v188, v188 op_sel_hi:[0,0,0]
	v_mfma_scale_f32_16x16x128_f8f6f4 v[126:129], v[18:25], v[190:197], v[126:129], v188, v188 op_sel_hi:[0,0,0]
	s_setprio 0
	s_barrier
	s_mov_b32 m0, s9
	v_lshl_add_u64 v[174:175], s[78:79], 0, v[162:163]
	s_add_u32 s62, s78, 0x10000
	ds_read_b128 v[190:193], v187 offset:16384
	ds_read_b128 v[194:197], v187 offset:17408
	ds_read_b128 v[198:201], v187 offset:18432
	ds_read_b128 v[202:205], v187 offset:19456
	ds_read_b128 v[206:209], v187 offset:20480
	ds_read_b128 v[210:213], v187 offset:21504
	ds_read_b128 v[214:217], v187 offset:22528
	ds_read_b128 v[218:221], v187 offset:23552
	global_load_lds_dwordx4 v[174:175], off
	v_lshl_add_u64 v[176:177], s[78:79], 0, v[164:165]
	s_mov_b32 m0, s61
	s_addc_u32 s63, s79, 0
	global_load_lds_dwordx4 v[176:177], off
	v_lshl_add_u64 v[182:183], s[62:63], 0, v[162:163]
	s_mov_b32 m0, s68
	v_lshl_add_u64 v[184:185], s[80:81], 0, v[168:169]
	global_load_lds_dwordx4 v[182:183], off
	v_lshl_add_u64 v[182:183], s[62:63], 0, v[164:165]
	s_mov_b32 m0, s69
	s_nop 0
	global_load_lds_dwordx4 v[182:183], off
	v_lshl_add_u64 v[182:183], s[80:81], 0, v[166:167]
	s_mov_b32 m0, s8
	s_nop 0
	global_load_lds_dwordx4 v[182:183], off
	s_mov_b32 m0, s71
	s_nop 0
	global_load_lds_dwordx4 v[184:185], off
	s_waitcnt vmcnt(8)
	s_waitcnt lgkmcnt(0)
	s_barrier
	s_setprio 1
	s_waitcnt lgkmcnt(0)
	v_mfma_scale_f32_16x16x128_f8f6f4 v[94:97], v[2:9], v[190:197], v[94:97], v188, v188 op_sel_hi:[0,0,0]
	v_mfma_scale_f32_16x16x128_f8f6f4 v[86:89], v[2:9], v[198:205], v[86:89], v188, v188 op_sel_hi:[0,0,0]
	v_mfma_scale_f32_16x16x128_f8f6f4 v[78:81], v[2:9], v[206:213], v[78:81], v188, v188 op_sel_hi:[0,0,0]
	v_mfma_scale_f32_16x16x128_f8f6f4 v[70:73], v[2:9], v[214:221], v[70:73], v188, v188 op_sel_hi:[0,0,0]
	v_mfma_scale_f32_16x16x128_f8f6f4 v[66:69], v[10:17], v[214:221], v[66:69], v188, v188 op_sel_hi:[0,0,0]
	v_mfma_scale_f32_16x16x128_f8f6f4 v[74:77], v[10:17], v[206:213], v[74:77], v188, v188 op_sel_hi:[0,0,0]
	v_mfma_scale_f32_16x16x128_f8f6f4 v[82:85], v[10:17], v[198:205], v[82:85], v188, v188 op_sel_hi:[0,0,0]
	v_mfma_scale_f32_16x16x128_f8f6f4 v[90:93], v[10:17], v[190:197], v[90:93], v188, v188 op_sel_hi:[0,0,0]
	s_setprio 0
	s_setprio 1
	v_mfma_scale_f32_16x16x128_f8f6f4 v[58:61], v[26:33], v[190:197], v[58:61], v188, v188 op_sel_hi:[0,0,0]
	v_mfma_scale_f32_16x16x128_f8f6f4 v[50:53], v[26:33], v[198:205], v[50:53], v188, v188 op_sel_hi:[0,0,0]
	v_mfma_scale_f32_16x16x128_f8f6f4 v[42:45], v[26:33], v[206:213], v[42:45], v188, v188 op_sel_hi:[0,0,0]
	v_mfma_scale_f32_16x16x128_f8f6f4 v[34:37], v[26:33], v[214:221], v[34:37], v188, v188 op_sel_hi:[0,0,0]
	v_mfma_scale_f32_16x16x128_f8f6f4 v[38:41], v[18:25], v[214:221], v[38:41], v188, v188 op_sel_hi:[0,0,0]
	v_mfma_scale_f32_16x16x128_f8f6f4 v[46:49], v[18:25], v[206:213], v[46:49], v188, v188 op_sel_hi:[0,0,0]
	v_mfma_scale_f32_16x16x128_f8f6f4 v[54:57], v[18:25], v[198:205], v[54:57], v188, v188 op_sel_hi:[0,0,0]
	v_mfma_scale_f32_16x16x128_f8f6f4 v[62:65], v[18:25], v[190:197], v[62:65], v188, v188 op_sel_hi:[0,0,0]
	s_setprio 0
	s_barrier
	ds_read_b128 v[2:5], v181 offset:32768
	ds_read_b128 v[6:9], v181 offset:33792
	ds_read_b128 v[10:13], v181 offset:34816
	ds_read_b128 v[14:17], v181 offset:35840
	ds_read_b128 v[18:21], v181 offset:49152
	ds_read_b128 v[22:25], v181 offset:50176
	ds_read_b128 v[26:29], v181 offset:51200
	ds_read_b128 v[30:33], v181 offset:52224
	s_add_u32 s62, s80, 0x40000
	s_addc_u32 s63, s81, 0
	s_mov_b32 m0, s73
	v_lshl_add_u64 v[222:223], s[62:63], 0, v[166:167]
	ds_read_b128 v[190:193], v187 offset:32768
	ds_read_b128 v[194:197], v187 offset:33792
	ds_read_b128 v[198:201], v187 offset:34816
	ds_read_b128 v[202:205], v187 offset:35840
	ds_read_b128 v[206:209], v187 offset:36864
	ds_read_b128 v[210:213], v187 offset:37888
	ds_read_b128 v[214:217], v187 offset:38912
	ds_read_b128 v[218:221], v187 offset:39936
	global_load_lds_dwordx4 v[222:223], off
	v_lshl_add_u64 v[222:223], s[62:63], 0, v[168:169]
	s_mov_b32 m0, s82
	s_nop 0
	global_load_lds_dwordx4 v[222:223], off
	s_waitcnt vmcnt(8)
	s_waitcnt lgkmcnt(0)
	s_barrier
	s_setprio 1
	s_waitcnt lgkmcnt(0)
	v_mfma_scale_f32_16x16x128_f8f6f4 v[158:161], v[2:9], v[190:197], v[158:161], v188, v188 op_sel_hi:[0,0,0]
	v_mfma_scale_f32_16x16x128_f8f6f4 v[150:153], v[2:9], v[198:205], v[150:153], v188, v188 op_sel_hi:[0,0,0]
	v_mfma_scale_f32_16x16x128_f8f6f4 v[142:145], v[2:9], v[206:213], v[142:145], v188, v188 op_sel_hi:[0,0,0]
	v_mfma_scale_f32_16x16x128_f8f6f4 v[134:137], v[2:9], v[214:221], v[134:137], v188, v188 op_sel_hi:[0,0,0]
	v_mfma_scale_f32_16x16x128_f8f6f4 v[130:133], v[10:17], v[214:221], v[130:133], v188, v188 op_sel_hi:[0,0,0]
	v_mfma_scale_f32_16x16x128_f8f6f4 v[138:141], v[10:17], v[206:213], v[138:141], v188, v188 op_sel_hi:[0,0,0]
	v_mfma_scale_f32_16x16x128_f8f6f4 v[146:149], v[10:17], v[198:205], v[146:149], v188, v188 op_sel_hi:[0,0,0]
	v_mfma_scale_f32_16x16x128_f8f6f4 v[154:157], v[10:17], v[190:197], v[154:157], v188, v188 op_sel_hi:[0,0,0]
	s_setprio 0
	s_setprio 1
	v_mfma_scale_f32_16x16x128_f8f6f4 v[122:125], v[26:33], v[190:197], v[122:125], v188, v188 op_sel_hi:[0,0,0]
	v_mfma_scale_f32_16x16x128_f8f6f4 v[114:117], v[26:33], v[198:205], v[114:117], v188, v188 op_sel_hi:[0,0,0]
	v_mfma_scale_f32_16x16x128_f8f6f4 v[106:109], v[26:33], v[206:213], v[106:109], v188, v188 op_sel_hi:[0,0,0]
	v_mfma_scale_f32_16x16x128_f8f6f4 v[98:101], v[26:33], v[214:221], v[98:101], v188, v188 op_sel_hi:[0,0,0]
	v_mfma_scale_f32_16x16x128_f8f6f4 v[102:105], v[18:25], v[214:221], v[102:105], v188, v188 op_sel_hi:[0,0,0]
	v_mfma_scale_f32_16x16x128_f8f6f4 v[110:113], v[18:25], v[206:213], v[110:113], v188, v188 op_sel_hi:[0,0,0]
	v_mfma_scale_f32_16x16x128_f8f6f4 v[118:121], v[18:25], v[198:205], v[118:121], v188, v188 op_sel_hi:[0,0,0]
	v_mfma_scale_f32_16x16x128_f8f6f4 v[126:129], v[18:25], v[190:197], v[126:129], v188, v188 op_sel_hi:[0,0,0]
	s_setprio 0
	s_barrier
	s_mov_b32 m0, s83
	v_lshl_add_u64 v[174:175], v[174:175], 0, s[38:39]
	s_add_u32 s62, s78, 0x10080
	ds_read_b128 v[190:193], v187 offset:49152
	ds_read_b128 v[194:197], v187 offset:50176
	ds_read_b128 v[198:201], v187 offset:51200
	ds_read_b128 v[202:205], v187 offset:52224
	ds_read_b128 v[206:209], v187 offset:53248
	ds_read_b128 v[210:213], v187 offset:54272
	ds_read_b128 v[214:217], v187 offset:55296
	ds_read_b128 v[218:221], v187 offset:56320
	global_load_lds_dwordx4 v[174:175], off
	v_lshl_add_u64 v[174:175], v[176:177], 0, s[38:39]
	s_mov_b32 m0, s84
	s_addc_u32 s63, s79, 0
	global_load_lds_dwordx4 v[174:175], off
	v_lshl_add_u64 v[174:175], s[62:63], 0, v[162:163]
	s_mov_b32 m0, s87
	s_nop 0
	global_load_lds_dwordx4 v[174:175], off
	v_lshl_add_u64 v[174:175], s[62:63], 0, v[164:165]
	s_mov_b32 m0, s88
	s_nop 0
	global_load_lds_dwordx4 v[174:175], off
	v_lshl_add_u64 v[174:175], v[182:183], 0, s[38:39]
	s_mov_b32 m0, s85
	s_nop 0
	global_load_lds_dwordx4 v[174:175], off
	v_lshl_add_u64 v[174:175], v[184:185], 0, s[38:39]
	s_mov_b32 m0, s86
	s_nop 0
	global_load_lds_dwordx4 v[174:175], off
	s_waitcnt vmcnt(8)
	s_waitcnt lgkmcnt(0)
	s_barrier
	s_setprio 1
	s_waitcnt lgkmcnt(0)
	v_mfma_scale_f32_16x16x128_f8f6f4 v[94:97], v[2:9], v[190:197], v[94:97], v188, v188 op_sel_hi:[0,0,0]
	v_mfma_scale_f32_16x16x128_f8f6f4 v[86:89], v[2:9], v[198:205], v[86:89], v188, v188 op_sel_hi:[0,0,0]
	v_mfma_scale_f32_16x16x128_f8f6f4 v[78:81], v[2:9], v[206:213], v[78:81], v188, v188 op_sel_hi:[0,0,0]
	v_mfma_scale_f32_16x16x128_f8f6f4 v[70:73], v[2:9], v[214:221], v[70:73], v188, v188 op_sel_hi:[0,0,0]
	v_mfma_scale_f32_16x16x128_f8f6f4 v[66:69], v[10:17], v[214:221], v[66:69], v188, v188 op_sel_hi:[0,0,0]
	v_mfma_scale_f32_16x16x128_f8f6f4 v[74:77], v[10:17], v[206:213], v[74:77], v188, v188 op_sel_hi:[0,0,0]
	v_mfma_scale_f32_16x16x128_f8f6f4 v[82:85], v[10:17], v[198:205], v[82:85], v188, v188 op_sel_hi:[0,0,0]
	v_mfma_scale_f32_16x16x128_f8f6f4 v[90:93], v[10:17], v[190:197], v[90:93], v188, v188 op_sel_hi:[0,0,0]
	s_setprio 0
	s_setprio 1
	v_mfma_scale_f32_16x16x128_f8f6f4 v[58:61], v[26:33], v[190:197], v[58:61], v188, v188 op_sel_hi:[0,0,0]
	v_mfma_scale_f32_16x16x128_f8f6f4 v[50:53], v[26:33], v[198:205], v[50:53], v188, v188 op_sel_hi:[0,0,0]
	v_mfma_scale_f32_16x16x128_f8f6f4 v[42:45], v[26:33], v[206:213], v[42:45], v188, v188 op_sel_hi:[0,0,0]
	v_mfma_scale_f32_16x16x128_f8f6f4 v[34:37], v[26:33], v[214:221], v[34:37], v188, v188 op_sel_hi:[0,0,0]
	v_mfma_scale_f32_16x16x128_f8f6f4 v[38:41], v[18:25], v[214:221], v[38:41], v188, v188 op_sel_hi:[0,0,0]
	v_mfma_scale_f32_16x16x128_f8f6f4 v[46:49], v[18:25], v[206:213], v[46:49], v188, v188 op_sel_hi:[0,0,0]
	v_mfma_scale_f32_16x16x128_f8f6f4 v[54:57], v[18:25], v[198:205], v[54:57], v188, v188 op_sel_hi:[0,0,0]
	v_mfma_scale_f32_16x16x128_f8f6f4 v[62:65], v[18:25], v[190:197], v[62:65], v188, v188 op_sel_hi:[0,0,0]
	s_setprio 0
	s_barrier
	s_andn2_b64 vcc, exec, s[40:41]
	s_cbranch_vccnz .LBB0_632
	s_barrier

.LBB0_791:
	ds_read_b128 v[2:5], v189
	ds_read_b128 v[6:9], v189 offset:1024
	ds_read_b128 v[192:195], v189 offset:2048
	ds_read_b128 v[196:199], v189 offset:3072
	ds_read_b128 v[200:203], v189 offset:16384
	ds_read_b128 v[204:207], v189 offset:17408
	ds_read_b128 v[208:211], v189 offset:18432
	ds_read_b128 v[212:215], v189 offset:19456
	s_add_u32 s37, s46, 0x100
	s_addc_u32 s39, s47, 0
	s_and_b64 s[50:51], s[48:49], exec
	s_cselect_b32 s51, s1, s39
	s_cselect_b32 s50, s0, s37
	s_add_u32 s37, s44, 0x100
	s_addc_u32 s39, s45, 0
	s_and_b64 s[48:49], s[48:49], exec
	s_cselect_b32 s49, s5, s39
	s_cselect_b32 s48, s4, s37
	s_add_u32 s88, s46, 0x80080
	s_addc_u32 s89, s47, 0
	s_add_i32 s37, s8, 0xc000
	v_lshl_add_u64 v[174:175], s[88:89], 0, v[154:155]
	s_mov_b32 m0, s37
	s_add_i32 s39, s8, 0xe000
	ds_read_b128 v[216:219], v190
	ds_read_b128 v[220:223], v190 offset:1024
	ds_read_b128 v[224:227], v190 offset:2048
	ds_read_b128 v[228:231], v190 offset:3072
	ds_read_b128 v[242:245], v190 offset:4096
	ds_read_b128 v[246:249], v190 offset:5120
	ds_read_b128 v[232:235], v190 offset:6144
	ds_read_b128 v[236:239], v190 offset:7168
	global_load_lds_dwordx4 v[174:175], off
	v_lshl_add_u64 v[174:175], s[88:89], 0, v[158:159]
	s_mov_b32 m0, s39
	s_nop 0
	global_load_lds_dwordx4 v[174:175], off
	s_waitcnt vmcnt(8)
	s_waitcnt lgkmcnt(0)
	s_barrier
	s_setprio 1
	s_waitcnt lgkmcnt(0)
	v_mfma_scale_f32_16x16x128_f8f6f4 v[134:137], v[2:9], v[216:223], 0, v188, v188 op_sel_hi:[0,0,0]
	v_mfma_scale_f32_16x16x128_f8f6f4 v[126:129], v[2:9], v[224:231], 0, v188, v188 op_sel_hi:[0,0,0]
	v_mfma_scale_f32_16x16x128_f8f6f4 v[118:121], v[2:9], v[242:249], 0, v188, v188 op_sel_hi:[0,0,0]
	v_mfma_scale_f32_16x16x128_f8f6f4 v[110:113], v[2:9], v[232:239], 0, v188, v188 op_sel_hi:[0,0,0]
	v_mfma_scale_f32_16x16x128_f8f6f4 v[106:109], v[192:199], v[232:239], 0, v188, v188 op_sel_hi:[0,0,0]
	v_mfma_scale_f32_16x16x128_f8f6f4 v[114:117], v[192:199], v[242:249], 0, v188, v188 op_sel_hi:[0,0,0]
	v_mfma_scale_f32_16x16x128_f8f6f4 v[122:125], v[192:199], v[224:231], 0, v188, v188 op_sel_hi:[0,0,0]
	v_mfma_scale_f32_16x16x128_f8f6f4 v[130:133], v[192:199], v[216:223], 0, v188, v188 op_sel_hi:[0,0,0]
	s_setprio 0
	s_setprio 1
	v_mfma_scale_f32_16x16x128_f8f6f4 v[98:101], v[208:215], v[216:223], 0, v188, v188 op_sel_hi:[0,0,0]
	v_mfma_scale_f32_16x16x128_f8f6f4 v[90:93], v[208:215], v[224:231], 0, v188, v188 op_sel_hi:[0,0,0]
	v_mfma_scale_f32_16x16x128_f8f6f4 v[82:85], v[208:215], v[242:249], 0, v188, v188 op_sel_hi:[0,0,0]
	v_mfma_scale_f32_16x16x128_f8f6f4 v[74:77], v[208:215], v[232:239], 0, v188, v188 op_sel_hi:[0,0,0]
	v_mfma_scale_f32_16x16x128_f8f6f4 v[78:81], v[200:207], v[232:239], 0, v188, v188 op_sel_hi:[0,0,0]
	v_mfma_scale_f32_16x16x128_f8f6f4 v[86:89], v[200:207], v[242:249], 0, v188, v188 op_sel_hi:[0,0,0]
	v_mfma_scale_f32_16x16x128_f8f6f4 v[94:97], v[200:207], v[224:231], 0, v188, v188 op_sel_hi:[0,0,0]
	v_mfma_scale_f32_16x16x128_f8f6f4 v[102:105], v[200:207], v[216:223], 0, v188, v188 op_sel_hi:[0,0,0]
	s_setprio 0
	s_barrier
	s_mov_b32 m0, s9
	v_lshl_add_u64 v[174:175], s[48:49], 0, v[156:157]
	s_add_u32 s88, s48, 0x80000
	ds_read_b128 v[216:219], v190 offset:16384
	ds_read_b128 v[220:223], v190 offset:17408
	ds_read_b128 v[224:227], v190 offset:18432
	ds_read_b128 v[228:231], v190 offset:19456
	ds_read_b128 v[232:235], v190 offset:20480
	ds_read_b128 v[236:239], v190 offset:21504
	ds_read_b128 v[242:245], v190 offset:22528
	ds_read_b128 v[246:249], v190 offset:23552
	global_load_lds_dwordx4 v[174:175], off
	v_lshl_add_u64 v[176:177], s[48:49], 0, v[160:161]
	s_mov_b32 m0, s27
	s_addc_u32 s89, s49, 0
	global_load_lds_dwordx4 v[176:177], off
	v_lshl_add_u64 v[182:183], s[88:89], 0, v[156:157]
	s_mov_b32 m0, s33
	v_lshl_add_u64 v[184:185], s[50:51], 0, v[158:159]
	global_load_lds_dwordx4 v[182:183], off
	v_lshl_add_u64 v[182:183], s[88:89], 0, v[160:161]
	s_mov_b32 m0, s35
	s_nop 0
	global_load_lds_dwordx4 v[182:183], off
	v_lshl_add_u64 v[182:183], s[50:51], 0, v[154:155]
	s_mov_b32 m0, s8
	s_nop 0
	global_load_lds_dwordx4 v[182:183], off
	s_mov_b32 m0, s43
	s_nop 0
	global_load_lds_dwordx4 v[184:185], off
	s_waitcnt vmcnt(8)
	s_waitcnt lgkmcnt(0)
	s_barrier
	s_setprio 1
	s_waitcnt lgkmcnt(0)
	v_mfma_scale_f32_16x16x128_f8f6f4 v[70:73], v[2:9], v[216:223], 0, v188, v188 op_sel_hi:[0,0,0]
	v_mfma_scale_f32_16x16x128_f8f6f4 v[62:65], v[2:9], v[224:231], 0, v188, v188 op_sel_hi:[0,0,0]
	v_mfma_scale_f32_16x16x128_f8f6f4 v[54:57], v[2:9], v[232:239], 0, v188, v188 op_sel_hi:[0,0,0]
	v_mfma_scale_f32_16x16x128_f8f6f4 v[46:49], v[2:9], v[242:249], 0, v188, v188 op_sel_hi:[0,0,0]
	v_mfma_scale_f32_16x16x128_f8f6f4 v[42:45], v[192:199], v[242:249], 0, v188, v188 op_sel_hi:[0,0,0]
	v_mfma_scale_f32_16x16x128_f8f6f4 v[50:53], v[192:199], v[232:239], 0, v188, v188 op_sel_hi:[0,0,0]
	v_mfma_scale_f32_16x16x128_f8f6f4 v[58:61], v[192:199], v[224:231], 0, v188, v188 op_sel_hi:[0,0,0]
	v_mfma_scale_f32_16x16x128_f8f6f4 v[66:69], v[192:199], v[216:223], 0, v188, v188 op_sel_hi:[0,0,0]
	s_setprio 0
	s_setprio 1
	v_mfma_scale_f32_16x16x128_f8f6f4 v[34:37], v[208:215], v[216:223], 0, v188, v188 op_sel_hi:[0,0,0]
	v_mfma_scale_f32_16x16x128_f8f6f4 v[26:29], v[208:215], v[224:231], 0, v188, v188 op_sel_hi:[0,0,0]
	v_mfma_scale_f32_16x16x128_f8f6f4 v[18:21], v[208:215], v[232:239], 0, v188, v188 op_sel_hi:[0,0,0]
	v_mfma_scale_f32_16x16x128_f8f6f4 v[10:13], v[208:215], v[242:249], 0, v188, v188 op_sel_hi:[0,0,0]
	v_mfma_scale_f32_16x16x128_f8f6f4 v[14:17], v[200:207], v[242:249], 0, v188, v188 op_sel_hi:[0,0,0]
	v_mfma_scale_f32_16x16x128_f8f6f4 v[22:25], v[200:207], v[232:239], 0, v188, v188 op_sel_hi:[0,0,0]
	v_mfma_scale_f32_16x16x128_f8f6f4 v[30:33], v[200:207], v[224:231], 0, v188, v188 op_sel_hi:[0,0,0]
	v_mfma_scale_f32_16x16x128_f8f6f4 v[38:41], v[200:207], v[216:223], 0, v188, v188 op_sel_hi:[0,0,0]
	s_setprio 0
	s_barrier
	ds_read_b128 v[2:5], v189 offset:32768
	ds_read_b128 v[6:9], v189 offset:33792
	ds_read_b128 v[192:195], v189 offset:34816
	ds_read_b128 v[196:199], v189 offset:35840
	ds_read_b128 v[200:203], v189 offset:49152
	ds_read_b128 v[204:207], v189 offset:50176
	ds_read_b128 v[208:211], v189 offset:51200
	ds_read_b128 v[212:215], v189 offset:52224
	s_add_u32 s50, s50, 0x80000
	s_addc_u32 s51, s51, 0
	s_mov_b32 m0, s52
	v_lshl_add_u64 v[186:187], s[50:51], 0, v[154:155]
	ds_read_b128 v[216:219], v190 offset:32768
	ds_read_b128 v[220:223], v190 offset:33792
	ds_read_b128 v[224:227], v190 offset:34816
	ds_read_b128 v[228:231], v190 offset:35840
	ds_read_b128 v[232:235], v190 offset:36864
	ds_read_b128 v[236:239], v190 offset:37888
	ds_read_b128 v[242:245], v190 offset:38912
	ds_read_b128 v[246:249], v190 offset:39936
	global_load_lds_dwordx4 v[186:187], off
	v_lshl_add_u64 v[186:187], s[50:51], 0, v[158:159]
	s_mov_b32 m0, s53
	s_nop 0
	global_load_lds_dwordx4 v[186:187], off
	s_waitcnt vmcnt(8)
	s_waitcnt lgkmcnt(0)
	s_barrier
	s_setprio 1
	s_waitcnt lgkmcnt(0)
	v_mfma_scale_f32_16x16x128_f8f6f4 v[134:137], v[2:9], v[216:223], v[134:137], v188, v188 op_sel_hi:[0,0,0]
	v_mfma_scale_f32_16x16x128_f8f6f4 v[126:129], v[2:9], v[224:231], v[126:129], v188, v188 op_sel_hi:[0,0,0]
	v_mfma_scale_f32_16x16x128_f8f6f4 v[118:121], v[2:9], v[232:239], v[118:121], v188, v188 op_sel_hi:[0,0,0]
	v_mfma_scale_f32_16x16x128_f8f6f4 v[110:113], v[2:9], v[242:249], v[110:113], v188, v188 op_sel_hi:[0,0,0]
	v_mfma_scale_f32_16x16x128_f8f6f4 v[106:109], v[192:199], v[242:249], v[106:109], v188, v188 op_sel_hi:[0,0,0]
	v_mfma_scale_f32_16x16x128_f8f6f4 v[114:117], v[192:199], v[232:239], v[114:117], v188, v188 op_sel_hi:[0,0,0]
	v_mfma_scale_f32_16x16x128_f8f6f4 v[122:125], v[192:199], v[224:231], v[122:125], v188, v188 op_sel_hi:[0,0,0]
	v_mfma_scale_f32_16x16x128_f8f6f4 v[130:133], v[192:199], v[216:223], v[130:133], v188, v188 op_sel_hi:[0,0,0]
	s_setprio 0
	s_setprio 1
	v_mfma_scale_f32_16x16x128_f8f6f4 v[98:101], v[208:215], v[216:223], v[98:101], v188, v188 op_sel_hi:[0,0,0]
	v_mfma_scale_f32_16x16x128_f8f6f4 v[90:93], v[208:215], v[224:231], v[90:93], v188, v188 op_sel_hi:[0,0,0]
	v_mfma_scale_f32_16x16x128_f8f6f4 v[82:85], v[208:215], v[232:239], v[82:85], v188, v188 op_sel_hi:[0,0,0]
	v_mfma_scale_f32_16x16x128_f8f6f4 v[74:77], v[208:215], v[242:249], v[74:77], v188, v188 op_sel_hi:[0,0,0]
	v_mfma_scale_f32_16x16x128_f8f6f4 v[78:81], v[200:207], v[242:249], v[78:81], v188, v188 op_sel_hi:[0,0,0]
	v_mfma_scale_f32_16x16x128_f8f6f4 v[86:89], v[200:207], v[232:239], v[86:89], v188, v188 op_sel_hi:[0,0,0]
	v_mfma_scale_f32_16x16x128_f8f6f4 v[94:97], v[200:207], v[224:231], v[94:97], v188, v188 op_sel_hi:[0,0,0]
	v_mfma_scale_f32_16x16x128_f8f6f4 v[102:105], v[200:207], v[216:223], v[102:105], v188, v188 op_sel_hi:[0,0,0]
	s_setprio 0
	s_barrier
	s_mov_b32 m0, s70
	v_lshl_add_u64 v[174:175], v[174:175], 0, s[18:19]
	s_add_u32 s48, s48, 0x80080
	ds_read_b128 v[216:219], v190 offset:49152
	ds_read_b128 v[220:223], v190 offset:50176
	ds_read_b128 v[224:227], v190 offset:51200
	ds_read_b128 v[228:231], v190 offset:52224
	ds_read_b128 v[232:235], v190 offset:53248
	ds_read_b128 v[236:239], v190 offset:54272
	ds_read_b128 v[242:245], v190 offset:55296
	ds_read_b128 v[246:249], v190 offset:56320
	global_load_lds_dwordx4 v[174:175], off
	v_lshl_add_u64 v[174:175], v[176:177], 0, s[18:19]
	s_mov_b32 m0, s71
	s_addc_u32 s49, s49, 0
	global_load_lds_dwordx4 v[174:175], off
	v_lshl_add_u64 v[174:175], s[48:49], 0, v[156:157]
	s_mov_b32 m0, s74
	s_nop 0
	global_load_lds_dwordx4 v[174:175], off
	v_lshl_add_u64 v[174:175], s[48:49], 0, v[160:161]
	s_mov_b32 m0, s75
	s_nop 0
	global_load_lds_dwordx4 v[174:175], off
	v_lshl_add_u64 v[174:175], v[182:183], 0, s[18:19]
	s_mov_b32 m0, s72
	s_nop 0
	global_load_lds_dwordx4 v[174:175], off
	v_lshl_add_u64 v[174:175], v[184:185], 0, s[18:19]
	s_mov_b32 m0, s73
	s_nop 0
	global_load_lds_dwordx4 v[174:175], off
	s_waitcnt vmcnt(8)
	s_waitcnt lgkmcnt(0)
	s_barrier
	s_setprio 1
	s_waitcnt lgkmcnt(0)
	v_mfma_scale_f32_16x16x128_f8f6f4 v[70:73], v[2:9], v[216:223], v[70:73], v188, v188 op_sel_hi:[0,0,0]
	v_mfma_scale_f32_16x16x128_f8f6f4 v[62:65], v[2:9], v[224:231], v[62:65], v188, v188 op_sel_hi:[0,0,0]
	v_mfma_scale_f32_16x16x128_f8f6f4 v[54:57], v[2:9], v[232:239], v[54:57], v188, v188 op_sel_hi:[0,0,0]
	v_mfma_scale_f32_16x16x128_f8f6f4 v[46:49], v[2:9], v[242:249], v[46:49], v188, v188 op_sel_hi:[0,0,0]
	v_mfma_scale_f32_16x16x128_f8f6f4 v[42:45], v[192:199], v[242:249], v[42:45], v188, v188 op_sel_hi:[0,0,0]
	v_mfma_scale_f32_16x16x128_f8f6f4 v[50:53], v[192:199], v[232:239], v[50:53], v188, v188 op_sel_hi:[0,0,0]
	v_mfma_scale_f32_16x16x128_f8f6f4 v[58:61], v[192:199], v[224:231], v[58:61], v188, v188 op_sel_hi:[0,0,0]
	v_mfma_scale_f32_16x16x128_f8f6f4 v[66:69], v[192:199], v[216:223], v[66:69], v188, v188 op_sel_hi:[0,0,0]
	s_setprio 0
	s_setprio 1
	v_mfma_scale_f32_16x16x128_f8f6f4 v[34:37], v[208:215], v[216:223], v[34:37], v188, v188 op_sel_hi:[0,0,0]
	v_mfma_scale_f32_16x16x128_f8f6f4 v[26:29], v[208:215], v[224:231], v[26:29], v188, v188 op_sel_hi:[0,0,0]
	v_mfma_scale_f32_16x16x128_f8f6f4 v[18:21], v[208:215], v[232:239], v[18:21], v188, v188 op_sel_hi:[0,0,0]
	v_mfma_scale_f32_16x16x128_f8f6f4 v[10:13], v[208:215], v[242:249], v[10:13], v188, v188 op_sel_hi:[0,0,0]
	v_mfma_scale_f32_16x16x128_f8f6f4 v[14:17], v[200:207], v[242:249], v[14:17], v188, v188 op_sel_hi:[0,0,0]
	v_mfma_scale_f32_16x16x128_f8f6f4 v[22:25], v[200:207], v[232:239], v[22:25], v188, v188 op_sel_hi:[0,0,0]
	v_mfma_scale_f32_16x16x128_f8f6f4 v[30:33], v[200:207], v[224:231], v[30:33], v188, v188 op_sel_hi:[0,0,0]
	v_mfma_scale_f32_16x16x128_f8f6f4 v[38:41], v[200:207], v[216:223], v[38:41], v188, v188 op_sel_hi:[0,0,0]
	s_setprio 0
	s_barrier
	s_cmp_lt_u32 s86, 3
	s_cbranch_scc1 .LBB0_796
	s_add_u32 s48, s55, s62
	s_addc_u32 s49, s61, s41
	s_add_u32 s46, s46, 0x80180
	s_addc_u32 s47, s47, 0
	s_add_u32 s41, s44, 0x200
	v_lshl_add_u64 v[174:175], v[172:173], 2, s[48:49]
	s_addc_u32 s50, s45, 0
	s_mov_b32 s51, 4
	s_cmp_eq_u32 s86, s51
	s_cselect_b64 s[44:45], -1, 0
	s_cmp_lg_u32 s86, s51
	s_cbranch_scc1 .LBB0_794

.LBB0_794:
	ds_read_b128 v[2:5], v189
	ds_read_b128 v[6:9], v189 offset:1024
	ds_read_b128 v[192:195], v189 offset:2048
	ds_read_b128 v[196:199], v189 offset:3072
	ds_read_b128 v[200:203], v189 offset:16384
	ds_read_b128 v[204:207], v189 offset:17408
	ds_read_b128 v[208:211], v189 offset:18432
	ds_read_b128 v[212:215], v189 offset:19456
	s_add_u32 s48, s46, 0xfff80080
	s_addc_u32 s49, s47, -1
	s_and_b64 s[44:45], s[44:45], exec
	s_cselect_b32 s44, s4, s41
	s_cselect_b32 s49, s1, s49
	s_cselect_b32 s48, s0, s48
	s_cselect_b32 s45, s5, s50
	s_mov_b32 m0, s37
	v_lshl_add_u64 v[176:177], s[46:47], 0, v[162:163]
	ds_read_b128 v[216:219], v190
	ds_read_b128 v[220:223], v190 offset:1024
	ds_read_b128 v[224:227], v190 offset:2048
	ds_read_b128 v[228:231], v190 offset:3072
	ds_read_b128 v[232:235], v190 offset:4096
	ds_read_b128 v[236:239], v190 offset:5120
	ds_read_b128 v[242:245], v190 offset:6144
	ds_read_b128 v[246:249], v190 offset:7168
	global_load_lds_dwordx4 v[176:177], off
	v_lshl_add_u64 v[176:177], s[46:47], 0, v[164:165]
	s_mov_b32 m0, s39
	s_nop 0
	global_load_lds_dwordx4 v[176:177], off
	s_waitcnt vmcnt(8)
	s_waitcnt lgkmcnt(0)
	s_barrier
	s_setprio 1
	s_waitcnt lgkmcnt(0)
	v_mfma_scale_f32_16x16x128_f8f6f4 v[134:137], v[2:9], v[216:223], v[134:137], v188, v188 op_sel_hi:[0,0,0]
	v_mfma_scale_f32_16x16x128_f8f6f4 v[126:129], v[2:9], v[224:231], v[126:129], v188, v188 op_sel_hi:[0,0,0]
	v_mfma_scale_f32_16x16x128_f8f6f4 v[118:121], v[2:9], v[232:239], v[118:121], v188, v188 op_sel_hi:[0,0,0]
	v_mfma_scale_f32_16x16x128_f8f6f4 v[110:113], v[2:9], v[242:249], v[110:113], v188, v188 op_sel_hi:[0,0,0]
	v_mfma_scale_f32_16x16x128_f8f6f4 v[106:109], v[192:199], v[242:249], v[106:109], v188, v188 op_sel_hi:[0,0,0]
	v_mfma_scale_f32_16x16x128_f8f6f4 v[114:117], v[192:199], v[232:239], v[114:117], v188, v188 op_sel_hi:[0,0,0]
	v_mfma_scale_f32_16x16x128_f8f6f4 v[122:125], v[192:199], v[224:231], v[122:125], v188, v188 op_sel_hi:[0,0,0]
	v_mfma_scale_f32_16x16x128_f8f6f4 v[130:133], v[192:199], v[216:223], v[130:133], v188, v188 op_sel_hi:[0,0,0]
	s_setprio 0
	s_setprio 1
	v_mfma_scale_f32_16x16x128_f8f6f4 v[98:101], v[208:215], v[216:223], v[98:101], v188, v188 op_sel_hi:[0,0,0]
	v_mfma_scale_f32_16x16x128_f8f6f4 v[90:93], v[208:215], v[224:231], v[90:93], v188, v188 op_sel_hi:[0,0,0]
	v_mfma_scale_f32_16x16x128_f8f6f4 v[82:85], v[208:215], v[232:239], v[82:85], v188, v188 op_sel_hi:[0,0,0]
	v_mfma_scale_f32_16x16x128_f8f6f4 v[74:77], v[208:215], v[242:249], v[74:77], v188, v188 op_sel_hi:[0,0,0]
	v_mfma_scale_f32_16x16x128_f8f6f4 v[78:81], v[200:207], v[242:249], v[78:81], v188, v188 op_sel_hi:[0,0,0]
	v_mfma_scale_f32_16x16x128_f8f6f4 v[86:89], v[200:207], v[232:239], v[86:89], v188, v188 op_sel_hi:[0,0,0]
	v_mfma_scale_f32_16x16x128_f8f6f4 v[94:97], v[200:207], v[224:231], v[94:97], v188, v188 op_sel_hi:[0,0,0]
	v_mfma_scale_f32_16x16x128_f8f6f4 v[102:105], v[200:207], v[216:223], v[102:105], v188, v188 op_sel_hi:[0,0,0]
	s_setprio 0
	s_barrier
	s_mov_b32 m0, s9
	v_lshl_add_u64 v[176:177], s[44:45], 0, v[156:157]
	s_add_u32 s62, s44, 0x80000
	ds_read_b128 v[216:219], v190 offset:16384
	ds_read_b128 v[220:223], v190 offset:17408
	ds_read_b128 v[224:227], v190 offset:18432
	ds_read_b128 v[228:231], v190 offset:19456
	ds_read_b128 v[232:235], v190 offset:20480
	ds_read_b128 v[236:239], v190 offset:21504
	ds_read_b128 v[242:245], v190 offset:22528
	ds_read_b128 v[246:249], v190 offset:23552
	global_load_lds_dwordx4 v[176:177], off
	v_lshl_add_u64 v[182:183], s[44:45], 0, v[160:161]
	s_mov_b32 m0, s27
	s_addc_u32 s63, s45, 0
	global_load_lds_dwordx4 v[182:183], off
	v_lshl_add_u64 v[184:185], s[62:63], 0, v[156:157]
	s_mov_b32 m0, s33
	v_lshl_add_u64 v[186:187], s[48:49], 0, v[158:159]
	global_load_lds_dwordx4 v[184:185], off
	v_lshl_add_u64 v[184:185], s[62:63], 0, v[160:161]
	s_mov_b32 m0, s35
	s_nop 0
	global_load_lds_dwordx4 v[184:185], off
	v_lshl_add_u64 v[184:185], s[48:49], 0, v[154:155]
	s_mov_b32 m0, s8
	s_nop 0
	global_load_lds_dwordx4 v[184:185], off
	s_mov_b32 m0, s43
	s_nop 0
	global_load_lds_dwordx4 v[186:187], off
	s_waitcnt vmcnt(8)
	s_waitcnt lgkmcnt(0)
	s_barrier
	s_setprio 1
	s_waitcnt lgkmcnt(0)
	v_mfma_scale_f32_16x16x128_f8f6f4 v[70:73], v[2:9], v[216:223], v[70:73], v188, v188 op_sel_hi:[0,0,0]
	v_mfma_scale_f32_16x16x128_f8f6f4 v[62:65], v[2:9], v[224:231], v[62:65], v188, v188 op_sel_hi:[0,0,0]
	v_mfma_scale_f32_16x16x128_f8f6f4 v[54:57], v[2:9], v[232:239], v[54:57], v188, v188 op_sel_hi:[0,0,0]
	v_mfma_scale_f32_16x16x128_f8f6f4 v[46:49], v[2:9], v[242:249], v[46:49], v188, v188 op_sel_hi:[0,0,0]
	v_mfma_scale_f32_16x16x128_f8f6f4 v[42:45], v[192:199], v[242:249], v[42:45], v188, v188 op_sel_hi:[0,0,0]
	v_mfma_scale_f32_16x16x128_f8f6f4 v[50:53], v[192:199], v[232:239], v[50:53], v188, v188 op_sel_hi:[0,0,0]
	v_mfma_scale_f32_16x16x128_f8f6f4 v[58:61], v[192:199], v[224:231], v[58:61], v188, v188 op_sel_hi:[0,0,0]
	v_mfma_scale_f32_16x16x128_f8f6f4 v[66:69], v[192:199], v[216:223], v[66:69], v188, v188 op_sel_hi:[0,0,0]
	s_setprio 0
	s_setprio 1
	v_mfma_scale_f32_16x16x128_f8f6f4 v[34:37], v[208:215], v[216:223], v[34:37], v188, v188 op_sel_hi:[0,0,0]
	v_mfma_scale_f32_16x16x128_f8f6f4 v[26:29], v[208:215], v[224:231], v[26:29], v188, v188 op_sel_hi:[0,0,0]
	v_mfma_scale_f32_16x16x128_f8f6f4 v[18:21], v[208:215], v[232:239], v[18:21], v188, v188 op_sel_hi:[0,0,0]
	v_mfma_scale_f32_16x16x128_f8f6f4 v[10:13], v[208:215], v[242:249], v[10:13], v188, v188 op_sel_hi:[0,0,0]
	v_mfma_scale_f32_16x16x128_f8f6f4 v[14:17], v[200:207], v[242:249], v[14:17], v188, v188 op_sel_hi:[0,0,0]
	v_mfma_scale_f32_16x16x128_f8f6f4 v[22:25], v[200:207], v[232:239], v[22:25], v188, v188 op_sel_hi:[0,0,0]
	v_mfma_scale_f32_16x16x128_f8f6f4 v[30:33], v[200:207], v[224:231], v[30:33], v188, v188 op_sel_hi:[0,0,0]
	v_mfma_scale_f32_16x16x128_f8f6f4 v[38:41], v[200:207], v[216:223], v[38:41], v188, v188 op_sel_hi:[0,0,0]
	s_setprio 0
	s_barrier
	ds_read_b128 v[192:195], v189 offset:32768
	ds_read_b128 v[196:199], v189 offset:33792
	ds_read_b128 v[200:203], v189 offset:34816
	ds_read_b128 v[204:207], v189 offset:35840
	ds_read_b128 v[2:5], v189 offset:49152
	ds_read_b128 v[6:9], v189 offset:50176
	ds_read_b128 v[208:211], v189 offset:51200
	ds_read_b128 v[212:215], v189 offset:52224
	s_add_u32 s48, s48, 0x80000
	s_addc_u32 s49, s49, 0
	s_mov_b32 m0, s52
	v_lshl_add_u64 v[252:253], s[48:49], 0, v[154:155]
	ds_read_b128 v[216:219], v190 offset:32768
	ds_read_b128 v[220:223], v190 offset:33792
	ds_read_b128 v[224:227], v190 offset:34816
	ds_read_b128 v[228:231], v190 offset:35840
	ds_read_b128 v[232:235], v190 offset:36864
	ds_read_b128 v[236:239], v190 offset:37888
	ds_read_b128 v[242:245], v190 offset:38912
	ds_read_b128 v[246:249], v190 offset:39936
	global_load_lds_dwordx4 v[252:253], off
	v_lshl_add_u64 v[252:253], s[48:49], 0, v[158:159]
	s_mov_b32 m0, s53
	s_nop 0
	global_load_lds_dwordx4 v[252:253], off
	s_waitcnt vmcnt(8)
	s_waitcnt lgkmcnt(0)
	s_barrier
	s_setprio 1
	s_waitcnt lgkmcnt(0)
	v_mfma_scale_f32_16x16x128_f8f6f4 v[134:137], v[192:199], v[216:223], v[134:137], v188, v188 op_sel_hi:[0,0,0]
	v_mfma_scale_f32_16x16x128_f8f6f4 v[126:129], v[192:199], v[224:231], v[126:129], v188, v188 op_sel_hi:[0,0,0]
	v_mfma_scale_f32_16x16x128_f8f6f4 v[118:121], v[192:199], v[232:239], v[118:121], v188, v188 op_sel_hi:[0,0,0]
	v_mfma_scale_f32_16x16x128_f8f6f4 v[110:113], v[192:199], v[242:249], v[110:113], v188, v188 op_sel_hi:[0,0,0]
	v_mfma_scale_f32_16x16x128_f8f6f4 v[106:109], v[200:207], v[242:249], v[106:109], v188, v188 op_sel_hi:[0,0,0]
	v_mfma_scale_f32_16x16x128_f8f6f4 v[114:117], v[200:207], v[232:239], v[114:117], v188, v188 op_sel_hi:[0,0,0]
	v_mfma_scale_f32_16x16x128_f8f6f4 v[122:125], v[200:207], v[224:231], v[122:125], v188, v188 op_sel_hi:[0,0,0]
	v_mfma_scale_f32_16x16x128_f8f6f4 v[130:133], v[200:207], v[216:223], v[130:133], v188, v188 op_sel_hi:[0,0,0]
	s_setprio 0
	s_setprio 1
	v_mfma_scale_f32_16x16x128_f8f6f4 v[98:101], v[208:215], v[216:223], v[98:101], v188, v188 op_sel_hi:[0,0,0]
	v_mfma_scale_f32_16x16x128_f8f6f4 v[90:93], v[208:215], v[224:231], v[90:93], v188, v188 op_sel_hi:[0,0,0]
	v_mfma_scale_f32_16x16x128_f8f6f4 v[82:85], v[208:215], v[232:239], v[82:85], v188, v188 op_sel_hi:[0,0,0]
	v_mfma_scale_f32_16x16x128_f8f6f4 v[74:77], v[208:215], v[242:249], v[74:77], v188, v188 op_sel_hi:[0,0,0]
	v_mfma_scale_f32_16x16x128_f8f6f4 v[78:81], v[2:9], v[242:249], v[78:81], v188, v188 op_sel_hi:[0,0,0]
	v_mfma_scale_f32_16x16x128_f8f6f4 v[86:89], v[2:9], v[232:239], v[86:89], v188, v188 op_sel_hi:[0,0,0]
	v_mfma_scale_f32_16x16x128_f8f6f4 v[94:97], v[2:9], v[224:231], v[94:97], v188, v188 op_sel_hi:[0,0,0]
	v_mfma_scale_f32_16x16x128_f8f6f4 v[102:105], v[2:9], v[216:223], v[102:105], v188, v188 op_sel_hi:[0,0,0]
	s_setprio 0
	s_barrier
	s_mov_b32 m0, s70
	v_lshl_add_u64 v[176:177], v[176:177], 0, s[18:19]
	s_add_u32 s44, s44, 0x80080
	ds_read_b128 v[216:219], v190 offset:49152
	ds_read_b128 v[220:223], v190 offset:50176
	ds_read_b128 v[224:227], v190 offset:51200
	ds_read_b128 v[228:231], v190 offset:52224
	ds_read_b128 v[232:235], v190 offset:53248
	ds_read_b128 v[236:239], v190 offset:54272
	ds_read_b128 v[242:245], v190 offset:55296
	ds_read_b128 v[246:249], v190 offset:56320
	global_load_lds_dwordx4 v[176:177], off
	v_lshl_add_u64 v[176:177], v[182:183], 0, s[18:19]
	s_mov_b32 m0, s71
	s_addc_u32 s45, s45, 0
	global_load_lds_dwordx4 v[176:177], off
	v_lshl_add_u64 v[176:177], s[44:45], 0, v[156:157]
	s_mov_b32 m0, s74
	s_nop 0
	global_load_lds_dwordx4 v[176:177], off
	v_lshl_add_u64 v[176:177], s[44:45], 0, v[160:161]
	s_mov_b32 m0, s75
	s_nop 0
	global_load_lds_dwordx4 v[176:177], off
	v_lshl_add_u64 v[176:177], v[184:185], 0, s[18:19]
	s_mov_b32 m0, s72
	s_nop 0
	global_load_lds_dwordx4 v[176:177], off
	v_lshl_add_u64 v[176:177], v[186:187], 0, s[18:19]
	s_mov_b32 m0, s73
	s_nop 0
	global_load_lds_dwordx4 v[176:177], off
	s_waitcnt vmcnt(8)
	s_waitcnt lgkmcnt(0)
	s_barrier
	s_setprio 1
	s_waitcnt lgkmcnt(0)
	v_mfma_scale_f32_16x16x128_f8f6f4 v[70:73], v[192:199], v[216:223], v[70:73], v188, v188 op_sel_hi:[0,0,0]
	v_mfma_scale_f32_16x16x128_f8f6f4 v[62:65], v[192:199], v[224:231], v[62:65], v188, v188 op_sel_hi:[0,0,0]
	v_mfma_scale_f32_16x16x128_f8f6f4 v[54:57], v[192:199], v[232:239], v[54:57], v188, v188 op_sel_hi:[0,0,0]
	v_mfma_scale_f32_16x16x128_f8f6f4 v[46:49], v[192:199], v[242:249], v[46:49], v188, v188 op_sel_hi:[0,0,0]
	v_mfma_scale_f32_16x16x128_f8f6f4 v[42:45], v[200:207], v[242:249], v[42:45], v188, v188 op_sel_hi:[0,0,0]
	v_mfma_scale_f32_16x16x128_f8f6f4 v[50:53], v[200:207], v[232:239], v[50:53], v188, v188 op_sel_hi:[0,0,0]
	v_mfma_scale_f32_16x16x128_f8f6f4 v[58:61], v[200:207], v[224:231], v[58:61], v188, v188 op_sel_hi:[0,0,0]
	v_mfma_scale_f32_16x16x128_f8f6f4 v[66:69], v[200:207], v[216:223], v[66:69], v188, v188 op_sel_hi:[0,0,0]
	s_setprio 0
	s_setprio 1
	v_mfma_scale_f32_16x16x128_f8f6f4 v[34:37], v[208:215], v[216:223], v[34:37], v188, v188 op_sel_hi:[0,0,0]
	v_mfma_scale_f32_16x16x128_f8f6f4 v[26:29], v[208:215], v[224:231], v[26:29], v188, v188 op_sel_hi:[0,0,0]
	v_mfma_scale_f32_16x16x128_f8f6f4 v[18:21], v[208:215], v[232:239], v[18:21], v188, v188 op_sel_hi:[0,0,0]
	v_mfma_scale_f32_16x16x128_f8f6f4 v[10:13], v[208:215], v[242:249], v[10:13], v188, v188 op_sel_hi:[0,0,0]
	v_mfma_scale_f32_16x16x128_f8f6f4 v[14:17], v[2:9], v[242:249], v[14:17], v188, v188 op_sel_hi:[0,0,0]
	v_mfma_scale_f32_16x16x128_f8f6f4 v[22:25], v[2:9], v[232:239], v[22:25], v188, v188 op_sel_hi:[0,0,0]
	v_mfma_scale_f32_16x16x128_f8f6f4 v[30:33], v[2:9], v[224:231], v[30:33], v188, v188 op_sel_hi:[0,0,0]
	v_mfma_scale_f32_16x16x128_f8f6f4 v[38:41], v[2:9], v[216:223], v[38:41], v188, v188 op_sel_hi:[0,0,0]
	s_setprio 0
	s_barrier
	s_add_i32 s44, s51, 2
	s_add_u32 s46, s46, 0x100
	s_addc_u32 s47, s47, 0
	s_add_u32 s41, s41, 0x100
	s_addc_u32 s50, s50, 0
	s_cmp_ge_i32 s51, s86
	s_cbranch_scc1 .LBB0_796
	s_mov_b32 s51, s44
	s_cmp_eq_u32 s86, s51
	s_cselect_b64 s[44:45], -1, 0
	s_cmp_lg_u32 s86, s51
	s_cbranch_scc0 .LBB0_793
	s_branch .LBB0_794

.LBB0_946:
	s_ashr_i32 s37, s36, 31
	ds_read_b128 v[18:21], v192
	ds_read_b128 v[22:25], v192 offset:1024
	ds_read_b128 v[26:29], v192 offset:2048
	ds_read_b128 v[30:33], v192 offset:3072
	ds_read_b128 v[2:5], v192 offset:16384
	ds_read_b128 v[6:9], v192 offset:17408
	ds_read_b128 v[10:13], v192 offset:18432
	ds_read_b128 v[14:17], v192 offset:19456
	s_lshl_b64 s[38:39], s[36:37], 20
	s_add_u32 s38, s22, s38
	s_addc_u32 s39, s23, s39
	s_and_b64 s[40:41], s[2:3], exec
	s_cselect_b32 s37, s39, s47
	s_cselect_b32 s84, s38, s46
	s_ashr_i32 s27, s26, 31
	s_lshl_b64 s[40:41], s[26:27], 20
	s_add_u32 s40, s25, s40
	s_addc_u32 s41, s35, s41
	s_and_b64 s[48:49], s[2:3], exec
	s_cselect_b32 s27, s41, s45
	s_cselect_b32 s85, s40, s44
	s_add_u32 s48, s46, 0x80080
	s_addc_u32 s49, s47, 0
	s_mov_b32 m0, s80
	v_lshl_add_u64 v[218:219], s[48:49], 0, v[164:165]
	ds_read_b128 v[184:187], v193
	ds_read_b128 v[188:191], v193 offset:1024
	ds_read_b128 v[194:197], v193 offset:2048
	ds_read_b128 v[198:201], v193 offset:3072
	ds_read_b128 v[202:205], v193 offset:4096
	ds_read_b128 v[206:209], v193 offset:5120
	ds_read_b128 v[210:213], v193 offset:6144
	ds_read_b128 v[214:217], v193 offset:7168
	global_load_lds_dwordx4 v[218:219], off
	v_lshl_add_u64 v[218:219], s[48:49], 0, v[168:169]
	s_mov_b32 m0, s81
	s_nop 0
	global_load_lds_dwordx4 v[218:219], off
	s_waitcnt vmcnt(8)
	s_waitcnt lgkmcnt(0)
	s_barrier
	s_setprio 1
	s_waitcnt lgkmcnt(0)
	v_mfma_scale_f32_16x16x128_f8f6f4 v[158:161], v[18:25], v[184:191], 0, v181, v181 op_sel_hi:[0,0,0]
	v_mfma_scale_f32_16x16x128_f8f6f4 v[150:153], v[18:25], v[194:201], 0, v181, v181 op_sel_hi:[0,0,0]
	v_mfma_scale_f32_16x16x128_f8f6f4 v[142:145], v[18:25], v[202:209], 0, v181, v181 op_sel_hi:[0,0,0]
	v_mfma_scale_f32_16x16x128_f8f6f4 v[134:137], v[18:25], v[210:217], 0, v181, v181 op_sel_hi:[0,0,0]
	v_mfma_scale_f32_16x16x128_f8f6f4 v[130:133], v[26:33], v[210:217], 0, v181, v181 op_sel_hi:[0,0,0]
	v_mfma_scale_f32_16x16x128_f8f6f4 v[138:141], v[26:33], v[202:209], 0, v181, v181 op_sel_hi:[0,0,0]
	v_mfma_scale_f32_16x16x128_f8f6f4 v[146:149], v[26:33], v[194:201], 0, v181, v181 op_sel_hi:[0,0,0]
	v_mfma_scale_f32_16x16x128_f8f6f4 v[154:157], v[26:33], v[184:191], 0, v181, v181 op_sel_hi:[0,0,0]
	s_setprio 0
	s_setprio 1
	v_mfma_scale_f32_16x16x128_f8f6f4 v[122:125], v[10:17], v[184:191], 0, v181, v181 op_sel_hi:[0,0,0]
	v_mfma_scale_f32_16x16x128_f8f6f4 v[114:117], v[10:17], v[194:201], 0, v181, v181 op_sel_hi:[0,0,0]
	v_mfma_scale_f32_16x16x128_f8f6f4 v[106:109], v[10:17], v[202:209], 0, v181, v181 op_sel_hi:[0,0,0]
	v_mfma_scale_f32_16x16x128_f8f6f4 v[98:101], v[10:17], v[210:217], 0, v181, v181 op_sel_hi:[0,0,0]
	v_mfma_scale_f32_16x16x128_f8f6f4 v[102:105], v[2:9], v[210:217], 0, v181, v181 op_sel_hi:[0,0,0]
	v_mfma_scale_f32_16x16x128_f8f6f4 v[110:113], v[2:9], v[202:209], 0, v181, v181 op_sel_hi:[0,0,0]
	v_mfma_scale_f32_16x16x128_f8f6f4 v[118:121], v[2:9], v[194:201], 0, v181, v181 op_sel_hi:[0,0,0]
	v_mfma_scale_f32_16x16x128_f8f6f4 v[126:129], v[2:9], v[184:191], 0, v181, v181 op_sel_hi:[0,0,0]
	s_setprio 0
	s_barrier
	v_lshl_add_u64 v[184:185], s[44:45], 0, v[166:167]
	s_mov_b32 m0, s52
	v_lshl_add_u64 v[186:187], v[184:185], 0, s[14:15]
	ds_read_b128 v[194:197], v193 offset:16384
	ds_read_b128 v[198:201], v193 offset:17408
	ds_read_b128 v[202:205], v193 offset:18432
	ds_read_b128 v[206:209], v193 offset:19456
	ds_read_b128 v[210:213], v193 offset:20480
	ds_read_b128 v[214:217], v193 offset:21504
	ds_read_b128 v[218:221], v193 offset:22528
	ds_read_b128 v[222:225], v193 offset:23552
	global_load_lds_dwordx4 v[186:187], off
	v_lshl_add_u64 v[186:187], s[44:45], 0, v[170:171]
	s_add_u32 s48, s44, 0x80100
	v_lshl_add_u64 v[188:189], v[186:187], 0, s[14:15]
	s_mov_b32 m0, s53
	s_addc_u32 s49, s45, 0
	global_load_lds_dwordx4 v[188:189], off
	v_lshl_add_u64 v[188:189], s[48:49], 0, v[166:167]
	s_mov_b32 m0, s54
	s_nop 0
	global_load_lds_dwordx4 v[188:189], off
	v_lshl_add_u64 v[188:189], s[48:49], 0, v[170:171]
	s_mov_b32 m0, s55
	s_nop 0
	global_load_lds_dwordx4 v[188:189], off
	v_lshl_add_u64 v[188:189], s[46:47], 0, v[164:165]
	v_lshl_add_u64 v[190:191], v[188:189], 0, s[14:15]
	s_mov_b32 m0, s43
	s_nop 0
	global_load_lds_dwordx4 v[190:191], off
	v_lshl_add_u64 v[190:191], s[46:47], 0, v[168:169]
	v_lshl_add_u64 v[226:227], v[190:191], 0, s[14:15]
	s_mov_b32 m0, s61
	s_nop 0
	global_load_lds_dwordx4 v[226:227], off
	s_waitcnt vmcnt(8)
	s_waitcnt lgkmcnt(0)
	s_barrier
	s_setprio 1
	s_waitcnt lgkmcnt(0)
	v_mfma_scale_f32_16x16x128_f8f6f4 v[94:97], v[18:25], v[194:201], 0, v181, v181 op_sel_hi:[0,0,0]
	v_mfma_scale_f32_16x16x128_f8f6f4 v[86:89], v[18:25], v[202:209], 0, v181, v181 op_sel_hi:[0,0,0]
	v_mfma_scale_f32_16x16x128_f8f6f4 v[78:81], v[18:25], v[210:217], 0, v181, v181 op_sel_hi:[0,0,0]
	v_mfma_scale_f32_16x16x128_f8f6f4 v[70:73], v[18:25], v[218:225], 0, v181, v181 op_sel_hi:[0,0,0]
	v_mfma_scale_f32_16x16x128_f8f6f4 v[66:69], v[26:33], v[218:225], 0, v181, v181 op_sel_hi:[0,0,0]
	v_mfma_scale_f32_16x16x128_f8f6f4 v[74:77], v[26:33], v[210:217], 0, v181, v181 op_sel_hi:[0,0,0]
	v_mfma_scale_f32_16x16x128_f8f6f4 v[82:85], v[26:33], v[202:209], 0, v181, v181 op_sel_hi:[0,0,0]
	v_mfma_scale_f32_16x16x128_f8f6f4 v[90:93], v[26:33], v[194:201], 0, v181, v181 op_sel_hi:[0,0,0]
	s_setprio 0
	s_setprio 1
	v_mfma_scale_f32_16x16x128_f8f6f4 v[58:61], v[10:17], v[194:201], 0, v181, v181 op_sel_hi:[0,0,0]
	v_mfma_scale_f32_16x16x128_f8f6f4 v[50:53], v[10:17], v[202:209], 0, v181, v181 op_sel_hi:[0,0,0]
	v_mfma_scale_f32_16x16x128_f8f6f4 v[42:45], v[10:17], v[210:217], 0, v181, v181 op_sel_hi:[0,0,0]
	v_mfma_scale_f32_16x16x128_f8f6f4 v[34:37], v[10:17], v[218:225], 0, v181, v181 op_sel_hi:[0,0,0]
	v_mfma_scale_f32_16x16x128_f8f6f4 v[38:41], v[2:9], v[218:225], 0, v181, v181 op_sel_hi:[0,0,0]
	v_mfma_scale_f32_16x16x128_f8f6f4 v[46:49], v[2:9], v[210:217], 0, v181, v181 op_sel_hi:[0,0,0]
	v_mfma_scale_f32_16x16x128_f8f6f4 v[54:57], v[2:9], v[202:209], 0, v181, v181 op_sel_hi:[0,0,0]
	v_mfma_scale_f32_16x16x128_f8f6f4 v[62:65], v[2:9], v[194:201], 0, v181, v181 op_sel_hi:[0,0,0]
	s_setprio 0
	s_barrier
	ds_read_b128 v[18:21], v192 offset:32768
	ds_read_b128 v[22:25], v192 offset:33792
	ds_read_b128 v[26:29], v192 offset:34816
	ds_read_b128 v[30:33], v192 offset:35840
	ds_read_b128 v[2:5], v192 offset:49152
	ds_read_b128 v[6:9], v192 offset:50176
	ds_read_b128 v[10:13], v192 offset:51200
	ds_read_b128 v[14:17], v192 offset:52224
	s_add_u32 s48, s46, 0x80100
	s_addc_u32 s49, s47, 0
	s_mov_b32 m0, s68
	v_lshl_add_u64 v[226:227], s[48:49], 0, v[164:165]
	ds_read_b128 v[194:197], v193 offset:32768
	ds_read_b128 v[198:201], v193 offset:33792
	ds_read_b128 v[202:205], v193 offset:34816
	ds_read_b128 v[206:209], v193 offset:35840
	ds_read_b128 v[210:213], v193 offset:36864
	ds_read_b128 v[214:217], v193 offset:37888
	ds_read_b128 v[218:221], v193 offset:38912
	ds_read_b128 v[222:225], v193 offset:39936
	global_load_lds_dwordx4 v[226:227], off
	v_lshl_add_u64 v[226:227], s[48:49], 0, v[168:169]
	s_mov_b32 m0, s69
	s_nop 0
	global_load_lds_dwordx4 v[226:227], off
	s_waitcnt vmcnt(8)
	s_waitcnt lgkmcnt(0)
	s_barrier
	s_setprio 1
	s_waitcnt lgkmcnt(0)
	v_mfma_scale_f32_16x16x128_f8f6f4 v[158:161], v[18:25], v[194:201], v[158:161], v181, v181 op_sel_hi:[0,0,0]
	v_mfma_scale_f32_16x16x128_f8f6f4 v[150:153], v[18:25], v[202:209], v[150:153], v181, v181 op_sel_hi:[0,0,0]
	v_mfma_scale_f32_16x16x128_f8f6f4 v[142:145], v[18:25], v[210:217], v[142:145], v181, v181 op_sel_hi:[0,0,0]
	v_mfma_scale_f32_16x16x128_f8f6f4 v[134:137], v[18:25], v[218:225], v[134:137], v181, v181 op_sel_hi:[0,0,0]
	v_mfma_scale_f32_16x16x128_f8f6f4 v[130:133], v[26:33], v[218:225], v[130:133], v181, v181 op_sel_hi:[0,0,0]
	v_mfma_scale_f32_16x16x128_f8f6f4 v[138:141], v[26:33], v[210:217], v[138:141], v181, v181 op_sel_hi:[0,0,0]
	v_mfma_scale_f32_16x16x128_f8f6f4 v[146:149], v[26:33], v[202:209], v[146:149], v181, v181 op_sel_hi:[0,0,0]
	v_mfma_scale_f32_16x16x128_f8f6f4 v[154:157], v[26:33], v[194:201], v[154:157], v181, v181 op_sel_hi:[0,0,0]
	s_setprio 0
	s_setprio 1
	v_mfma_scale_f32_16x16x128_f8f6f4 v[122:125], v[10:17], v[194:201], v[122:125], v181, v181 op_sel_hi:[0,0,0]
	v_mfma_scale_f32_16x16x128_f8f6f4 v[114:117], v[10:17], v[202:209], v[114:117], v181, v181 op_sel_hi:[0,0,0]
	v_mfma_scale_f32_16x16x128_f8f6f4 v[106:109], v[10:17], v[210:217], v[106:109], v181, v181 op_sel_hi:[0,0,0]
	v_mfma_scale_f32_16x16x128_f8f6f4 v[98:101], v[10:17], v[218:225], v[98:101], v181, v181 op_sel_hi:[0,0,0]
	v_mfma_scale_f32_16x16x128_f8f6f4 v[102:105], v[2:9], v[218:225], v[102:105], v181, v181 op_sel_hi:[0,0,0]
	v_mfma_scale_f32_16x16x128_f8f6f4 v[110:113], v[2:9], v[210:217], v[110:113], v181, v181 op_sel_hi:[0,0,0]
	v_mfma_scale_f32_16x16x128_f8f6f4 v[118:121], v[2:9], v[202:209], v[118:121], v181, v181 op_sel_hi:[0,0,0]
	v_mfma_scale_f32_16x16x128_f8f6f4 v[126:129], v[2:9], v[194:201], v[126:129], v181, v181 op_sel_hi:[0,0,0]
	s_setprio 0
	s_barrier
	s_mov_b32 m0, s74
	v_lshl_add_u64 v[184:185], v[184:185], 0, s[18:19]
	s_add_u32 s48, s44, 0x80180
	ds_read_b128 v[194:197], v193 offset:49152
	ds_read_b128 v[198:201], v193 offset:50176
	ds_read_b128 v[202:205], v193 offset:51200
	ds_read_b128 v[206:209], v193 offset:52224
	ds_read_b128 v[210:213], v193 offset:53248
	ds_read_b128 v[214:217], v193 offset:54272
	ds_read_b128 v[218:221], v193 offset:55296
	ds_read_b128 v[222:225], v193 offset:56320
	global_load_lds_dwordx4 v[184:185], off
	v_lshl_add_u64 v[184:185], v[186:187], 0, s[18:19]
	s_mov_b32 m0, s75
	s_addc_u32 s49, s45, 0
	global_load_lds_dwordx4 v[184:185], off
	v_lshl_add_u64 v[184:185], s[48:49], 0, v[166:167]
	s_mov_b32 m0, s78
	s_nop 0
	global_load_lds_dwordx4 v[184:185], off
	v_lshl_add_u64 v[184:185], s[48:49], 0, v[170:171]
	s_mov_b32 m0, s79
	s_nop 0
	global_load_lds_dwordx4 v[184:185], off
	v_lshl_add_u64 v[184:185], v[188:189], 0, s[18:19]
	s_mov_b32 m0, s76
	s_nop 0
	global_load_lds_dwordx4 v[184:185], off
	v_lshl_add_u64 v[184:185], v[190:191], 0, s[18:19]
	s_mov_b32 m0, s77
	s_nop 0
	global_load_lds_dwordx4 v[184:185], off
	s_waitcnt vmcnt(8)
	s_waitcnt lgkmcnt(0)
	s_barrier
	s_setprio 1
	s_waitcnt lgkmcnt(0)
	v_mfma_scale_f32_16x16x128_f8f6f4 v[94:97], v[18:25], v[194:201], v[94:97], v181, v181 op_sel_hi:[0,0,0]
	v_mfma_scale_f32_16x16x128_f8f6f4 v[86:89], v[18:25], v[202:209], v[86:89], v181, v181 op_sel_hi:[0,0,0]
	v_mfma_scale_f32_16x16x128_f8f6f4 v[78:81], v[18:25], v[210:217], v[78:81], v181, v181 op_sel_hi:[0,0,0]
	v_mfma_scale_f32_16x16x128_f8f6f4 v[70:73], v[18:25], v[218:225], v[70:73], v181, v181 op_sel_hi:[0,0,0]
	v_mfma_scale_f32_16x16x128_f8f6f4 v[66:69], v[26:33], v[218:225], v[66:69], v181, v181 op_sel_hi:[0,0,0]
	v_mfma_scale_f32_16x16x128_f8f6f4 v[74:77], v[26:33], v[210:217], v[74:77], v181, v181 op_sel_hi:[0,0,0]
	v_mfma_scale_f32_16x16x128_f8f6f4 v[82:85], v[26:33], v[202:209], v[82:85], v181, v181 op_sel_hi:[0,0,0]
	v_mfma_scale_f32_16x16x128_f8f6f4 v[90:93], v[26:33], v[194:201], v[90:93], v181, v181 op_sel_hi:[0,0,0]
	s_setprio 0
	s_setprio 1
	v_mfma_scale_f32_16x16x128_f8f6f4 v[58:61], v[10:17], v[194:201], v[58:61], v181, v181 op_sel_hi:[0,0,0]
	v_mfma_scale_f32_16x16x128_f8f6f4 v[50:53], v[10:17], v[202:209], v[50:53], v181, v181 op_sel_hi:[0,0,0]
	v_mfma_scale_f32_16x16x128_f8f6f4 v[42:45], v[10:17], v[210:217], v[42:45], v181, v181 op_sel_hi:[0,0,0]
	v_mfma_scale_f32_16x16x128_f8f6f4 v[34:37], v[10:17], v[218:225], v[34:37], v181, v181 op_sel_hi:[0,0,0]
	v_mfma_scale_f32_16x16x128_f8f6f4 v[38:41], v[2:9], v[218:225], v[38:41], v181, v181 op_sel_hi:[0,0,0]
	v_mfma_scale_f32_16x16x128_f8f6f4 v[46:49], v[2:9], v[210:217], v[46:49], v181, v181 op_sel_hi:[0,0,0]
	v_mfma_scale_f32_16x16x128_f8f6f4 v[54:57], v[2:9], v[202:209], v[54:57], v181, v181 op_sel_hi:[0,0,0]
	v_mfma_scale_f32_16x16x128_f8f6f4 v[62:65], v[2:9], v[194:201], v[62:65], v181, v181 op_sel_hi:[0,0,0]
	s_setprio 0
	s_barrier
	s_add_u32 s46, s46, 0x80180
	s_addc_u32 s47, s47, 0
	s_add_u32 s62, s44, 0x200
	s_addc_u32 s63, s45, 0
	s_mov_b32 s86, 0
.LBB0_947:
	ds_read_b128 v[2:5], v192
	ds_read_b128 v[6:9], v192 offset:1024
	ds_read_b128 v[18:21], v192 offset:2048
	ds_read_b128 v[22:25], v192 offset:3072
	ds_read_b128 v[26:29], v192 offset:16384
	ds_read_b128 v[30:33], v192 offset:17408
	ds_read_b128 v[184:187], v192 offset:18432
	ds_read_b128 v[188:191], v192 offset:19456
	s_add_u32 s44, s46, 0xfff80080
	s_addc_u32 s45, s47, -1
	s_cmp_eq_u32 s86, 28
	s_cselect_b32 s49, s37, s45
	s_cselect_b32 s48, s84, s44
	s_cselect_b32 s45, s27, s63
	s_cselect_b32 s44, s85, s62
	s_mov_b32 m0, s80
	v_lshl_add_u64 v[218:219], s[46:47], 0, v[172:173]
	ds_read_b128 v[10:13], v193
	ds_read_b128 v[14:17], v193 offset:1024
	ds_read_b128 v[194:197], v193 offset:2048
	ds_read_b128 v[198:201], v193 offset:3072
	ds_read_b128 v[202:205], v193 offset:4096
	ds_read_b128 v[206:209], v193 offset:5120
	ds_read_b128 v[210:213], v193 offset:6144
	ds_read_b128 v[214:217], v193 offset:7168
	global_load_lds_dwordx4 v[218:219], off
	v_lshl_add_u64 v[218:219], s[46:47], 0, v[174:175]
	s_mov_b32 m0, s81
	s_nop 0
	global_load_lds_dwordx4 v[218:219], off
	s_waitcnt vmcnt(8)
	s_waitcnt lgkmcnt(0)
	s_barrier
	s_setprio 1
	s_waitcnt lgkmcnt(0)
	v_mfma_scale_f32_16x16x128_f8f6f4 v[158:161], v[2:9], v[10:17], v[158:161], v181, v181 op_sel_hi:[0,0,0]
	v_mfma_scale_f32_16x16x128_f8f6f4 v[150:153], v[2:9], v[194:201], v[150:153], v181, v181 op_sel_hi:[0,0,0]
	v_mfma_scale_f32_16x16x128_f8f6f4 v[142:145], v[2:9], v[202:209], v[142:145], v181, v181 op_sel_hi:[0,0,0]
	v_mfma_scale_f32_16x16x128_f8f6f4 v[134:137], v[2:9], v[210:217], v[134:137], v181, v181 op_sel_hi:[0,0,0]
	v_mfma_scale_f32_16x16x128_f8f6f4 v[130:133], v[18:25], v[210:217], v[130:133], v181, v181 op_sel_hi:[0,0,0]
	v_mfma_scale_f32_16x16x128_f8f6f4 v[138:141], v[18:25], v[202:209], v[138:141], v181, v181 op_sel_hi:[0,0,0]
	v_mfma_scale_f32_16x16x128_f8f6f4 v[146:149], v[18:25], v[194:201], v[146:149], v181, v181 op_sel_hi:[0,0,0]
	v_mfma_scale_f32_16x16x128_f8f6f4 v[154:157], v[18:25], v[10:17], v[154:157], v181, v181 op_sel_hi:[0,0,0]
	s_setprio 0
	s_setprio 1
	v_mfma_scale_f32_16x16x128_f8f6f4 v[122:125], v[184:191], v[10:17], v[122:125], v181, v181 op_sel_hi:[0,0,0]
	v_mfma_scale_f32_16x16x128_f8f6f4 v[114:117], v[184:191], v[194:201], v[114:117], v181, v181 op_sel_hi:[0,0,0]
	v_mfma_scale_f32_16x16x128_f8f6f4 v[106:109], v[184:191], v[202:209], v[106:109], v181, v181 op_sel_hi:[0,0,0]
	v_mfma_scale_f32_16x16x128_f8f6f4 v[98:101], v[184:191], v[210:217], v[98:101], v181, v181 op_sel_hi:[0,0,0]
	v_mfma_scale_f32_16x16x128_f8f6f4 v[102:105], v[26:33], v[210:217], v[102:105], v181, v181 op_sel_hi:[0,0,0]
	v_mfma_scale_f32_16x16x128_f8f6f4 v[110:113], v[26:33], v[202:209], v[110:113], v181, v181 op_sel_hi:[0,0,0]
	v_mfma_scale_f32_16x16x128_f8f6f4 v[118:121], v[26:33], v[194:201], v[118:121], v181, v181 op_sel_hi:[0,0,0]
	v_mfma_scale_f32_16x16x128_f8f6f4 v[126:129], v[26:33], v[10:17], v[126:129], v181, v181 op_sel_hi:[0,0,0]
	s_setprio 0
	s_barrier
	s_mov_b32 m0, s52
	v_lshl_add_u64 v[10:11], s[44:45], 0, v[166:167]
	s_add_u32 s88, s44, 0x80000
	ds_read_b128 v[194:197], v193 offset:16384
	ds_read_b128 v[198:201], v193 offset:17408
	ds_read_b128 v[202:205], v193 offset:18432
	ds_read_b128 v[206:209], v193 offset:19456
	ds_read_b128 v[210:213], v193 offset:20480
	ds_read_b128 v[214:217], v193 offset:21504
	ds_read_b128 v[218:221], v193 offset:22528
	ds_read_b128 v[222:225], v193 offset:23552
	global_load_lds_dwordx4 v[10:11], off
	v_lshl_add_u64 v[12:13], s[44:45], 0, v[170:171]
	s_mov_b32 m0, s53
	s_addc_u32 s89, s45, 0
	global_load_lds_dwordx4 v[12:13], off
	v_lshl_add_u64 v[14:15], s[88:89], 0, v[166:167]
	s_mov_b32 m0, s54
	v_lshl_add_u64 v[16:17], s[48:49], 0, v[168:169]
	global_load_lds_dwordx4 v[14:15], off
	v_lshl_add_u64 v[14:15], s[88:89], 0, v[170:171]
	s_mov_b32 m0, s55
	s_nop 0
	global_load_lds_dwordx4 v[14:15], off
	v_lshl_add_u64 v[14:15], s[48:49], 0, v[164:165]
	s_mov_b32 m0, s43
	s_nop 0
	global_load_lds_dwordx4 v[14:15], off
	s_mov_b32 m0, s61
	s_nop 0
	global_load_lds_dwordx4 v[16:17], off
	s_waitcnt vmcnt(8)
	s_waitcnt lgkmcnt(0)
	s_barrier
	s_setprio 1
	s_waitcnt lgkmcnt(0)
	v_mfma_scale_f32_16x16x128_f8f6f4 v[94:97], v[2:9], v[194:201], v[94:97], v181, v181 op_sel_hi:[0,0,0]
	v_mfma_scale_f32_16x16x128_f8f6f4 v[86:89], v[2:9], v[202:209], v[86:89], v181, v181 op_sel_hi:[0,0,0]
	v_mfma_scale_f32_16x16x128_f8f6f4 v[78:81], v[2:9], v[210:217], v[78:81], v181, v181 op_sel_hi:[0,0,0]
	v_mfma_scale_f32_16x16x128_f8f6f4 v[70:73], v[2:9], v[218:225], v[70:73], v181, v181 op_sel_hi:[0,0,0]
	v_mfma_scale_f32_16x16x128_f8f6f4 v[66:69], v[18:25], v[218:225], v[66:69], v181, v181 op_sel_hi:[0,0,0]
	v_mfma_scale_f32_16x16x128_f8f6f4 v[74:77], v[18:25], v[210:217], v[74:77], v181, v181 op_sel_hi:[0,0,0]
	v_mfma_scale_f32_16x16x128_f8f6f4 v[82:85], v[18:25], v[202:209], v[82:85], v181, v181 op_sel_hi:[0,0,0]
	v_mfma_scale_f32_16x16x128_f8f6f4 v[90:93], v[18:25], v[194:201], v[90:93], v181, v181 op_sel_hi:[0,0,0]
	s_setprio 0
	s_setprio 1
	v_mfma_scale_f32_16x16x128_f8f6f4 v[58:61], v[184:191], v[194:201], v[58:61], v181, v181 op_sel_hi:[0,0,0]
	v_mfma_scale_f32_16x16x128_f8f6f4 v[50:53], v[184:191], v[202:209], v[50:53], v181, v181 op_sel_hi:[0,0,0]
	v_mfma_scale_f32_16x16x128_f8f6f4 v[42:45], v[184:191], v[210:217], v[42:45], v181, v181 op_sel_hi:[0,0,0]
	v_mfma_scale_f32_16x16x128_f8f6f4 v[34:37], v[184:191], v[218:225], v[34:37], v181, v181 op_sel_hi:[0,0,0]
	v_mfma_scale_f32_16x16x128_f8f6f4 v[38:41], v[26:33], v[218:225], v[38:41], v181, v181 op_sel_hi:[0,0,0]
	v_mfma_scale_f32_16x16x128_f8f6f4 v[46:49], v[26:33], v[210:217], v[46:49], v181, v181 op_sel_hi:[0,0,0]
	v_mfma_scale_f32_16x16x128_f8f6f4 v[54:57], v[26:33], v[202:209], v[54:57], v181, v181 op_sel_hi:[0,0,0]
	v_mfma_scale_f32_16x16x128_f8f6f4 v[62:65], v[26:33], v[194:201], v[62:65], v181, v181 op_sel_hi:[0,0,0]
	s_setprio 0
	s_barrier
	ds_read_b128 v[18:21], v192 offset:32768
	ds_read_b128 v[22:25], v192 offset:33792
	ds_read_b128 v[26:29], v192 offset:34816
	ds_read_b128 v[30:33], v192 offset:35840
	ds_read_b128 v[2:5], v192 offset:49152
	ds_read_b128 v[6:9], v192 offset:50176
	ds_read_b128 v[184:187], v192 offset:51200
	ds_read_b128 v[188:191], v192 offset:52224
	s_add_u32 s48, s48, 0x80000
	s_addc_u32 s49, s49, 0
	s_mov_b32 m0, s68
	v_lshl_add_u64 v[226:227], s[48:49], 0, v[164:165]
	ds_read_b128 v[194:197], v193 offset:32768
	ds_read_b128 v[198:201], v193 offset:33792
	ds_read_b128 v[202:205], v193 offset:34816
	ds_read_b128 v[206:209], v193 offset:35840
	ds_read_b128 v[210:213], v193 offset:36864
	ds_read_b128 v[214:217], v193 offset:37888
	ds_read_b128 v[218:221], v193 offset:38912
	ds_read_b128 v[222:225], v193 offset:39936
	global_load_lds_dwordx4 v[226:227], off
	v_lshl_add_u64 v[226:227], s[48:49], 0, v[168:169]
	s_mov_b32 m0, s69
	s_nop 0
	global_load_lds_dwordx4 v[226:227], off
	s_waitcnt vmcnt(8)
	s_waitcnt lgkmcnt(0)
	s_barrier
	s_setprio 1
	s_waitcnt lgkmcnt(0)
	v_mfma_scale_f32_16x16x128_f8f6f4 v[158:161], v[18:25], v[194:201], v[158:161], v181, v181 op_sel_hi:[0,0,0]
	v_mfma_scale_f32_16x16x128_f8f6f4 v[150:153], v[18:25], v[202:209], v[150:153], v181, v181 op_sel_hi:[0,0,0]
	v_mfma_scale_f32_16x16x128_f8f6f4 v[142:145], v[18:25], v[210:217], v[142:145], v181, v181 op_sel_hi:[0,0,0]
	v_mfma_scale_f32_16x16x128_f8f6f4 v[134:137], v[18:25], v[218:225], v[134:137], v181, v181 op_sel_hi:[0,0,0]
	v_mfma_scale_f32_16x16x128_f8f6f4 v[130:133], v[26:33], v[218:225], v[130:133], v181, v181 op_sel_hi:[0,0,0]
	v_mfma_scale_f32_16x16x128_f8f6f4 v[138:141], v[26:33], v[210:217], v[138:141], v181, v181 op_sel_hi:[0,0,0]
	v_mfma_scale_f32_16x16x128_f8f6f4 v[146:149], v[26:33], v[202:209], v[146:149], v181, v181 op_sel_hi:[0,0,0]
	v_mfma_scale_f32_16x16x128_f8f6f4 v[154:157], v[26:33], v[194:201], v[154:157], v181, v181 op_sel_hi:[0,0,0]
	s_setprio 0
	s_setprio 1
	v_mfma_scale_f32_16x16x128_f8f6f4 v[122:125], v[184:191], v[194:201], v[122:125], v181, v181 op_sel_hi:[0,0,0]
	v_mfma_scale_f32_16x16x128_f8f6f4 v[114:117], v[184:191], v[202:209], v[114:117], v181, v181 op_sel_hi:[0,0,0]
	v_mfma_scale_f32_16x16x128_f8f6f4 v[106:109], v[184:191], v[210:217], v[106:109], v181, v181 op_sel_hi:[0,0,0]
	v_mfma_scale_f32_16x16x128_f8f6f4 v[98:101], v[184:191], v[218:225], v[98:101], v181, v181 op_sel_hi:[0,0,0]
	v_mfma_scale_f32_16x16x128_f8f6f4 v[102:105], v[2:9], v[218:225], v[102:105], v181, v181 op_sel_hi:[0,0,0]
	v_mfma_scale_f32_16x16x128_f8f6f4 v[110:113], v[2:9], v[210:217], v[110:113], v181, v181 op_sel_hi:[0,0,0]
	v_mfma_scale_f32_16x16x128_f8f6f4 v[118:121], v[2:9], v[202:209], v[118:121], v181, v181 op_sel_hi:[0,0,0]
	v_mfma_scale_f32_16x16x128_f8f6f4 v[126:129], v[2:9], v[194:201], v[126:129], v181, v181 op_sel_hi:[0,0,0]
	s_setprio 0
	s_barrier
	s_mov_b32 m0, s74
	v_lshl_add_u64 v[10:11], v[10:11], 0, s[4:5]
	s_add_u32 s44, s44, 0x80080
	ds_read_b128 v[194:197], v193 offset:49152
	ds_read_b128 v[198:201], v193 offset:50176
	ds_read_b128 v[202:205], v193 offset:51200
	ds_read_b128 v[206:209], v193 offset:52224
	ds_read_b128 v[210:213], v193 offset:53248
	ds_read_b128 v[214:217], v193 offset:54272
	ds_read_b128 v[218:221], v193 offset:55296
	ds_read_b128 v[222:225], v193 offset:56320
	global_load_lds_dwordx4 v[10:11], off
	v_lshl_add_u64 v[10:11], v[12:13], 0, s[4:5]
	s_mov_b32 m0, s75
	s_addc_u32 s45, s45, 0
	global_load_lds_dwordx4 v[10:11], off
	v_lshl_add_u64 v[10:11], s[44:45], 0, v[166:167]
	s_mov_b32 m0, s78
	s_nop 0
	global_load_lds_dwordx4 v[10:11], off
	v_lshl_add_u64 v[10:11], s[44:45], 0, v[170:171]
	s_mov_b32 m0, s79
	s_nop 0
	global_load_lds_dwordx4 v[10:11], off
	v_lshl_add_u64 v[10:11], v[14:15], 0, s[4:5]
	s_mov_b32 m0, s76
	s_nop 0
	global_load_lds_dwordx4 v[10:11], off
	v_lshl_add_u64 v[10:11], v[16:17], 0, s[4:5]
	s_mov_b32 m0, s77
	s_nop 0
	global_load_lds_dwordx4 v[10:11], off
	s_waitcnt vmcnt(8)
	s_waitcnt lgkmcnt(0)
	s_barrier
	s_setprio 1
	s_waitcnt lgkmcnt(0)
	v_mfma_scale_f32_16x16x128_f8f6f4 v[94:97], v[18:25], v[194:201], v[94:97], v181, v181 op_sel_hi:[0,0,0]
	v_mfma_scale_f32_16x16x128_f8f6f4 v[86:89], v[18:25], v[202:209], v[86:89], v181, v181 op_sel_hi:[0,0,0]
	v_mfma_scale_f32_16x16x128_f8f6f4 v[78:81], v[18:25], v[210:217], v[78:81], v181, v181 op_sel_hi:[0,0,0]
	v_mfma_scale_f32_16x16x128_f8f6f4 v[70:73], v[18:25], v[218:225], v[70:73], v181, v181 op_sel_hi:[0,0,0]
	v_mfma_scale_f32_16x16x128_f8f6f4 v[66:69], v[26:33], v[218:225], v[66:69], v181, v181 op_sel_hi:[0,0,0]
	v_mfma_scale_f32_16x16x128_f8f6f4 v[74:77], v[26:33], v[210:217], v[74:77], v181, v181 op_sel_hi:[0,0,0]
	v_mfma_scale_f32_16x16x128_f8f6f4 v[82:85], v[26:33], v[202:209], v[82:85], v181, v181 op_sel_hi:[0,0,0]
	v_mfma_scale_f32_16x16x128_f8f6f4 v[90:93], v[26:33], v[194:201], v[90:93], v181, v181 op_sel_hi:[0,0,0]
	s_setprio 0
	s_setprio 1
	v_mfma_scale_f32_16x16x128_f8f6f4 v[58:61], v[184:191], v[194:201], v[58:61], v181, v181 op_sel_hi:[0,0,0]
	v_mfma_scale_f32_16x16x128_f8f6f4 v[50:53], v[184:191], v[202:209], v[50:53], v181, v181 op_sel_hi:[0,0,0]
	v_mfma_scale_f32_16x16x128_f8f6f4 v[42:45], v[184:191], v[210:217], v[42:45], v181, v181 op_sel_hi:[0,0,0]
	v_mfma_scale_f32_16x16x128_f8f6f4 v[34:37], v[184:191], v[218:225], v[34:37], v181, v181 op_sel_hi:[0,0,0]
	v_mfma_scale_f32_16x16x128_f8f6f4 v[38:41], v[2:9], v[218:225], v[38:41], v181, v181 op_sel_hi:[0,0,0]
	v_mfma_scale_f32_16x16x128_f8f6f4 v[46:49], v[2:9], v[210:217], v[46:49], v181, v181 op_sel_hi:[0,0,0]
	v_mfma_scale_f32_16x16x128_f8f6f4 v[54:57], v[2:9], v[202:209], v[54:57], v181, v181 op_sel_hi:[0,0,0]
	v_mfma_scale_f32_16x16x128_f8f6f4 v[62:65], v[2:9], v[194:201], v[62:65], v181, v181 op_sel_hi:[0,0,0]
	s_setprio 0
	s_barrier
	s_add_i32 s86, s86, 2
	s_add_u32 s46, s46, 0x100
	s_addc_u32 s47, s47, 0
	s_add_u32 s62, s62, 0x100
	s_addc_u32 s63, s63, 0
	s_cmp_gt_u32 s86, 29
	s_cbranch_scc0 .LBB0_947
	s_and_b64 vcc, exec, s[6:7]
	s_cbranch_vccz .LBB0_950
	s_barrier

.LBB0_1031:
	ds_read_b128 v[2:5], v189
	ds_read_b128 v[6:9], v189 offset:1024
	ds_read_b128 v[192:195], v189 offset:2048
	ds_read_b128 v[196:199], v189 offset:3072
	ds_read_b128 v[200:203], v189 offset:16384
	ds_read_b128 v[204:207], v189 offset:17408
	ds_read_b128 v[208:211], v189 offset:18432
	ds_read_b128 v[212:215], v189 offset:19456
	s_add_u32 s25, s36, 0x100
	s_addc_u32 s83, s37, 0
	s_and_b64 s[40:41], s[38:39], exec
	s_cselect_b32 s41, s1, s83
	s_cselect_b32 s40, s0, s25
	s_add_u32 s25, s26, 0x100
	s_addc_u32 s83, s27, 0
	s_and_b64 s[38:39], s[38:39], exec
	s_cselect_b32 s39, s5, s83
	s_cselect_b32 s38, s4, s25
	s_add_u32 s84, s36, 0x158080
	s_addc_u32 s85, s37, 0
	s_add_i32 s25, s23, 0xc000
	v_lshl_add_u64 v[174:175], s[84:85], 0, v[154:155]
	s_mov_b32 m0, s25
	s_add_i32 s83, s23, 0xe000
	ds_read_b128 v[216:219], v190
	ds_read_b128 v[220:223], v190 offset:1024
	ds_read_b128 v[224:227], v190 offset:2048
	ds_read_b128 v[228:231], v190 offset:3072
	ds_read_b128 v[232:235], v190 offset:4096
	ds_read_b128 v[236:239], v190 offset:5120
	ds_read_b128 v[240:243], v190 offset:6144
	ds_read_b128 v[244:247], v190 offset:7168
	global_load_lds_dwordx4 v[174:175], off
	v_lshl_add_u64 v[174:175], s[84:85], 0, v[158:159]
	s_mov_b32 m0, s83
	s_nop 0
	global_load_lds_dwordx4 v[174:175], off
	s_waitcnt vmcnt(8)
	s_waitcnt lgkmcnt(0)
	s_barrier
	s_setprio 1
	s_waitcnt lgkmcnt(0)
	v_mfma_scale_f32_16x16x128_f8f6f4 v[134:137], v[2:9], v[216:223], 0, v188, v188 op_sel_hi:[0,0,0]
	v_mfma_scale_f32_16x16x128_f8f6f4 v[126:129], v[2:9], v[224:231], 0, v188, v188 op_sel_hi:[0,0,0]
	v_mfma_scale_f32_16x16x128_f8f6f4 v[118:121], v[2:9], v[232:239], 0, v188, v188 op_sel_hi:[0,0,0]
	v_mfma_scale_f32_16x16x128_f8f6f4 v[110:113], v[2:9], v[240:247], 0, v188, v188 op_sel_hi:[0,0,0]
	v_mfma_scale_f32_16x16x128_f8f6f4 v[106:109], v[192:199], v[240:247], 0, v188, v188 op_sel_hi:[0,0,0]
	v_mfma_scale_f32_16x16x128_f8f6f4 v[114:117], v[192:199], v[232:239], 0, v188, v188 op_sel_hi:[0,0,0]
	v_mfma_scale_f32_16x16x128_f8f6f4 v[122:125], v[192:199], v[224:231], 0, v188, v188 op_sel_hi:[0,0,0]
	v_mfma_scale_f32_16x16x128_f8f6f4 v[130:133], v[192:199], v[216:223], 0, v188, v188 op_sel_hi:[0,0,0]
	s_setprio 0
	s_setprio 1
	v_mfma_scale_f32_16x16x128_f8f6f4 v[98:101], v[208:215], v[216:223], 0, v188, v188 op_sel_hi:[0,0,0]
	v_mfma_scale_f32_16x16x128_f8f6f4 v[90:93], v[208:215], v[224:231], 0, v188, v188 op_sel_hi:[0,0,0]
	v_mfma_scale_f32_16x16x128_f8f6f4 v[82:85], v[208:215], v[232:239], 0, v188, v188 op_sel_hi:[0,0,0]
	v_mfma_scale_f32_16x16x128_f8f6f4 v[74:77], v[208:215], v[240:247], 0, v188, v188 op_sel_hi:[0,0,0]
	v_mfma_scale_f32_16x16x128_f8f6f4 v[78:81], v[200:207], v[240:247], 0, v188, v188 op_sel_hi:[0,0,0]
	v_mfma_scale_f32_16x16x128_f8f6f4 v[86:89], v[200:207], v[232:239], 0, v188, v188 op_sel_hi:[0,0,0]
	v_mfma_scale_f32_16x16x128_f8f6f4 v[94:97], v[200:207], v[224:231], 0, v188, v188 op_sel_hi:[0,0,0]
	v_mfma_scale_f32_16x16x128_f8f6f4 v[102:105], v[200:207], v[216:223], 0, v188, v188 op_sel_hi:[0,0,0]
	s_setprio 0
	s_barrier
	s_mov_b32 m0, s33
	v_lshl_add_u64 v[174:175], s[38:39], 0, v[156:157]
	s_add_u32 s84, s38, 0x158000
	ds_read_b128 v[216:219], v190 offset:16384
	ds_read_b128 v[220:223], v190 offset:17408
	ds_read_b128 v[224:227], v190 offset:18432
	ds_read_b128 v[228:231], v190 offset:19456
	ds_read_b128 v[232:235], v190 offset:20480
	ds_read_b128 v[236:239], v190 offset:21504
	ds_read_b128 v[240:243], v190 offset:22528
	ds_read_b128 v[244:247], v190 offset:23552
	global_load_lds_dwordx4 v[174:175], off
	v_lshl_add_u64 v[176:177], s[38:39], 0, v[160:161]
	s_mov_b32 m0, s35
	s_addc_u32 s85, s39, 0
	global_load_lds_dwordx4 v[176:177], off
	v_lshl_add_u64 v[182:183], s[84:85], 0, v[156:157]
	s_mov_b32 m0, s42
	v_lshl_add_u64 v[184:185], s[40:41], 0, v[158:159]
	global_load_lds_dwordx4 v[182:183], off
	v_lshl_add_u64 v[182:183], s[84:85], 0, v[160:161]
	s_mov_b32 m0, s43
	s_nop 0
	global_load_lds_dwordx4 v[182:183], off
	v_lshl_add_u64 v[182:183], s[40:41], 0, v[154:155]
	s_mov_b32 m0, s23
	s_nop 0
	global_load_lds_dwordx4 v[182:183], off
	s_mov_b32 m0, s44
	s_nop 0
	global_load_lds_dwordx4 v[184:185], off
	s_waitcnt vmcnt(8)
	s_waitcnt lgkmcnt(0)
	s_barrier
	s_setprio 1
	s_waitcnt lgkmcnt(0)
	v_mfma_scale_f32_16x16x128_f8f6f4 v[70:73], v[2:9], v[216:223], 0, v188, v188 op_sel_hi:[0,0,0]
	v_mfma_scale_f32_16x16x128_f8f6f4 v[62:65], v[2:9], v[224:231], 0, v188, v188 op_sel_hi:[0,0,0]
	v_mfma_scale_f32_16x16x128_f8f6f4 v[54:57], v[2:9], v[232:239], 0, v188, v188 op_sel_hi:[0,0,0]
	v_mfma_scale_f32_16x16x128_f8f6f4 v[46:49], v[2:9], v[240:247], 0, v188, v188 op_sel_hi:[0,0,0]
	v_mfma_scale_f32_16x16x128_f8f6f4 v[42:45], v[192:199], v[240:247], 0, v188, v188 op_sel_hi:[0,0,0]
	v_mfma_scale_f32_16x16x128_f8f6f4 v[50:53], v[192:199], v[232:239], 0, v188, v188 op_sel_hi:[0,0,0]
	v_mfma_scale_f32_16x16x128_f8f6f4 v[58:61], v[192:199], v[224:231], 0, v188, v188 op_sel_hi:[0,0,0]
	v_mfma_scale_f32_16x16x128_f8f6f4 v[66:69], v[192:199], v[216:223], 0, v188, v188 op_sel_hi:[0,0,0]
	s_setprio 0
	s_setprio 1
	v_mfma_scale_f32_16x16x128_f8f6f4 v[34:37], v[208:215], v[216:223], 0, v188, v188 op_sel_hi:[0,0,0]
	v_mfma_scale_f32_16x16x128_f8f6f4 v[26:29], v[208:215], v[224:231], 0, v188, v188 op_sel_hi:[0,0,0]
	v_mfma_scale_f32_16x16x128_f8f6f4 v[18:21], v[208:215], v[232:239], 0, v188, v188 op_sel_hi:[0,0,0]
	v_mfma_scale_f32_16x16x128_f8f6f4 v[10:13], v[208:215], v[240:247], 0, v188, v188 op_sel_hi:[0,0,0]
	v_mfma_scale_f32_16x16x128_f8f6f4 v[14:17], v[200:207], v[240:247], 0, v188, v188 op_sel_hi:[0,0,0]
	v_mfma_scale_f32_16x16x128_f8f6f4 v[22:25], v[200:207], v[232:239], 0, v188, v188 op_sel_hi:[0,0,0]
	v_mfma_scale_f32_16x16x128_f8f6f4 v[30:33], v[200:207], v[224:231], 0, v188, v188 op_sel_hi:[0,0,0]
	v_mfma_scale_f32_16x16x128_f8f6f4 v[38:41], v[200:207], v[216:223], 0, v188, v188 op_sel_hi:[0,0,0]
	s_setprio 0
	s_barrier
	ds_read_b128 v[2:5], v189 offset:32768
	ds_read_b128 v[6:9], v189 offset:33792
	ds_read_b128 v[192:195], v189 offset:34816
	ds_read_b128 v[196:199], v189 offset:35840
	ds_read_b128 v[200:203], v189 offset:49152
	ds_read_b128 v[204:207], v189 offset:50176
	ds_read_b128 v[208:211], v189 offset:51200
	ds_read_b128 v[212:215], v189 offset:52224
	s_add_u32 s40, s40, 0x158000
	s_addc_u32 s41, s41, 0
	s_mov_b32 m0, s45
	v_lshl_add_u64 v[186:187], s[40:41], 0, v[154:155]
	ds_read_b128 v[216:219], v190 offset:32768
	ds_read_b128 v[220:223], v190 offset:33792
	ds_read_b128 v[224:227], v190 offset:34816
	ds_read_b128 v[228:231], v190 offset:35840
	ds_read_b128 v[232:235], v190 offset:36864
	ds_read_b128 v[236:239], v190 offset:37888
	ds_read_b128 v[240:243], v190 offset:38912
	ds_read_b128 v[244:247], v190 offset:39936
	global_load_lds_dwordx4 v[186:187], off
	v_lshl_add_u64 v[186:187], s[40:41], 0, v[158:159]
	s_mov_b32 m0, s46
	s_nop 0
	global_load_lds_dwordx4 v[186:187], off
	s_waitcnt vmcnt(8)
	s_waitcnt lgkmcnt(0)
	s_barrier
	s_setprio 1
	s_waitcnt lgkmcnt(0)
	v_mfma_scale_f32_16x16x128_f8f6f4 v[134:137], v[2:9], v[216:223], v[134:137], v188, v188 op_sel_hi:[0,0,0]
	v_mfma_scale_f32_16x16x128_f8f6f4 v[126:129], v[2:9], v[224:231], v[126:129], v188, v188 op_sel_hi:[0,0,0]
	v_mfma_scale_f32_16x16x128_f8f6f4 v[118:121], v[2:9], v[232:239], v[118:121], v188, v188 op_sel_hi:[0,0,0]
	v_mfma_scale_f32_16x16x128_f8f6f4 v[110:113], v[2:9], v[240:247], v[110:113], v188, v188 op_sel_hi:[0,0,0]
	v_mfma_scale_f32_16x16x128_f8f6f4 v[106:109], v[192:199], v[240:247], v[106:109], v188, v188 op_sel_hi:[0,0,0]
	v_mfma_scale_f32_16x16x128_f8f6f4 v[114:117], v[192:199], v[232:239], v[114:117], v188, v188 op_sel_hi:[0,0,0]
	v_mfma_scale_f32_16x16x128_f8f6f4 v[122:125], v[192:199], v[224:231], v[122:125], v188, v188 op_sel_hi:[0,0,0]
	v_mfma_scale_f32_16x16x128_f8f6f4 v[130:133], v[192:199], v[216:223], v[130:133], v188, v188 op_sel_hi:[0,0,0]
	s_setprio 0
	s_setprio 1
	v_mfma_scale_f32_16x16x128_f8f6f4 v[98:101], v[208:215], v[216:223], v[98:101], v188, v188 op_sel_hi:[0,0,0]
	v_mfma_scale_f32_16x16x128_f8f6f4 v[90:93], v[208:215], v[224:231], v[90:93], v188, v188 op_sel_hi:[0,0,0]
	v_mfma_scale_f32_16x16x128_f8f6f4 v[82:85], v[208:215], v[232:239], v[82:85], v188, v188 op_sel_hi:[0,0,0]
	v_mfma_scale_f32_16x16x128_f8f6f4 v[74:77], v[208:215], v[240:247], v[74:77], v188, v188 op_sel_hi:[0,0,0]
	v_mfma_scale_f32_16x16x128_f8f6f4 v[78:81], v[200:207], v[240:247], v[78:81], v188, v188 op_sel_hi:[0,0,0]
	v_mfma_scale_f32_16x16x128_f8f6f4 v[86:89], v[200:207], v[232:239], v[86:89], v188, v188 op_sel_hi:[0,0,0]
	v_mfma_scale_f32_16x16x128_f8f6f4 v[94:97], v[200:207], v[224:231], v[94:97], v188, v188 op_sel_hi:[0,0,0]
	v_mfma_scale_f32_16x16x128_f8f6f4 v[102:105], v[200:207], v[216:223], v[102:105], v188, v188 op_sel_hi:[0,0,0]
	s_setprio 0
	s_barrier
	s_mov_b32 m0, s52
	v_lshl_add_u64 v[174:175], v[174:175], 0, s[14:15]
	s_add_u32 s38, s38, 0x158080
	ds_read_b128 v[216:219], v190 offset:49152
	ds_read_b128 v[220:223], v190 offset:50176
	ds_read_b128 v[224:227], v190 offset:51200
	ds_read_b128 v[228:231], v190 offset:52224
	ds_read_b128 v[232:235], v190 offset:53248
	ds_read_b128 v[236:239], v190 offset:54272
	ds_read_b128 v[240:243], v190 offset:55296
	ds_read_b128 v[244:247], v190 offset:56320
	global_load_lds_dwordx4 v[174:175], off
	v_lshl_add_u64 v[174:175], v[176:177], 0, s[14:15]
	s_mov_b32 m0, s53
	s_addc_u32 s39, s39, 0
	global_load_lds_dwordx4 v[174:175], off
	v_lshl_add_u64 v[174:175], s[38:39], 0, v[156:157]
	s_mov_b32 m0, s56
	s_nop 0
	global_load_lds_dwordx4 v[174:175], off
	v_lshl_add_u64 v[174:175], s[38:39], 0, v[160:161]
	s_mov_b32 m0, s57
	s_nop 0
	global_load_lds_dwordx4 v[174:175], off
	v_lshl_add_u64 v[174:175], v[182:183], 0, s[14:15]
	s_mov_b32 m0, s54
	s_nop 0
	global_load_lds_dwordx4 v[174:175], off
	v_lshl_add_u64 v[174:175], v[184:185], 0, s[14:15]
	s_mov_b32 m0, s55
	s_nop 0
	global_load_lds_dwordx4 v[174:175], off
	s_waitcnt vmcnt(8)
	s_waitcnt lgkmcnt(0)
	s_barrier
	s_setprio 1
	s_waitcnt lgkmcnt(0)
	v_mfma_scale_f32_16x16x128_f8f6f4 v[70:73], v[2:9], v[216:223], v[70:73], v188, v188 op_sel_hi:[0,0,0]
	v_mfma_scale_f32_16x16x128_f8f6f4 v[62:65], v[2:9], v[224:231], v[62:65], v188, v188 op_sel_hi:[0,0,0]
	v_mfma_scale_f32_16x16x128_f8f6f4 v[54:57], v[2:9], v[232:239], v[54:57], v188, v188 op_sel_hi:[0,0,0]
	v_mfma_scale_f32_16x16x128_f8f6f4 v[46:49], v[2:9], v[240:247], v[46:49], v188, v188 op_sel_hi:[0,0,0]
	v_mfma_scale_f32_16x16x128_f8f6f4 v[42:45], v[192:199], v[240:247], v[42:45], v188, v188 op_sel_hi:[0,0,0]
	v_mfma_scale_f32_16x16x128_f8f6f4 v[50:53], v[192:199], v[232:239], v[50:53], v188, v188 op_sel_hi:[0,0,0]
	v_mfma_scale_f32_16x16x128_f8f6f4 v[58:61], v[192:199], v[224:231], v[58:61], v188, v188 op_sel_hi:[0,0,0]
	v_mfma_scale_f32_16x16x128_f8f6f4 v[66:69], v[192:199], v[216:223], v[66:69], v188, v188 op_sel_hi:[0,0,0]
	s_setprio 0
	s_setprio 1
	v_mfma_scale_f32_16x16x128_f8f6f4 v[34:37], v[208:215], v[216:223], v[34:37], v188, v188 op_sel_hi:[0,0,0]
	v_mfma_scale_f32_16x16x128_f8f6f4 v[26:29], v[208:215], v[224:231], v[26:29], v188, v188 op_sel_hi:[0,0,0]
	v_mfma_scale_f32_16x16x128_f8f6f4 v[18:21], v[208:215], v[232:239], v[18:21], v188, v188 op_sel_hi:[0,0,0]
	v_mfma_scale_f32_16x16x128_f8f6f4 v[10:13], v[208:215], v[240:247], v[10:13], v188, v188 op_sel_hi:[0,0,0]
	v_mfma_scale_f32_16x16x128_f8f6f4 v[14:17], v[200:207], v[240:247], v[14:17], v188, v188 op_sel_hi:[0,0,0]
	v_mfma_scale_f32_16x16x128_f8f6f4 v[22:25], v[200:207], v[232:239], v[22:25], v188, v188 op_sel_hi:[0,0,0]
	v_mfma_scale_f32_16x16x128_f8f6f4 v[30:33], v[200:207], v[224:231], v[30:33], v188, v188 op_sel_hi:[0,0,0]
	v_mfma_scale_f32_16x16x128_f8f6f4 v[38:41], v[200:207], v[216:223], v[38:41], v188, v188 op_sel_hi:[0,0,0]
	s_setprio 0
	s_barrier
	s_cmp_lt_u32 s82, 3
	s_cbranch_scc1 .LBB0_1036
	s_add_u32 s38, s48, s63
	s_addc_u32 s39, s49, s62
	s_add_u32 s36, s36, 0x158180
	s_addc_u32 s37, s37, 0
	s_add_u32 s40, s26, 0x200
	v_lshl_add_u64 v[174:175], v[172:173], 2, s[38:39]
	s_addc_u32 s41, s27, 0
	s_mov_b32 s84, 4
	s_cmp_eq_u32 s82, s84
	s_cselect_b64 s[26:27], -1, 0
	s_cmp_lg_u32 s82, s84
	s_cbranch_scc1 .LBB0_1034

.LBB0_1034:
	ds_read_b128 v[2:5], v189
	ds_read_b128 v[6:9], v189 offset:1024
	ds_read_b128 v[192:195], v189 offset:2048
	ds_read_b128 v[196:199], v189 offset:3072
	ds_read_b128 v[200:203], v189 offset:16384
	ds_read_b128 v[204:207], v189 offset:17408
	ds_read_b128 v[208:211], v189 offset:18432
	ds_read_b128 v[212:215], v189 offset:19456
	s_add_u32 s38, s36, 0xffea8080
	s_addc_u32 s39, s37, -1
	s_and_b64 s[26:27], s[26:27], exec
	s_cselect_b32 s26, s4, s40
	s_cselect_b32 s39, s1, s39
	s_cselect_b32 s38, s0, s38
	s_cselect_b32 s27, s5, s41
	s_mov_b32 m0, s25
	v_lshl_add_u64 v[176:177], s[36:37], 0, v[162:163]
	ds_read_b128 v[216:219], v190
	ds_read_b128 v[220:223], v190 offset:1024
	ds_read_b128 v[224:227], v190 offset:2048
	ds_read_b128 v[228:231], v190 offset:3072
	ds_read_b128 v[232:235], v190 offset:4096
	ds_read_b128 v[236:239], v190 offset:5120
	ds_read_b128 v[240:243], v190 offset:6144
	ds_read_b128 v[244:247], v190 offset:7168
	global_load_lds_dwordx4 v[176:177], off
	v_lshl_add_u64 v[176:177], s[36:37], 0, v[164:165]
	s_mov_b32 m0, s83
	s_nop 0
	global_load_lds_dwordx4 v[176:177], off
	s_waitcnt vmcnt(8)
	s_waitcnt lgkmcnt(0)
	s_barrier
	s_setprio 1
	s_waitcnt lgkmcnt(0)
	v_mfma_scale_f32_16x16x128_f8f6f4 v[134:137], v[2:9], v[216:223], v[134:137], v188, v188 op_sel_hi:[0,0,0]
	v_mfma_scale_f32_16x16x128_f8f6f4 v[126:129], v[2:9], v[224:231], v[126:129], v188, v188 op_sel_hi:[0,0,0]
	v_mfma_scale_f32_16x16x128_f8f6f4 v[118:121], v[2:9], v[232:239], v[118:121], v188, v188 op_sel_hi:[0,0,0]
	v_mfma_scale_f32_16x16x128_f8f6f4 v[110:113], v[2:9], v[240:247], v[110:113], v188, v188 op_sel_hi:[0,0,0]
	v_mfma_scale_f32_16x16x128_f8f6f4 v[106:109], v[192:199], v[240:247], v[106:109], v188, v188 op_sel_hi:[0,0,0]
	v_mfma_scale_f32_16x16x128_f8f6f4 v[114:117], v[192:199], v[232:239], v[114:117], v188, v188 op_sel_hi:[0,0,0]
	v_mfma_scale_f32_16x16x128_f8f6f4 v[122:125], v[192:199], v[224:231], v[122:125], v188, v188 op_sel_hi:[0,0,0]
	v_mfma_scale_f32_16x16x128_f8f6f4 v[130:133], v[192:199], v[216:223], v[130:133], v188, v188 op_sel_hi:[0,0,0]
	s_setprio 0
	s_setprio 1
	v_mfma_scale_f32_16x16x128_f8f6f4 v[98:101], v[208:215], v[216:223], v[98:101], v188, v188 op_sel_hi:[0,0,0]
	v_mfma_scale_f32_16x16x128_f8f6f4 v[90:93], v[208:215], v[224:231], v[90:93], v188, v188 op_sel_hi:[0,0,0]
	v_mfma_scale_f32_16x16x128_f8f6f4 v[82:85], v[208:215], v[232:239], v[82:85], v188, v188 op_sel_hi:[0,0,0]
	v_mfma_scale_f32_16x16x128_f8f6f4 v[74:77], v[208:215], v[240:247], v[74:77], v188, v188 op_sel_hi:[0,0,0]
	v_mfma_scale_f32_16x16x128_f8f6f4 v[78:81], v[200:207], v[240:247], v[78:81], v188, v188 op_sel_hi:[0,0,0]
	v_mfma_scale_f32_16x16x128_f8f6f4 v[86:89], v[200:207], v[232:239], v[86:89], v188, v188 op_sel_hi:[0,0,0]
	v_mfma_scale_f32_16x16x128_f8f6f4 v[94:97], v[200:207], v[224:231], v[94:97], v188, v188 op_sel_hi:[0,0,0]
	v_mfma_scale_f32_16x16x128_f8f6f4 v[102:105], v[200:207], v[216:223], v[102:105], v188, v188 op_sel_hi:[0,0,0]
	s_setprio 0
	s_barrier
	s_mov_b32 m0, s33
	v_lshl_add_u64 v[176:177], s[26:27], 0, v[156:157]
	s_add_u32 s62, s26, 0x158000
	ds_read_b128 v[216:219], v190 offset:16384
	ds_read_b128 v[220:223], v190 offset:17408
	ds_read_b128 v[224:227], v190 offset:18432
	ds_read_b128 v[228:231], v190 offset:19456
	ds_read_b128 v[232:235], v190 offset:20480
	ds_read_b128 v[236:239], v190 offset:21504
	ds_read_b128 v[240:243], v190 offset:22528
	ds_read_b128 v[244:247], v190 offset:23552
	global_load_lds_dwordx4 v[176:177], off
	v_lshl_add_u64 v[182:183], s[26:27], 0, v[160:161]
	s_mov_b32 m0, s35
	s_addc_u32 s63, s27, 0
	global_load_lds_dwordx4 v[182:183], off
	v_lshl_add_u64 v[184:185], s[62:63], 0, v[156:157]
	s_mov_b32 m0, s42
	v_lshl_add_u64 v[186:187], s[38:39], 0, v[158:159]
	global_load_lds_dwordx4 v[184:185], off
	v_lshl_add_u64 v[184:185], s[62:63], 0, v[160:161]
	s_mov_b32 m0, s43
	s_nop 0
	global_load_lds_dwordx4 v[184:185], off
	v_lshl_add_u64 v[184:185], s[38:39], 0, v[154:155]
	s_mov_b32 m0, s23
	s_nop 0
	global_load_lds_dwordx4 v[184:185], off
	s_mov_b32 m0, s44
	s_nop 0
	global_load_lds_dwordx4 v[186:187], off
	s_waitcnt vmcnt(8)
	s_waitcnt lgkmcnt(0)
	s_barrier
	s_setprio 1
	s_waitcnt lgkmcnt(0)
	v_mfma_scale_f32_16x16x128_f8f6f4 v[70:73], v[2:9], v[216:223], v[70:73], v188, v188 op_sel_hi:[0,0,0]
	v_mfma_scale_f32_16x16x128_f8f6f4 v[62:65], v[2:9], v[224:231], v[62:65], v188, v188 op_sel_hi:[0,0,0]
	v_mfma_scale_f32_16x16x128_f8f6f4 v[54:57], v[2:9], v[232:239], v[54:57], v188, v188 op_sel_hi:[0,0,0]
	v_mfma_scale_f32_16x16x128_f8f6f4 v[46:49], v[2:9], v[240:247], v[46:49], v188, v188 op_sel_hi:[0,0,0]
	v_mfma_scale_f32_16x16x128_f8f6f4 v[42:45], v[192:199], v[240:247], v[42:45], v188, v188 op_sel_hi:[0,0,0]
	v_mfma_scale_f32_16x16x128_f8f6f4 v[50:53], v[192:199], v[232:239], v[50:53], v188, v188 op_sel_hi:[0,0,0]
	v_mfma_scale_f32_16x16x128_f8f6f4 v[58:61], v[192:199], v[224:231], v[58:61], v188, v188 op_sel_hi:[0,0,0]
	v_mfma_scale_f32_16x16x128_f8f6f4 v[66:69], v[192:199], v[216:223], v[66:69], v188, v188 op_sel_hi:[0,0,0]
	s_setprio 0
	s_setprio 1
	v_mfma_scale_f32_16x16x128_f8f6f4 v[34:37], v[208:215], v[216:223], v[34:37], v188, v188 op_sel_hi:[0,0,0]
	v_mfma_scale_f32_16x16x128_f8f6f4 v[26:29], v[208:215], v[224:231], v[26:29], v188, v188 op_sel_hi:[0,0,0]
	v_mfma_scale_f32_16x16x128_f8f6f4 v[18:21], v[208:215], v[232:239], v[18:21], v188, v188 op_sel_hi:[0,0,0]
	v_mfma_scale_f32_16x16x128_f8f6f4 v[10:13], v[208:215], v[240:247], v[10:13], v188, v188 op_sel_hi:[0,0,0]
	v_mfma_scale_f32_16x16x128_f8f6f4 v[14:17], v[200:207], v[240:247], v[14:17], v188, v188 op_sel_hi:[0,0,0]
	v_mfma_scale_f32_16x16x128_f8f6f4 v[22:25], v[200:207], v[232:239], v[22:25], v188, v188 op_sel_hi:[0,0,0]
	v_mfma_scale_f32_16x16x128_f8f6f4 v[30:33], v[200:207], v[224:231], v[30:33], v188, v188 op_sel_hi:[0,0,0]
	v_mfma_scale_f32_16x16x128_f8f6f4 v[38:41], v[200:207], v[216:223], v[38:41], v188, v188 op_sel_hi:[0,0,0]
	s_setprio 0
	s_barrier
	ds_read_b128 v[192:195], v189 offset:32768
	ds_read_b128 v[196:199], v189 offset:33792
	ds_read_b128 v[200:203], v189 offset:34816
	ds_read_b128 v[204:207], v189 offset:35840
	ds_read_b128 v[2:5], v189 offset:49152
	ds_read_b128 v[6:9], v189 offset:50176
	ds_read_b128 v[208:211], v189 offset:51200
	ds_read_b128 v[212:215], v189 offset:52224
	s_add_u32 s38, s38, 0x158000
	s_addc_u32 s39, s39, 0
	s_mov_b32 m0, s45
	v_lshl_add_u64 v[248:249], s[38:39], 0, v[154:155]
	ds_read_b128 v[216:219], v190 offset:32768
	ds_read_b128 v[220:223], v190 offset:33792
	ds_read_b128 v[224:227], v190 offset:34816
	ds_read_b128 v[228:231], v190 offset:35840
	ds_read_b128 v[232:235], v190 offset:36864
	ds_read_b128 v[236:239], v190 offset:37888
	ds_read_b128 v[240:243], v190 offset:38912
	ds_read_b128 v[244:247], v190 offset:39936
	global_load_lds_dwordx4 v[248:249], off
	v_lshl_add_u64 v[248:249], s[38:39], 0, v[158:159]
	s_mov_b32 m0, s46
	s_nop 0
	global_load_lds_dwordx4 v[248:249], off
	s_waitcnt vmcnt(8)
	s_waitcnt lgkmcnt(0)
	s_barrier
	s_setprio 1
	s_waitcnt lgkmcnt(0)
	v_mfma_scale_f32_16x16x128_f8f6f4 v[134:137], v[192:199], v[216:223], v[134:137], v188, v188 op_sel_hi:[0,0,0]
	v_mfma_scale_f32_16x16x128_f8f6f4 v[126:129], v[192:199], v[224:231], v[126:129], v188, v188 op_sel_hi:[0,0,0]
	v_mfma_scale_f32_16x16x128_f8f6f4 v[118:121], v[192:199], v[232:239], v[118:121], v188, v188 op_sel_hi:[0,0,0]
	v_mfma_scale_f32_16x16x128_f8f6f4 v[110:113], v[192:199], v[240:247], v[110:113], v188, v188 op_sel_hi:[0,0,0]
	v_mfma_scale_f32_16x16x128_f8f6f4 v[106:109], v[200:207], v[240:247], v[106:109], v188, v188 op_sel_hi:[0,0,0]
	v_mfma_scale_f32_16x16x128_f8f6f4 v[114:117], v[200:207], v[232:239], v[114:117], v188, v188 op_sel_hi:[0,0,0]
	v_mfma_scale_f32_16x16x128_f8f6f4 v[122:125], v[200:207], v[224:231], v[122:125], v188, v188 op_sel_hi:[0,0,0]
	v_mfma_scale_f32_16x16x128_f8f6f4 v[130:133], v[200:207], v[216:223], v[130:133], v188, v188 op_sel_hi:[0,0,0]
	s_setprio 0
	s_setprio 1
	v_mfma_scale_f32_16x16x128_f8f6f4 v[98:101], v[208:215], v[216:223], v[98:101], v188, v188 op_sel_hi:[0,0,0]
	v_mfma_scale_f32_16x16x128_f8f6f4 v[90:93], v[208:215], v[224:231], v[90:93], v188, v188 op_sel_hi:[0,0,0]
	v_mfma_scale_f32_16x16x128_f8f6f4 v[82:85], v[208:215], v[232:239], v[82:85], v188, v188 op_sel_hi:[0,0,0]
	v_mfma_scale_f32_16x16x128_f8f6f4 v[74:77], v[208:215], v[240:247], v[74:77], v188, v188 op_sel_hi:[0,0,0]
	v_mfma_scale_f32_16x16x128_f8f6f4 v[78:81], v[2:9], v[240:247], v[78:81], v188, v188 op_sel_hi:[0,0,0]
	v_mfma_scale_f32_16x16x128_f8f6f4 v[86:89], v[2:9], v[232:239], v[86:89], v188, v188 op_sel_hi:[0,0,0]
	v_mfma_scale_f32_16x16x128_f8f6f4 v[94:97], v[2:9], v[224:231], v[94:97], v188, v188 op_sel_hi:[0,0,0]
	v_mfma_scale_f32_16x16x128_f8f6f4 v[102:105], v[2:9], v[216:223], v[102:105], v188, v188 op_sel_hi:[0,0,0]
	s_setprio 0
	s_barrier
	s_mov_b32 m0, s52
	v_lshl_add_u64 v[176:177], v[176:177], 0, s[14:15]
	s_add_u32 s26, s26, 0x158080
	ds_read_b128 v[216:219], v190 offset:49152
	ds_read_b128 v[220:223], v190 offset:50176
	ds_read_b128 v[224:227], v190 offset:51200
	ds_read_b128 v[228:231], v190 offset:52224
	ds_read_b128 v[232:235], v190 offset:53248
	ds_read_b128 v[236:239], v190 offset:54272
	ds_read_b128 v[240:243], v190 offset:55296
	ds_read_b128 v[244:247], v190 offset:56320
	global_load_lds_dwordx4 v[176:177], off
	v_lshl_add_u64 v[176:177], v[182:183], 0, s[14:15]
	s_mov_b32 m0, s53
	s_addc_u32 s27, s27, 0
	global_load_lds_dwordx4 v[176:177], off
	v_lshl_add_u64 v[176:177], s[26:27], 0, v[156:157]
	s_mov_b32 m0, s56
	s_nop 0
	global_load_lds_dwordx4 v[176:177], off
	v_lshl_add_u64 v[176:177], s[26:27], 0, v[160:161]
	s_mov_b32 m0, s57
	s_nop 0
	global_load_lds_dwordx4 v[176:177], off
	v_lshl_add_u64 v[176:177], v[184:185], 0, s[14:15]
	s_mov_b32 m0, s54
	s_nop 0
	global_load_lds_dwordx4 v[176:177], off
	v_lshl_add_u64 v[176:177], v[186:187], 0, s[14:15]
	s_mov_b32 m0, s55
	s_nop 0
	global_load_lds_dwordx4 v[176:177], off
	s_waitcnt vmcnt(8)
	s_waitcnt lgkmcnt(0)
	s_barrier
	s_setprio 1
	s_waitcnt lgkmcnt(0)
	v_mfma_scale_f32_16x16x128_f8f6f4 v[70:73], v[192:199], v[216:223], v[70:73], v188, v188 op_sel_hi:[0,0,0]
	v_mfma_scale_f32_16x16x128_f8f6f4 v[62:65], v[192:199], v[224:231], v[62:65], v188, v188 op_sel_hi:[0,0,0]
	v_mfma_scale_f32_16x16x128_f8f6f4 v[54:57], v[192:199], v[232:239], v[54:57], v188, v188 op_sel_hi:[0,0,0]
	v_mfma_scale_f32_16x16x128_f8f6f4 v[46:49], v[192:199], v[240:247], v[46:49], v188, v188 op_sel_hi:[0,0,0]
	v_mfma_scale_f32_16x16x128_f8f6f4 v[42:45], v[200:207], v[240:247], v[42:45], v188, v188 op_sel_hi:[0,0,0]
	v_mfma_scale_f32_16x16x128_f8f6f4 v[50:53], v[200:207], v[232:239], v[50:53], v188, v188 op_sel_hi:[0,0,0]
	v_mfma_scale_f32_16x16x128_f8f6f4 v[58:61], v[200:207], v[224:231], v[58:61], v188, v188 op_sel_hi:[0,0,0]
	v_mfma_scale_f32_16x16x128_f8f6f4 v[66:69], v[200:207], v[216:223], v[66:69], v188, v188 op_sel_hi:[0,0,0]
	s_setprio 0
	s_setprio 1
	v_mfma_scale_f32_16x16x128_f8f6f4 v[34:37], v[208:215], v[216:223], v[34:37], v188, v188 op_sel_hi:[0,0,0]
	v_mfma_scale_f32_16x16x128_f8f6f4 v[26:29], v[208:215], v[224:231], v[26:29], v188, v188 op_sel_hi:[0,0,0]
	v_mfma_scale_f32_16x16x128_f8f6f4 v[18:21], v[208:215], v[232:239], v[18:21], v188, v188 op_sel_hi:[0,0,0]
	v_mfma_scale_f32_16x16x128_f8f6f4 v[10:13], v[208:215], v[240:247], v[10:13], v188, v188 op_sel_hi:[0,0,0]
	v_mfma_scale_f32_16x16x128_f8f6f4 v[14:17], v[2:9], v[240:247], v[14:17], v188, v188 op_sel_hi:[0,0,0]
	v_mfma_scale_f32_16x16x128_f8f6f4 v[22:25], v[2:9], v[232:239], v[22:25], v188, v188 op_sel_hi:[0,0,0]
	v_mfma_scale_f32_16x16x128_f8f6f4 v[30:33], v[2:9], v[224:231], v[30:33], v188, v188 op_sel_hi:[0,0,0]
	v_mfma_scale_f32_16x16x128_f8f6f4 v[38:41], v[2:9], v[216:223], v[38:41], v188, v188 op_sel_hi:[0,0,0]
	s_setprio 0
	s_barrier
	s_add_i32 s26, s84, 2
	s_add_u32 s36, s36, 0x100
	s_addc_u32 s37, s37, 0
	s_add_u32 s40, s40, 0x100
	s_addc_u32 s41, s41, 0
	s_cmp_ge_i32 s84, s82
	s_cbranch_scc1 .LBB0_1036
	s_mov_b32 s84, s26
	s_cmp_eq_u32 s82, s84
	s_cselect_b64 s[26:27], -1, 0
	s_cmp_lg_u32 s82, s84
	s_cbranch_scc0 .LBB0_1033
	s_branch .LBB0_1034
